# instruction selection: 135 bf16 pack idioms (bfe/add3/lshr/and_or bit trick) in the second half of the layer replaced by v_cvt_pk_bf16_f32; on top of v76
# baseline (speedup 1.0000x reference)
.LBB0_1018:
	s_or_b64 exec, exec, s[0:1]
	s_waitcnt vmcnt(3)
	v_cvt_pk_bf16_f32 v38, v24, v25
	s_nop 0
	s_nop 0
	s_nop 0
	s_nop 0
	v_cvt_pk_bf16_f32 v39, v26, v27
	s_waitcnt vmcnt(2)
	v_cvt_pk_bf16_f32 v40, v20, v21
	v_cvt_pk_bf16_f32 v41, v22, v23
	s_waitcnt vmcnt(1)
	v_bfe_u32 v35, v10, 16, 1
	v_add3_u32 v35, v10, v35, s79
	ds_write_b128 v29, v[38:41]
	ds_write_b16_d16_hi v36, v35
	v_bfe_u32 v35, v11, 16, 1
	v_add3_u32 v35, v11, v35, s79
	ds_write_b16_d16_hi v36, v35 offset:400
	v_bfe_u32 v35, v12, 16, 1
	v_add3_u32 v35, v12, v35, s79
	ds_write_b16_d16_hi v36, v35 offset:800
	v_bfe_u32 v35, v13, 16, 1
	v_add3_u32 v35, v13, v35, s79
	ds_write_b16_d16_hi v36, v35 offset:1200
	s_waitcnt vmcnt(0)
	v_bfe_u32 v35, v14, 16, 1
	v_add3_u32 v35, v14, v35, s79
	ds_write_b16_d16_hi v36, v35 offset:1600
	v_bfe_u32 v35, v15, 16, 1
	v_add3_u32 v35, v15, v35, s79
	ds_write_b16_d16_hi v36, v35 offset:2000
	v_bfe_u32 v35, v16, 16, 1
	v_add3_u32 v35, v16, v35, s79
	ds_write_b16_d16_hi v36, v35 offset:2400
	v_bfe_u32 v35, v17, 16, 1
	v_add3_u32 v35, v17, v35, s79
	ds_write_b16_d16_hi v36, v35 offset:2800
	v_add_u32_e32 v35, 0x78, v18
	s_movk_i32 s0, 0x80
	v_cmp_gt_u32_e32 vcc, s0, v35
	s_and_saveexec_b64 s[0:1], vcc
	s_cbranch_execz .LBB0_1011
	v_or_b32_e32 v38, s18, v35
	v_mov_b32_e32 v39, s19
	v_lshlrev_b64 v[38:39], 9, v[38:39]
	v_readlane_b32 s22, v251, 20
	v_lshl_or_b32 v38, v28, 2, v38
	v_readlane_b32 s23, v251, 21
	s_nop 1
	v_lshl_add_u64 v[40:41], s[22:23], 0, v[38:39]
	v_readlane_b32 s22, v250, 52
	v_readlane_b32 s23, v250, 53
	s_nop 1
	v_lshl_add_u64 v[38:39], s[22:23], 0, v[38:39]
	global_store_dwordx4 v[38:39], v[24:27], off
	global_store_dwordx4 v[38:39], v[20:23], off offset:16
	global_store_dwordx4 v[40:41], v[10:13], off
	global_store_dwordx4 v[40:41], v[14:17], off offset:16
	s_branch .LBB0_1011
.LBB0_1020:
	s_or_b64 exec, exec, s[16:17]
	s_and_b64 vcc, exec, s[4:5]
	s_cbranch_vccz .LBB0_1022
	v_or_b32_e32 v4, s10, v106
	v_mov_b64_e32 v[2:3], s[14:15]
	v_mad_u64_u32 v[2:3], s[0:1], v4, s33, v[2:3]
	v_mov_b32_e32 v4, 0x2600
	v_mad_i32_i24 v3, s11, v4, v3
	v_lshl_add_u32 v4, s45, 8, v1
	v_ashrrev_i32_e32 v5, 31, v4
	v_lshl_add_u64 v[2:3], v[4:5], 1, v[2:3]
	v_lshlrev_b32_e32 v18, 1, v108
	v_lshl_add_u64 v[6:7], v[2:3], 0, v[18:19]
	s_mov_b64 s[0:1], 0x2000
	v_lshl_add_u64 v[8:9], v[6:7], 0, s[0:1]
	global_load_dwordx4 v[14:17], v[8:9], off offset:16
	global_load_dwordx4 v[2:5], v[8:9], off offset:32
	v_add_co_u32_e32 v6, vcc, s35, v6
	s_mov_b32 s0, 0x204c8
	s_nop 0
	v_addc_co_u32_e32 v7, vcc, 0, v7, vcc
	global_load_dwordx4 v[24:27], v[6:7], off
	global_load_dwordx4 v[80:83], v[8:9], off offset:48
	s_add_i32 s0, s0, 0
	v_mov_b32_e32 v6, s0
	ds_read_b64 v[6:7], v6
	v_readlane_b32 s0, v250, 58
	v_readlane_b32 s1, v250, 59
	v_mov_b32_e32 v129, v19
	s_lshl_b64 s[0:1], s[0:1], 2
	v_lshl_add_u64 v[8:9], s[12:13], 0, v[128:129]
	s_waitcnt lgkmcnt(0)
	v_readfirstlane_b32 s13, v6
	v_readfirstlane_b32 s12, v7
	s_add_u32 s0, s13, s0
	s_addc_u32 s1, s12, s1
	s_mov_b32 s12, 0x100000
	v_add_co_u32_e32 v28, vcc, s12, v8
	s_mov_b64 s[12:13], 0x100000
	v_lshlrev_b32_e32 v45, 2, v108
	v_addc_co_u32_e32 v29, vcc, 0, v9, vcc
	v_lshl_add_u64 v[6:7], v[8:9], 0, s[12:13]
	s_mov_b64 s[12:13], 0x100080
	global_load_dwordx4 v[52:55], v45, s[0:1]
	global_load_dwordx4 v[60:63], v[28:29], off
	global_load_dwordx4 v[76:79], v[28:29], off offset:128
	global_load_dwordx4 v[68:71], v45, s[0:1] offset:16
	v_lshl_add_u64 v[20:21], v[8:9], 0, s[12:13]
	s_mov_b64 s[12:13], 0x100040
	global_load_dwordx4 v[10:13], v[6:7], off offset:32
	global_load_dwordx4 v[48:51], v[6:7], off offset:16
	v_lshl_add_u64 v[36:37], v[8:9], 0, s[12:13]
	global_load_dwordx4 v[64:67], v[20:21], off offset:16
	s_mov_b64 s[12:13], 0x1000c0
	v_lshl_add_u64 v[38:39], v[8:9], 0, s[12:13]
	global_load_dwordx4 v[84:87], v[6:7], off offset:48
	global_load_dwordx4 v[92:95], v45, s[0:1] offset:48
	global_load_dwordx4 v[100:103], v45, s[0:1] offset:32
	global_load_dwordx4 v[88:91], v[20:21], off offset:48
	global_load_dwordx4 v[96:99], v[20:21], off offset:32
	global_load_dwordx4 v[32:35], v[28:29], off offset:64
	global_load_dwordx4 v[6:9], v[36:37], off offset:32
	s_nop 0
	global_load_dwordx4 v[20:23], v[36:37], off offset:16
	global_load_dwordx4 v[40:43], v[28:29], off offset:192
	s_nop 0
	global_load_dwordx4 v[28:31], v45, s[0:1] offset:80
	global_load_dwordx4 v[72:75], v45, s[0:1] offset:64
	v_xor_b32_e32 v46, 1, v213
	s_mov_b32 s12, 0x3e000000
	s_waitcnt vmcnt(21)
	v_and_b32_e32 v139, 0xffff0000, v15
	v_and_b32_e32 v138, 0xffff0000, v14
	v_and_b32_e32 v135, 0xffff0000, v17
	v_and_b32_e32 v134, 0xffff0000, v16
	v_lshlrev_b32_e32 v141, 16, v15
	v_lshlrev_b32_e32 v140, 16, v14
	v_lshlrev_b32_e32 v137, 16, v17
	v_lshlrev_b32_e32 v136, 16, v16
	s_waitcnt vmcnt(20)
	v_lshlrev_b32_e32 v154, 16, v2
	v_and_b32_e32 v155, 0xffff0000, v2
	v_lshlrev_b32_e32 v132, 16, v3
	v_and_b32_e32 v133, 0xffff0000, v3
	v_lshlrev_b32_e32 v156, 16, v4
	v_and_b32_e32 v157, 0xffff0000, v4
	v_lshlrev_b32_e32 v130, 16, v5
	v_and_b32_e32 v131, 0xffff0000, v5
	v_pk_mul_f32 v[2:3], v[138:139], v[138:139]
	v_pk_mul_f32 v[4:5], v[134:135], v[134:135]
	v_pk_fma_f32 v[2:3], v[140:141], v[140:141], v[2:3]
	v_pk_fma_f32 v[4:5], v[136:137], v[136:137], v[4:5]
	v_pk_add_f32 v[172:173], v[2:3], v[2:3] op_sel:[0,1] op_sel_hi:[1,0]
	v_pk_add_f32 v[174:175], v[4:5], v[4:5] op_sel:[0,1] op_sel_hi:[1,0]
	global_load_dwordx4 v[2:5], v[36:37], off offset:48
	global_load_dwordx4 v[56:59], v[38:39], off offset:16
	v_mul_f32_e32 v14, v155, v155
	v_pk_fma_f32 v[158:159], v[154:155], v[154:155], v[14:15] op_sel_hi:[1,1,0]
	v_and_b32_e32 v14, 64, v213
	v_add_u32_e32 v14, 64, v14
	v_mul_f32_e32 v44, v131, v131
	v_cmp_lt_i32_e32 vcc, v46, v14
	v_pk_fma_f32 v[170:171], v[130:131], v[130:131], v[44:45] op_sel_hi:[1,1,0]
	s_waitcnt vmcnt(21)
	v_lshlrev_b32_e32 v177, 16, v25
	v_cndmask_b32_e32 v14, v213, v46, vcc
	v_lshlrev_b32_e32 v176, 16, v24
	v_and_b32_e32 v179, 0xffff0000, v25
	v_and_b32_e32 v178, 0xffff0000, v24
	v_lshlrev_b32_e32 v189, 16, v27
	v_lshlrev_b32_e32 v188, 16, v26
	v_and_b32_e32 v191, 0xffff0000, v27
	v_and_b32_e32 v190, 0xffff0000, v26
	global_load_dwordx4 v[24:27], v45, s[0:1] offset:112
	s_nop 0
	global_load_dwordx4 v[44:47], v45, s[0:1] offset:96
	v_mul_f32_e32 v18, v157, v157
	v_pk_fma_f32 v[162:163], v[156:157], v[156:157], v[18:19] op_sel_hi:[1,1,0]
	v_lshlrev_b32_e32 v18, 2, v14
	v_pk_mul_f32 v[14:15], v[178:179], v[178:179]
	v_mul_f32_e32 v16, v133, v133
	v_pk_fma_f32 v[14:15], v[176:177], v[176:177], v[14:15]
	v_pk_fma_f32 v[160:161], v[132:133], v[132:133], v[16:17] op_sel_hi:[1,1,0]
	v_pk_add_f32 v[180:181], v[14:15], v[14:15] op_sel:[0,1] op_sel_hi:[1,0]
	v_pk_mul_f32 v[14:15], v[190:191], v[190:191]
	s_waitcnt vmcnt(18)
	v_mov_b32_e32 v194, v68
	v_pk_fma_f32 v[14:15], v[188:189], v[188:189], v[14:15]
	v_mov_b32_e32 v195, v70
	v_pk_add_f32 v[192:193], v[14:15], v[14:15] op_sel:[0,1] op_sel_hi:[1,0]
	global_load_dwordx4 v[14:17], v[38:39], off offset:48
	s_nop 0
	global_load_dwordx4 v[36:39], v[38:39], off offset:32
	v_mov_b32_e32 v70, v69
	s_waitcnt vmcnt(19)
	v_mov_b32_e32 v142, v10
	v_mov_b32_e32 v143, v12
	v_mov_b32_e32 v12, v11
	s_waitcnt vmcnt(8)
	v_mov_b32_e32 v68, v40
	v_mov_b32_e32 v69, v42
	v_mov_b32_e32 v42, v41
	v_mov_b32_e32 v40, v20
	v_mov_b32_e32 v41, v22
	v_mov_b32_e32 v22, v21
	v_lshlrev_b32_e32 v21, 16, v81
	v_lshlrev_b32_e32 v20, 16, v80
	v_and_b32_e32 v11, 0xffff0000, v81
	v_and_b32_e32 v10, 0xffff0000, v80
	v_mov_b32_e32 v184, v60
	v_mov_b32_e32 v185, v62
	v_mov_b32_e32 v62, v61
	v_mov_b32_e32 v198, v64
	v_mov_b32_e32 v199, v66
	v_mov_b32_e32 v66, v65
	v_mov_b32_e32 v64, v32
	v_mov_b32_e32 v65, v34
	v_mov_b32_e32 v34, v33
	s_waitcnt vmcnt(7)
	v_mov_b32_e32 v60, v28
	v_mov_b32_e32 v61, v30
	v_mov_b32_e32 v30, v29
	v_pk_mul_f32 v[28:29], v[20:21], v[20:21]
	v_pk_mul_f32 v[32:33], v[10:11], v[10:11]
	v_mov_b32_e32 v173, v29
	v_mov_b32_e32 v175, v33
	v_mov_b32_e32 v181, v28
	v_mov_b32_e32 v193, v32
	v_mov_b32_e32 v146, v100
	v_mov_b32_e32 v147, v102
	v_mov_b32_e32 v102, v101
	v_mov_b32_e32 v100, v92
	v_mov_b32_e32 v101, v94
	v_mov_b32_e32 v94, v93
	v_mov_b32_e32 v92, v84
	v_mov_b32_e32 v93, v86
	v_mov_b32_e32 v86, v85
	s_waitcnt vmcnt(6)
	v_mov_b32_e32 v84, v72
	v_mov_b32_e32 v85, v74
	v_mov_b32_e32 v74, v73
	v_pk_add_f32 v[72:73], v[172:173], v[174:175]
	v_pk_add_f32 v[28:29], v[180:181], v[192:193]
	v_lshlrev_b32_e32 v33, 16, v83
	v_pk_add_f32 v[72:73], v[28:29], v[72:73]
	v_lshlrev_b32_e32 v32, 16, v82
	v_and_b32_e32 v29, 0xffff0000, v83
	v_and_b32_e32 v28, 0xffff0000, v82
	v_pk_mul_f32 v[80:81], v[32:33], v[32:33]
	v_pk_mul_f32 v[82:83], v[28:29], v[28:29]
	v_mov_b32_e32 v159, v80
	v_mov_b32_e32 v161, v82
	v_mov_b32_e32 v163, v81
	v_mov_b32_e32 v171, v83
	v_mov_b32_e32 v144, v96
	v_mov_b32_e32 v145, v98
	v_mov_b32_e32 v98, v97
	v_mov_b32_e32 v96, v88
	v_mov_b32_e32 v97, v90
	v_mov_b32_e32 v90, v89
	v_pk_add_f32 v[88:89], v[158:159], v[160:161]
	v_pk_add_f32 v[80:81], v[162:163], v[170:171]
	v_mov_b32_e32 v196, v48
	v_pk_add_f32 v[80:81], v[88:89], v[80:81]
	s_waitcnt vmcnt(4)
	v_mov_b32_e32 v48, v56
	v_pk_add_f32 v[72:73], v[72:73], v[80:81]
	s_mov_b32 s0, 0xf800000
	v_add_f32_e32 v56, v72, v73
	ds_bpermute_b32 v80, v18, v56
	s_waitcnt vmcnt(2)
	v_mov_b32_e32 v72, v44
	v_mov_b32_e32 v73, v46
	v_mov_b32_e32 v46, v45
	v_mov_b32_e32 v197, v50
	s_waitcnt lgkmcnt(0)
	v_add_f32_e32 v44, v56, v80
	v_fmamk_f32 v44, v44, 0x3c800000, v165
	v_mul_f32_e32 v45, 0x4f800000, v44
	v_cmp_gt_f32_e32 vcc, s0, v44
	v_mov_b32_e32 v50, v49
	v_mov_b32_e32 v49, v58
	v_mov_b32_e32 v58, v57
	v_cndmask_b32_e32 v57, v44, v45, vcc
	v_sqrt_f32_e32 v80, v57
	v_mov_b32_e32 v44, v6
	v_mov_b32_e32 v45, v8
	s_waitcnt vmcnt(0)
	v_mov_b32_e32 v56, v36
	v_add_u32_e32 v6, -1, v80
	v_fma_f32 v8, -v6, v80, v57
	v_cmp_ge_f32_e64 s[0:1], 0, v8
	v_add_u32_e32 v8, 1, v80
	v_fma_f32 v36, -v8, v80, v57
	v_cndmask_b32_e64 v6, v80, v6, s[0:1]
	v_cmp_lt_f32_e64 s[0:1], 0, v36
	v_mov_b32_e32 v182, v52
	v_mov_b32_e32 v183, v54
	v_cndmask_b32_e64 v6, v6, v8, s[0:1]
	v_mul_f32_e32 v8, 0x37800000, v6
	v_cndmask_b32_e32 v6, v6, v8, vcc
	v_cmp_class_f32_e32 vcc, v57, v212
	v_mov_b32_e32 v8, v7
	v_mov_b32_e32 v54, v53
	v_cndmask_b32_e32 v6, v6, v57, vcc
	v_div_scale_f32 v36, s[0:1], v6, v6, s12
	v_rcp_f32_e32 v80, v36
	v_mov_b32_e32 v57, v38
	v_mov_b32_e32 v38, v37
	v_mov_b32_e32 v186, v76
	v_fma_f32 v7, -v36, v80, 1.0
	v_fmac_f32_e32 v80, v7, v80
	v_div_scale_f32 v7, vcc, s12, v6, s12
	v_mul_f32_e32 v37, v7, v80
	v_fma_f32 v81, -v36, v37, v7
	v_fmac_f32_e32 v37, v81, v80
	v_fma_f32 v7, -v36, v37, v7
	v_div_fmas_f32 v7, v7, v80, v37
	v_div_fixup_f32 v6, v7, v6, s12
	v_pk_mul_f32 v[36:37], v[6:7], v[176:177] op_sel_hi:[0,1]
	v_pk_mul_f32 v[36:37], v[182:183], v[36:37]
	ds_bpermute_b32 v80, v18, v36
	ds_bpermute_b32 v81, v18, v37
	v_pk_mul_f32 v[82:83], v[6:7], v[178:179] op_sel_hi:[0,1]
	v_pk_mul_f32 v[54:55], v[54:55], v[82:83]
	ds_bpermute_b32 v82, v18, v54
	ds_bpermute_b32 v83, v18, v55
	v_mov_b32_e32 v187, v78
	s_waitcnt lgkmcnt(2)
	v_pk_mul_f32 v[80:81], v[186:187], v[80:81]
	v_mov_b32_e32 v78, v77
	v_cndmask_b32_e64 v81, v81, -v81, s[42:43]
	v_cndmask_b32_e64 v80, v80, -v80, s[42:43]
	v_pk_fma_f32 v[36:37], v[184:185], v[36:37], v[80:81]
	v_pk_mul_f32 v[80:81], v[6:7], v[190:191] op_sel_hi:[0,1]
	s_waitcnt lgkmcnt(0)
	v_pk_mul_f32 v[78:79], v[78:79], v[82:83]
	v_pk_mul_f32 v[70:71], v[70:71], v[80:81]
	v_cndmask_b32_e64 v79, v79, -v79, s[42:43]
	v_cndmask_b32_e64 v78, v78, -v78, s[42:43]
	ds_bpermute_b32 v80, v18, v70
	ds_bpermute_b32 v81, v18, v71
	v_pk_fma_f32 v[54:55], v[62:63], v[54:55], v[78:79]
	v_pk_mul_f32 v[62:63], v[6:7], v[188:189] op_sel_hi:[0,1]
	v_pk_mul_f32 v[62:63], v[194:195], v[62:63]
	ds_bpermute_b32 v78, v18, v62
	ds_bpermute_b32 v79, v18, v63
	s_waitcnt lgkmcnt(2)
	v_pk_mul_f32 v[66:67], v[66:67], v[80:81]
	v_mov_b32_e32 v76, v154
	v_cndmask_b32_e64 v67, v67, -v67, s[42:43]
	v_cndmask_b32_e64 v66, v66, -v66, s[42:43]
	v_pk_fma_f32 v[50:51], v[50:51], v[70:71], v[66:67]
	s_waitcnt lgkmcnt(0)
	v_pk_mul_f32 v[78:79], v[198:199], v[78:79]
	v_bfe_u32 v7, v51, 16, 1
	v_bfe_u32 v66, v50, 16, 1
	v_cndmask_b32_e64 v79, v79, -v79, s[42:43]
	v_cndmask_b32_e64 v78, v78, -v78, s[42:43]
	v_add3_u32 v50, v50, v66, s79
	v_add3_u32 v7, v51, v7, s79
	v_cvt_pk_bf16_f32 v51, v36, v54
	v_cvt_pk_bf16_f32 v66, v37, v55
	v_pk_fma_f32 v[62:63], v[196:197], v[62:63], v[78:79]
	v_bfe_u32 v67, v62, 16, 1
	v_add3_u32 v62, v62, v67, s79
	v_mov_b32_e32 v79, v66
	v_mov_b32_e32 v78, v51
	v_pk_mul_f32 v[36:37], v[6:7], v[140:141] op_sel_hi:[0,1]
	v_bfe_u32 v70, v63, 16, 1
	v_lshrrev_b32_e32 v51, 16, v62
	v_pk_mul_f32 v[36:37], v[36:37], v[146:147]
	v_add3_u32 v63, v63, v70, s79
	v_and_or_b32 v80, v50, s80, v51
	ds_bpermute_b32 v50, v18, v36
	ds_bpermute_b32 v51, v18, v37
	v_pk_mul_f32 v[54:55], v[6:7], v[138:139] op_sel_hi:[0,1]
	v_lshrrev_b32_e32 v62, 16, v63
	v_pk_mul_f32 v[54:55], v[54:55], v[102:103]
	v_and_or_b32 v81, v7, s80, v62
	ds_bpermute_b32 v62, v18, v54
	ds_bpermute_b32 v63, v18, v55
	s_waitcnt lgkmcnt(2)
	v_pk_mul_f32 v[50:51], v[144:145], v[50:51]
	v_mov_b32_e32 v77, v132
	v_cndmask_b32_e64 v51, v51, -v51, s[42:43]
	v_cndmask_b32_e64 v50, v50, -v50, s[42:43]
	v_pk_fma_f32 v[36:37], v[36:37], v[142:143], v[50:51]
	s_waitcnt lgkmcnt(0)
	v_pk_mul_f32 v[50:51], v[98:99], v[62:63]
	v_pk_mul_f32 v[62:63], v[6:7], v[134:135] op_sel_hi:[0,1]
	v_cndmask_b32_e64 v51, v51, -v51, s[42:43]
	v_cndmask_b32_e64 v50, v50, -v50, s[42:43]
	v_pk_fma_f32 v[12:13], v[54:55], v[12:13], v[50:51]
	v_pk_mul_f32 v[50:51], v[6:7], v[136:137] op_sel_hi:[0,1]
	v_pk_mul_f32 v[50:51], v[50:51], v[100:101]
	ds_bpermute_b32 v54, v18, v50
	ds_bpermute_b32 v55, v18, v51
	v_pk_mul_f32 v[62:63], v[62:63], v[94:95]
	ds_bpermute_b32 v66, v18, v62
	ds_bpermute_b32 v67, v18, v63
	ds_write_b128 v105, v[78:81] offset:53248
	s_waitcnt lgkmcnt(3)
	v_pk_mul_f32 v[54:55], v[96:97], v[54:55]
	v_mov_b32_e32 v132, v155
	v_cndmask_b32_e64 v55, v55, -v55, s[42:43]
	v_cndmask_b32_e64 v54, v54, -v54, s[42:43]
	v_pk_fma_f32 v[50:51], v[50:51], v[92:93], v[54:55]
	s_waitcnt lgkmcnt(1)
	v_pk_mul_f32 v[54:55], v[90:91], v[66:67]
	v_cvt_pk_bf16_f32 v78, v36, v12
	v_cndmask_b32_e64 v55, v55, -v55, s[42:43]
	v_cndmask_b32_e64 v54, v54, -v54, s[42:43]
	v_pk_fma_f32 v[54:55], v[62:63], v[86:87], v[54:55]
	v_cvt_pk_bf16_f32 v79, v37, v13
	v_bfe_u32 v7, v55, 16, 1
	v_cvt_pk_bf16_f32 v80, v50, v54
	v_add3_u32 v7, v55, v7, s79
	v_bfe_u32 v66, v51, 16, 1
	v_add3_u32 v51, v51, v66, s79
	v_pk_mul_f32 v[12:13], v[6:7], v[76:77] op_sel_hi:[0,1]
	s_nop 0
	v_lshrrev_b32_e32 v51, 16, v51
	v_pk_mul_f32 v[12:13], v[12:13], v[84:85]
	v_and_or_b32 v81, v7, s80, v51
	s_nop 0
	ds_bpermute_b32 v36, v18, v12
	ds_bpermute_b32 v37, v18, v13
	v_pk_mul_f32 v[50:51], v[6:7], v[132:133] op_sel_hi:[0,1]
	v_pk_mul_f32 v[50:51], v[50:51], v[74:75]
	ds_bpermute_b32 v54, v18, v50
	ds_bpermute_b32 v55, v18, v51
	s_waitcnt lgkmcnt(2)
	v_pk_mul_f32 v[36:37], v[68:69], v[36:37]
	v_mov_b32_e32 v52, v156
	v_cndmask_b32_e64 v37, v37, -v37, s[42:43]
	v_cndmask_b32_e64 v36, v36, -v36, s[42:43]
	v_pk_fma_f32 v[12:13], v[12:13], v[64:65], v[36:37]
	s_waitcnt lgkmcnt(0)
	v_pk_mul_f32 v[36:37], v[42:43], v[54:55]
	v_mov_b32_e32 v53, v130
	v_cndmask_b32_e64 v37, v37, -v37, s[42:43]
	v_cndmask_b32_e64 v36, v36, -v36, s[42:43]
	v_pk_fma_f32 v[34:35], v[50:51], v[34:35], v[36:37]
	v_pk_mul_f32 v[36:37], v[6:7], v[52:53] op_sel_hi:[0,1]
	v_mov_b32_e32 v130, v157
	v_pk_mul_f32 v[36:37], v[36:37], v[60:61]
	ds_bpermute_b32 v42, v18, v36
	ds_bpermute_b32 v43, v18, v37
	v_pk_mul_f32 v[50:51], v[6:7], v[130:131] op_sel_hi:[0,1]
	v_pk_mul_f32 v[30:31], v[50:51], v[30:31]
	ds_bpermute_b32 v50, v18, v30
	ds_bpermute_b32 v51, v18, v31
	s_waitcnt lgkmcnt(2)
	v_pk_mul_f32 v[42:43], v[48:49], v[42:43]
	ds_write_b128 v105, v[78:81] offset:53264
	v_cndmask_b32_e64 v43, v43, -v43, s[42:43]
	v_cndmask_b32_e64 v42, v42, -v42, s[42:43]
	v_pk_fma_f32 v[36:37], v[36:37], v[40:41], v[42:43]
	s_waitcnt lgkmcnt(1)
	v_pk_mul_f32 v[40:41], v[58:59], v[50:51]
	s_nop 0
	v_cndmask_b32_e64 v41, v41, -v41, s[42:43]
	v_cndmask_b32_e64 v40, v40, -v40, s[42:43]
	v_pk_fma_f32 v[22:23], v[30:31], v[22:23], v[40:41]
	v_cvt_pk_bf16_f32 v31, v13, v35
	v_bfe_u32 v7, v23, 16, 1
	v_cvt_pk_bf16_f32 v36, v36, v22
	v_add3_u32 v7, v23, v7, s79
	v_cvt_pk_bf16_f32 v34, v12, v34
	s_nop 0
	s_nop 0
	v_mov_b32_e32 v35, v31
	s_nop 0
	v_pk_mul_f32 v[12:13], v[6:7], v[20:21] op_sel_hi:[0,1]
	v_pk_mul_f32 v[12:13], v[12:13], v[72:73]
	ds_bpermute_b32 v20, v18, v12
	ds_bpermute_b32 v21, v18, v13
	v_pk_mul_f32 v[10:11], v[6:7], v[10:11] op_sel_hi:[0,1]
	v_pk_mul_f32 v[10:11], v[10:11], v[46:47]
	s_nop 0
	ds_bpermute_b32 v22, v18, v10
	ds_bpermute_b32 v23, v18, v11
	s_waitcnt lgkmcnt(2)
	v_pk_mul_f32 v[20:21], v[56:57], v[20:21]
	v_bfe_u32 v40, v37, 16, 1
	v_cndmask_b32_e64 v21, v21, -v21, s[42:43]
	v_cndmask_b32_e64 v20, v20, -v20, s[42:43]
	v_add3_u32 v37, v37, v40, s79
	v_pk_fma_f32 v[12:13], v[12:13], v[44:45], v[20:21]
	s_waitcnt lgkmcnt(0)
	v_pk_mul_f32 v[20:21], v[38:39], v[22:23]
	v_lshrrev_b32_e32 v30, 16, v37
	v_cndmask_b32_e64 v21, v21, -v21, s[42:43]
	v_cndmask_b32_e64 v20, v20, -v20, s[42:43]
	v_and_or_b32 v37, v7, s80, v30
	v_pk_fma_f32 v[8:9], v[10:11], v[8:9], v[20:21]
	v_pk_mul_f32 v[10:11], v[6:7], v[32:33] op_sel_hi:[0,1]
	v_mov_b32_e32 v21, v26
	v_pk_mul_f32 v[6:7], v[6:7], v[28:29] op_sel_hi:[0,1]
	v_mov_b32_e32 v26, v25
	v_mov_b32_e32 v20, v24
	v_pk_mul_f32 v[6:7], v[6:7], v[26:27]
	v_pk_mul_f32 v[10:11], v[10:11], v[20:21]
	ds_bpermute_b32 v22, v18, v6
	ds_bpermute_b32 v23, v18, v7
	ds_bpermute_b32 v20, v18, v10
	ds_bpermute_b32 v21, v18, v11
	v_mov_b32_e32 v27, v16
	v_mov_b32_e32 v16, v15
	v_mov_b32_e32 v24, v2
	v_mov_b32_e32 v25, v4
	v_mov_b32_e32 v26, v14
	v_mov_b32_e32 v4, v3
	s_waitcnt lgkmcnt(2)
	v_pk_mul_f32 v[2:3], v[16:17], v[22:23]
	s_waitcnt lgkmcnt(0)
	v_pk_mul_f32 v[20:21], v[26:27], v[20:21]
	v_cndmask_b32_e64 v3, v3, -v3, s[42:43]
	v_cndmask_b32_e64 v2, v2, -v2, s[42:43]
	v_cndmask_b32_e64 v21, v21, -v21, s[42:43]
	v_cndmask_b32_e64 v20, v20, -v20, s[42:43]
	v_pk_fma_f32 v[2:3], v[6:7], v[4:5], v[2:3]
	v_pk_fma_f32 v[10:11], v[10:11], v[24:25], v[20:21]
	v_bfe_u32 v4, v3, 16, 1
	v_bfe_u32 v5, v2, 16, 1
	v_cvt_pk_bf16_f32 v6, v13, v9
	v_cvt_pk_bf16_f32 v7, v12, v8
	v_add3_u32 v2, v2, v5, s79
	v_add3_u32 v3, v3, v4, s79
	v_bfe_u32 v8, v10, 16, 1
	v_bfe_u32 v9, v11, 16, 1
	v_add3_u32 v9, v11, v9, s79
	v_add3_u32 v8, v10, v8, s79
	v_lshrrev_b32_e32 v4, 16, v8
	v_lshrrev_b32_e32 v5, 16, v9
	v_and_or_b32 v5, v3, s80, v5
	v_and_or_b32 v4, v2, s80, v4
	v_mov_b32_e32 v3, v6
	v_mov_b32_e32 v2, v7
	ds_write_b128 v105, v[34:37] offset:53280
	ds_write_b128 v105, v[2:5] offset:53296

.LBB0_1298:
	v_lshl_add_u64 v[84:85], v[6:7], 0, v[78:79]
	v_lshl_add_u64 v[86:87], v[8:9], 0, v[18:19]
	global_load_dword v123, v[84:85], off
	global_load_dword v82, v[8:9], off
	global_load_dword v83, v[86:87], off
	v_lshl_add_u64 v[86:87], v[84:85], 0, v[76:77]
	global_load_dword v125, v[86:87], off
	v_lshl_add_u64 v[84:85], v[8:9], 0, v[70:71]
	v_lshl_add_u64 v[88:89], v[8:9], 0, v[72:73]
	global_load_dword v84, v[84:85], off
	v_lshl_add_u64 v[90:91], v[8:9], 0, v[68:69]
	global_load_dword v85, v[88:89], off
	v_lshl_add_u64 v[88:89], v[86:87], 0, v[76:77]
	global_load_dword v127, v[88:89], off
	v_lshl_add_u64 v[86:87], v[8:9], 0, v[66:67]
	global_load_dword v86, v[86:87], off
	v_lshl_add_u64 v[92:93], v[8:9], 0, v[64:65]
	global_load_dword v87, v[90:91], off
	v_lshl_add_u64 v[90:91], v[88:89], 0, v[76:77]
	global_load_dword v129, v[90:91], off
	v_lshl_add_u64 v[88:89], v[8:9], 0, v[62:63]
	global_load_dword v88, v[88:89], off
	v_lshl_add_u64 v[94:95], v[8:9], 0, v[60:61]
	global_load_dword v89, v[92:93], off
	v_lshl_add_u64 v[92:93], v[90:91], 0, v[76:77]
	global_load_dword v131, v[92:93], off
	v_lshl_add_u64 v[90:91], v[8:9], 0, v[58:59]
	global_load_dword v90, v[90:91], off
	v_lshl_add_u64 v[96:97], v[8:9], 0, v[56:57]
	global_load_dword v91, v[94:95], off
	v_lshl_add_u64 v[94:95], v[92:93], 0, v[76:77]
	global_load_dword v132, v[94:95], off
	v_lshl_add_u64 v[92:93], v[8:9], 0, v[54:55]
	global_load_dword v92, v[92:93], off
	v_lshl_add_u64 v[98:99], v[8:9], 0, v[52:53]
	global_load_dword v93, v[96:97], off
	v_lshl_add_u64 v[96:97], v[94:95], 0, v[76:77]
	global_load_dword v133, v[96:97], off
	v_lshl_add_u64 v[94:95], v[8:9], 0, v[50:51]
	global_load_dword v94, v[94:95], off
	v_lshl_add_u64 v[100:101], v[8:9], 0, v[48:49]
	global_load_dword v95, v[98:99], off
	v_lshl_add_u64 v[98:99], v[96:97], 0, v[76:77]
	global_load_dword v134, v[98:99], off
	v_lshl_add_u64 v[96:97], v[8:9], 0, v[46:47]
	global_load_dword v96, v[96:97], off
	v_lshl_add_u64 v[102:103], v[8:9], 0, v[44:45]
	global_load_dword v97, v[100:101], off
	v_lshl_add_u64 v[100:101], v[98:99], 0, v[76:77]
	global_load_dword v135, v[100:101], off
	v_lshl_add_u64 v[98:99], v[8:9], 0, v[42:43]
	global_load_dword v98, v[98:99], off
	v_lshl_add_u64 v[104:105], v[8:9], 0, v[40:41]
	global_load_dword v99, v[102:103], off
	v_lshl_add_u64 v[102:103], v[100:101], 0, v[76:77]
	global_load_dword v136, v[102:103], off
	v_lshl_add_u64 v[100:101], v[8:9], 0, v[38:39]
	global_load_dword v100, v[100:101], off
	v_lshl_add_u64 v[112:113], v[8:9], 0, v[36:37]
	global_load_dword v101, v[104:105], off
	v_lshl_add_u64 v[104:105], v[102:103], 0, v[76:77]
	v_lshl_add_u64 v[102:103], v[8:9], 0, v[34:35]
	global_load_dword v137, v[104:105], off
	v_lshl_add_u64 v[114:115], v[8:9], 0, v[32:33]
	global_load_dword v102, v[102:103], off
	v_lshl_add_u64 v[116:117], v[8:9], 0, v[28:29]
	global_load_dword v103, v[112:113], off
	v_lshl_add_u64 v[112:113], v[104:105], 0, v[76:77]
	global_load_dword v138, v[112:113], off
	v_lshl_add_u64 v[112:113], v[112:113], 0, v[76:77]
	v_lshl_add_u64 v[104:105], v[8:9], 0, v[30:31]
	global_load_dword v139, v[112:113], off
	v_lshl_add_u64 v[112:113], v[112:113], 0, v[76:77]
	global_load_dword v104, v[104:105], off
	v_lshl_add_u64 v[118:119], v[8:9], 0, v[24:25]
	global_load_dword v105, v[114:115], off
	global_load_dword v140, v[112:113], off
	v_lshl_add_u64 v[112:113], v[112:113], 0, v[76:77]
	global_load_dword v141, v[112:113], off
	v_lshl_add_u64 v[112:113], v[112:113], 0, v[76:77]
	global_load_dword v142, v[112:113], off
	v_lshl_add_u64 v[112:113], v[8:9], 0, v[10:11]
	global_load_dword v112, v[112:113], off
	v_lshl_add_u64 v[114:115], v[8:9], 0, v[26:27]
	global_load_dword v114, v[114:115], off
	v_lshl_add_u64 v[120:121], v[8:9], 0, v[20:21]
	global_load_dword v115, v[116:117], off
	v_lshl_add_u64 v[116:117], v[8:9], 0, v[22:23]
	global_load_dword v116, v[116:117], off
	s_waitcnt vmcnt(40)
	v_lshlrev_b32_e32 v124, 16, v125
	global_load_dword v117, v[118:119], off
	v_lshl_add_u64 v[118:119], v[8:9], 0, v[16:17]
	global_load_dword v118, v[118:119], off
	v_and_b32_e32 v125, 0xffff0000, v125
	global_load_dword v119, v[120:121], off
	v_lshl_add_u64 v[120:121], v[8:9], 0, v[12:13]
	global_load_dword v113, v[120:121], off
	v_cvt_pk_bf16_f32 v122, v80, v81
	v_lshl_add_u64 v[120:121], v[4:5], 0, v[78:79]
	global_store_dword v[120:121], v122, off
	v_lshlrev_b32_e32 v122, 16, v123
	v_and_b32_e32 v123, 0xffff0000, v123
	v_pk_fma_f32 v[80:81], v[80:81], v[82:83], v[122:123]
	s_waitcnt vmcnt(42)
	v_lshlrev_b32_e32 v126, 16, v127
	v_cvt_pk_bf16_f32 v122, v80, v81
	v_pk_fma_f32 v[80:81], v[80:81], v[84:85], v[124:125]
	v_cvt_pk_bf16_f32 v84, v80, v81
	v_and_b32_e32 v127, 0xffff0000, v127
	v_lshl_add_u64 v[82:83], v[120:121], 0, v[76:77]
	global_store_dword v[82:83], v122, off
	s_nop 0
	v_lshl_add_u64 v[82:83], v[82:83], 0, v[76:77]
	s_waitcnt vmcnt(41)
	v_pk_fma_f32 v[80:81], v[80:81], v[86:87], v[126:127]
	global_store_dword v[82:83], v84, off
	v_cvt_pk_bf16_f32 v84, v80, v81
	s_nop 0
	s_nop 0
	s_waitcnt vmcnt(41)
	v_lshlrev_b32_e32 v128, 16, v129
	v_and_b32_e32 v129, 0xffff0000, v129
	v_lshl_add_u64 v[82:83], v[82:83], 0, v[76:77]
	s_waitcnt vmcnt(39)
	v_pk_fma_f32 v[80:81], v[80:81], v[88:89], v[128:129]
	global_store_dword v[82:83], v84, off
	v_cvt_pk_bf16_f32 v84, v80, v81
	s_nop 0
	s_nop 0
	s_waitcnt vmcnt(39)
	v_lshlrev_b32_e32 v130, 16, v131
	v_and_b32_e32 v131, 0xffff0000, v131
	v_lshl_add_u64 v[82:83], v[82:83], 0, v[76:77]
	s_waitcnt vmcnt(37)
	v_pk_fma_f32 v[80:81], v[80:81], v[90:91], v[130:131]
	global_store_dword v[82:83], v84, off
	v_cvt_pk_bf16_f32 v84, v80, v81
	s_nop 0
	s_nop 0
	s_nop 0
	s_nop 0
	s_nop 0
	v_lshl_add_u64 v[82:83], v[82:83], 0, v[76:77]
	global_store_dword v[82:83], v84, off
	s_waitcnt vmcnt(38)
	v_lshlrev_b32_e32 v84, 16, v132
	v_and_b32_e32 v85, 0xffff0000, v132
	s_waitcnt vmcnt(36)
	v_pk_fma_f32 v[80:81], v[80:81], v[92:93], v[84:85]
	s_waitcnt vmcnt(35)
	v_lshlrev_b32_e32 v86, 16, v133
	v_cvt_pk_bf16_f32 v84, v80, v81
	v_and_b32_e32 v87, 0xffff0000, v133
	v_lshl_add_u64 v[82:83], v[82:83], 0, v[76:77]
	s_waitcnt vmcnt(33)
	v_pk_fma_f32 v[80:81], v[80:81], v[94:95], v[86:87]
	global_store_dword v[82:83], v84, off
	v_cvt_pk_bf16_f32 v84, v80, v81
	s_nop 0
	s_nop 0
	s_waitcnt vmcnt(33)
	v_lshlrev_b32_e32 v88, 16, v134
	v_and_b32_e32 v89, 0xffff0000, v134
	v_lshl_add_u64 v[82:83], v[82:83], 0, v[76:77]
	s_waitcnt vmcnt(31)
	v_pk_fma_f32 v[80:81], v[80:81], v[96:97], v[88:89]
	global_store_dword v[82:83], v84, off
	v_cvt_pk_bf16_f32 v84, v80, v81
	s_nop 0
	s_nop 0
	s_waitcnt vmcnt(31)
	v_lshlrev_b32_e32 v90, 16, v135
	v_and_b32_e32 v91, 0xffff0000, v135
	v_lshl_add_u64 v[82:83], v[82:83], 0, v[76:77]
	s_waitcnt vmcnt(29)
	v_pk_fma_f32 v[80:81], v[80:81], v[98:99], v[90:91]
	global_store_dword v[82:83], v84, off
	v_cvt_pk_bf16_f32 v84, v80, v81
	s_nop 0
	s_nop 0
	s_waitcnt vmcnt(29)
	v_lshlrev_b32_e32 v120, 16, v136
	v_and_b32_e32 v121, 0xffff0000, v136
	v_lshl_add_u64 v[82:83], v[82:83], 0, v[76:77]
	s_waitcnt vmcnt(27)
	v_pk_fma_f32 v[80:81], v[80:81], v[100:101], v[120:121]
	global_store_dword v[82:83], v84, off
	v_cvt_pk_bf16_f32 v84, v80, v81
	s_nop 0
	s_nop 0
	s_waitcnt vmcnt(27)
	v_lshlrev_b32_e32 v122, 16, v137
	s_nop 0
	v_and_b32_e32 v123, 0xffff0000, v137
	v_lshl_add_u64 v[82:83], v[82:83], 0, v[76:77]
	s_waitcnt vmcnt(25)
	v_pk_fma_f32 v[80:81], v[80:81], v[102:103], v[122:123]
	global_store_dword v[82:83], v84, off
	s_waitcnt vmcnt(25)
	v_lshlrev_b32_e32 v84, 16, v138
	v_and_b32_e32 v85, 0xffff0000, v138
	v_cvt_pk_bf16_f32 v94, v80, v81
	s_nop 0
	s_nop 0
	s_waitcnt vmcnt(22)
	v_pk_fma_f32 v[80:81], v[80:81], v[104:105], v[84:85]
	v_cvt_pk_bf16_f32 v84, v80, v81
	v_lshlrev_b32_e32 v86, 16, v139
	v_and_b32_e32 v87, 0xffff0000, v139
	v_lshl_add_u64 v[82:83], v[82:83], 0, v[76:77]
	global_store_dword v[82:83], v94, off
	s_nop 0
	v_lshl_add_u64 v[82:83], v[82:83], 0, v[76:77]
	s_waitcnt vmcnt(17)
	v_pk_fma_f32 v[80:81], v[80:81], v[114:115], v[86:87]
	global_store_dword v[82:83], v84, off
	v_cvt_pk_bf16_f32 v84, v80, v81
	s_nop 0
	s_nop 0
	v_lshlrev_b32_e32 v88, 16, v140
	v_and_b32_e32 v89, 0xffff0000, v140
	s_nop 0
	v_lshl_add_u64 v[82:83], v[82:83], 0, v[76:77]
	s_waitcnt vmcnt(16)
	v_pk_fma_f32 v[80:81], v[80:81], v[116:117], v[88:89]
	global_store_dword v[82:83], v84, off
	v_cvt_pk_bf16_f32 v84, v80, v81
	s_nop 0
	s_nop 0
	v_lshlrev_b32_e32 v90, 16, v141
	v_and_b32_e32 v91, 0xffff0000, v141
	s_nop 0
	v_lshl_add_u64 v[82:83], v[82:83], 0, v[76:77]
	s_waitcnt vmcnt(15)
	v_pk_fma_f32 v[80:81], v[80:81], v[118:119], v[90:91]
	global_store_dword v[82:83], v84, off
	v_cvt_pk_bf16_f32 v84, v80, v81
	s_nop 0
	s_nop 0
	v_lshlrev_b32_e32 v92, 16, v142
	v_and_b32_e32 v93, 0xffff0000, v142
	s_nop 0
	s_add_i32 s4, s4, 16
	v_lshl_add_u64 v[82:83], v[82:83], 0, v[76:77]
	s_waitcnt vmcnt(15)
	v_pk_fma_f32 v[80:81], v[80:81], v[112:113], v[92:93]
	v_lshl_add_u64 v[8:9], v[8:9], 0, v[14:15]
	v_lshl_add_u64 v[78:79], v[78:79], 0, v[74:75]
	s_cmp_gt_u32 s4, 47
	global_store_dword v[82:83], v84, off
	s_cbranch_scc0 .LBB0_1298
	s_and_saveexec_b64 s[4:5], vcc
	s_xor_b64 s[4:5], exec, s[4:5]
	s_cbranch_execz .LBB0_1301
	v_readlane_b32 s22, v251, 0
	v_lshlrev_b32_e32 v18, 15, v107
	s_nop 0
	v_add_u32_e32 v2, s22, v108
	v_ashrrev_i32_e32 v3, 31, v2
	v_readlane_b32 s22, v251, 16
	v_lshlrev_b64 v[2:3], 18, v[2:3]
	v_readlane_b32 s23, v251, 17
	s_nop 1
	v_lshl_add_u64 v[2:3], s[22:23], 0, v[2:3]
	v_lshl_add_u64 v[2:3], v[2:3], 0, v[18:19]
	v_lshlrev_b32_e32 v18, 2, v110
	v_lshl_add_u64 v[2:3], v[2:3], 0, v[18:19]
	global_store_dwordx2 v[2:3], v[80:81], off nt

.LBB0_1472:
	s_cmp_lt_i32 s90, 0
	s_cbranch_scc1 .LBB0_1460
	s_mov_b64 s[18:19], s[30:31]
	s_barrier
	s_mov_b64 s[18:19], s[30:31]
	s_mov_b64 s[18:19], s[30:31]
	s_mov_b64 s[18:19], s[30:31]
	s_mov_b64 s[18:19], s[30:31]
	s_mov_b64 s[18:19], s[30:31]
	s_mov_b64 s[18:19], s[30:31]
	s_mov_b64 s[18:19], s[30:31]
	s_mov_b64 s[18:19], s[30:31]
	s_mov_b32 s74, s60
	s_mov_b64 s[62:63], s[30:31]
	s_mov_b64 s[60:61], s[30:31]
	s_mov_b64 s[18:19], s[30:31]
	s_mov_b64 s[18:19], s[30:31]
	s_mov_b64 s[20:21], s[30:31]
	s_mov_b64 s[18:19], s[30:31]
	s_mov_b64 s[18:19], s[30:31]
	s_mov_b64 s[18:19], s[30:31]
	s_mov_b64 s[18:19], s[30:31]
	s_mov_b32 s18, 0x20420
	s_mov_b64 s[64:65], s[30:31]
	s_mov_b64 s[24:25], s[30:31]
	s_mov_b64 s[22:23], s[30:31]
	s_mov_b64 s[18:19], s[30:31]
	s_barrier
	s_and_saveexec_b64 s[66:67], s[0:1]
	ds_write_b32 v1, v19
	s_or_b64 exec, exec, s[66:67]
	s_add_u32 s64, s64, 0x47b00000
	s_addc_u32 s65, s65, 0
	s_add_u32 s24, s24, 0x48300000
	s_addc_u32 s25, s25, 0
	s_add_u32 s22, s22, 0x48b00000
	s_addc_u32 s23, s23, 0
	s_lshl_b64 s[66:67], s[90:91], 13
	v_lshl_add_u64 v[2:3], s[66:67], 0, v[30:31]
	v_lshlrev_b64 v[10:11], 1, v[2:3]
	v_lshl_add_u64 v[2:3], s[64:65], 0, v[10:11]
	global_load_dwordx4 v[2:5], v[2:3], off
	v_lshl_add_u64 v[6:7], s[24:25], 0, v[10:11]
	global_load_dwordx4 v[6:9], v[6:7], off
	v_lshl_add_u64 v[20:21], s[22:23], 0, v[10:11]
	v_lshl_add_u64 v[10:11], s[66:67], 0, v[32:33]
	v_lshlrev_b64 v[22:23], 1, v[10:11]
	v_lshl_add_u64 v[10:11], s[64:65], 0, v[22:23]
	v_lshl_add_u64 v[14:15], s[24:25], 0, v[22:23]
	global_load_dwordx4 v[10:13], v[10:11], off
	v_lshl_add_u64 v[22:23], s[22:23], 0, v[22:23]
	global_load_dwordx4 v[14:17], v[14:15], off
	s_lshl_b64 s[22:23], s[90:91], 15
	s_add_u32 s20, s20, s22
	s_addc_u32 s21, s21, s23
	s_waitcnt vmcnt(16)
	v_mov_b32_e32 v39, v19
	s_waitcnt vmcnt(3)
	ds_write_b128 v56, v[2:5] offset:32768
	s_waitcnt vmcnt(2)
	ds_write_b128 v56, v[6:9] offset:50176
	global_load_dwordx4 v[2:5], v[20:21], off
	s_waitcnt vmcnt(0)
	ds_write_b16 v57, v2
	ds_write_b16_d16_hi v57, v2 offset:144
	ds_write_b16 v57, v3 offset:288
	ds_write_b16_d16_hi v57, v3 offset:432
	ds_write_b16 v57, v4 offset:576
	ds_write_b16_d16_hi v57, v4 offset:720
	ds_write_b16 v57, v5 offset:864
	ds_write_b16_d16_hi v57, v5 offset:1008
	ds_write_b128 v59, v[10:13] offset:32768
	ds_write_b128 v59, v[14:17] offset:50176
	global_load_dwordx4 v[2:5], v[22:23], off
	s_waitcnt vmcnt(0)
	ds_write_b16 v60, v2
	ds_write_b16_d16_hi v60, v2 offset:144
	ds_write_b16 v60, v3 offset:288
	ds_write_b16_d16_hi v60, v3 offset:432
	ds_write_b16 v60, v4 offset:576
	ds_write_b16_d16_hi v60, v4 offset:720
	ds_write_b16 v60, v5 offset:864
	ds_write_b16_d16_hi v60, v5 offset:1008
	v_lshl_add_u64 v[2:3], v[28:29], 4, s[20:21]
	s_mov_b32 s20, 0x2b100000
	v_add_co_u32_e32 v4, vcc, s20, v2
	s_mov_b32 s20, 0x2b102000
	s_nop 0
	v_addc_co_u32_e32 v5, vcc, 0, v3, vcc
	global_load_dwordx4 v[24:27], v[4:5], off
	v_add_co_u32_e32 v4, vcc, s20, v2
	s_mov_b32 s20, 0x2b104000
	s_nop 0
	v_addc_co_u32_e32 v5, vcc, 0, v3, vcc
	global_load_dwordx4 v[20:23], v[4:5], off
	v_add_co_u32_e32 v4, vcc, s20, v2
	s_mov_b32 s20, 0x2b106000
	s_nop 0
	v_addc_co_u32_e32 v5, vcc, 0, v3, vcc
	v_add_co_u32_e32 v2, vcc, s20, v2
	s_lshl_b32 s20, s90, 7
	s_mov_b32 s21, s91
	s_lshl_b64 s[20:21], s[20:21], 2
	s_add_u32 s18, s18, s20
	s_addc_u32 s19, s19, s21
	v_lshl_add_u64 v[10:11], s[18:19], 0, v[38:39]
	s_mov_b64 s[18:19], 0x49300000
	v_addc_co_u32_e32 v3, vcc, 0, v3, vcc
	v_lshl_add_u64 v[14:15], v[10:11], 0, s[18:19]
	s_mov_b32 s18, 0x49300000
	v_add_co_u32_e32 v10, vcc, s18, v10
	global_load_dwordx4 v[6:9], v[4:5], off
	s_nop 0
	v_addc_co_u32_e32 v11, vcc, 0, v11, vcc
	global_load_dwordx4 v[2:5], v[2:3], off
	s_nop 0
	global_load_dwordx4 v[10:13], v[10:11], off
	s_nop 0
	global_load_dwordx4 v[14:17], v[14:15], off offset:16
	s_andn2_b64 vcc, exec, s[42:43]
	s_waitcnt vmcnt(5)
	v_lshlrev_b32_e32 v47, 16, v25
	v_lshlrev_b32_e32 v46, 16, v24
	v_and_b32_e32 v25, 0xffff0000, v25
	v_and_b32_e32 v24, 0xffff0000, v24
	s_waitcnt vmcnt(1)
	v_mov_b32_e32 v49, v12
	v_mov_b32_e32 v12, v11
	v_mov_b32_e32 v48, v10
	v_pk_mul_f32 v[10:11], v[12:13], v[24:25]
	v_lshlrev_b32_e32 v25, 16, v27
	v_lshlrev_b32_e32 v24, 16, v26
	s_waitcnt vmcnt(0)
	v_mov_b32_e32 v51, v16
	v_and_b32_e32 v27, 0xffff0000, v27
	v_and_b32_e32 v26, 0xffff0000, v26
	v_mov_b32_e32 v16, v15
	v_mov_b32_e32 v50, v14
	v_pk_mul_f32 v[14:15], v[16:17], v[26:27]
	v_pk_mul_f32 v[46:47], v[48:49], v[46:47]
	v_pk_mul_f32 v[24:25], v[50:51], v[24:25]
	v_bfe_u32 v18, v11, 16, 1
	v_bfe_u32 v26, v10, 16, 1
	v_bfe_u32 v27, v15, 16, 1
	v_bfe_u32 v39, v14, 16, 1
	v_add3_u32 v10, v10, v26, s79
	v_add3_u32 v11, v11, v18, s79
	v_add3_u32 v14, v14, v39, s79
	v_add3_u32 v15, v15, v27, s79
	v_bfe_u32 v18, v46, 16, 1
	v_bfe_u32 v26, v47, 16, 1
	v_bfe_u32 v27, v24, 16, 1
	v_bfe_u32 v39, v25, 16, 1
	v_add3_u32 v25, v25, v39, s79
	v_add3_u32 v24, v24, v27, s79
	v_add3_u32 v26, v47, v26, s79
	v_add3_u32 v18, v46, v18, s79
	v_lshrrev_b32_e32 v18, 16, v18
	v_lshrrev_b32_e32 v39, 16, v26
	v_lshrrev_b32_e32 v24, 16, v24
	v_lshrrev_b32_e32 v25, 16, v25
	v_and_or_b32 v27, v15, s80, v25
	v_and_or_b32 v26, v14, s80, v24
	v_and_or_b32 v25, v11, s80, v39
	v_and_or_b32 v24, v10, s80, v18
	v_add_u32_e32 v10, v61, v37
	ds_write_b128 v10, v[24:27]
	v_lshlrev_b32_e32 v11, 16, v21
	v_lshlrev_b32_e32 v10, 16, v20
	v_and_b32_e32 v15, 0xffff0000, v21
	v_and_b32_e32 v14, 0xffff0000, v20
	v_lshlrev_b32_e32 v21, 16, v23
	v_lshlrev_b32_e32 v20, 16, v22
	v_and_b32_e32 v23, 0xffff0000, v23
	v_and_b32_e32 v22, 0xffff0000, v22
	v_pk_mul_f32 v[14:15], v[12:13], v[14:15]
	v_pk_mul_f32 v[22:23], v[16:17], v[22:23]
	v_pk_mul_f32 v[10:11], v[48:49], v[10:11]
	v_pk_mul_f32 v[20:21], v[50:51], v[20:21]
	v_bfe_u32 v18, v15, 16, 1
	v_bfe_u32 v24, v14, 16, 1
	v_bfe_u32 v25, v23, 16, 1
	v_bfe_u32 v26, v22, 16, 1
	v_add3_u32 v14, v14, v24, s79
	v_add3_u32 v15, v15, v18, s79
	v_add3_u32 v18, v22, v26, s79
	v_add3_u32 v22, v23, v25, s79
	v_bfe_u32 v23, v10, 16, 1
	v_bfe_u32 v24, v11, 16, 1
	v_bfe_u32 v25, v20, 16, 1
	v_bfe_u32 v26, v21, 16, 1
	v_add3_u32 v21, v21, v26, s79
	v_add3_u32 v20, v20, v25, s79
	v_add3_u32 v11, v11, v24, s79
	v_add3_u32 v10, v10, v23, s79
	v_lshrrev_b32_e32 v10, 16, v10
	v_lshrrev_b32_e32 v11, 16, v11
	v_lshrrev_b32_e32 v20, 16, v20
	v_lshrrev_b32_e32 v21, 16, v21
	v_and_or_b32 v23, v22, s80, v21
	v_and_or_b32 v22, v18, s80, v20
	v_and_or_b32 v21, v15, s80, v11
	v_and_or_b32 v20, v14, s80, v10
	v_add_u32_e32 v10, v61, v58
	ds_write_b128 v10, v[20:23]
	v_lshlrev_b32_e32 v11, 16, v7
	v_lshlrev_b32_e32 v10, 16, v6
	v_and_b32_e32 v7, 0xffff0000, v7
	v_and_b32_e32 v6, 0xffff0000, v6
	v_lshlrev_b32_e32 v15, 16, v9
	v_lshlrev_b32_e32 v14, 16, v8
	v_and_b32_e32 v9, 0xffff0000, v9
	v_and_b32_e32 v8, 0xffff0000, v8
	v_pk_mul_f32 v[6:7], v[12:13], v[6:7]
	v_pk_mul_f32 v[8:9], v[16:17], v[8:9]
	v_pk_mul_f32 v[10:11], v[48:49], v[10:11]
	v_pk_mul_f32 v[14:15], v[50:51], v[14:15]
	v_cvt_pk_bf16_f32 v7, v11, v7
	v_cvt_pk_bf16_f32 v6, v10, v6
	v_cvt_pk_bf16_f32 v9, v15, v9
	v_cvt_pk_bf16_f32 v8, v14, v8
	ds_write_b128 v72, v[6:9]
	v_lshlrev_b32_e32 v7, 16, v3
	v_lshlrev_b32_e32 v6, 16, v2
	v_and_b32_e32 v3, 0xffff0000, v3
	v_and_b32_e32 v2, 0xffff0000, v2
	v_lshlrev_b32_e32 v9, 16, v5
	v_lshlrev_b32_e32 v8, 16, v4
	v_and_b32_e32 v5, 0xffff0000, v5
	v_and_b32_e32 v4, 0xffff0000, v4
	v_pk_mul_f32 v[2:3], v[12:13], v[2:3]
	v_pk_mul_f32 v[4:5], v[16:17], v[4:5]
	v_pk_mul_f32 v[6:7], v[48:49], v[6:7]
	v_pk_mul_f32 v[8:9], v[50:51], v[8:9]
	v_cvt_pk_bf16_f32 v3, v7, v3
	v_cvt_pk_bf16_f32 v2, v6, v2
	v_cvt_pk_bf16_f32 v5, v9, v5
	v_cvt_pk_bf16_f32 v4, v8, v4
	ds_write_b128 v73, v[2:5]
	v_cndmask_b32_e64 v2, 0, 1, s[42:43]
	v_cmp_ne_u32_e64 s[24:25], 1, v2
	s_waitcnt lgkmcnt(0)
	s_barrier
	s_cbranch_vccnz .LBB0_1479
	v_mov_b32_e32 v2, 0
	s_andn2_b64 vcc, exec, s[4:5]
	v_mov_b32_e32 v3, 0
	v_mov_b32_e32 v4, 0
	v_mov_b32_e32 v5, 0
	s_cbranch_vccnz .LBB0_1478
	ds_read_b128 v[2:5], v74 offset:32768
	ds_read_b128 v[6:9], v75 offset:50176
	s_waitcnt lgkmcnt(0)
	v_mfma_f32_16x16x32_bf16 v[2:5], v[2:5], v[6:9], 0
	ds_read_b128 v[6:9], v74 offset:32832
	ds_read_b128 v[10:13], v75 offset:50240
	s_waitcnt lgkmcnt(0)
	v_mfma_f32_16x16x32_bf16 v[2:5], v[6:9], v[10:13], v[2:5]
	ds_read_b128 v[6:9], v74 offset:32896
	ds_read_b128 v[10:13], v75 offset:50304
	s_waitcnt lgkmcnt(0)
	v_mfma_f32_16x16x32_bf16 v[2:5], v[6:9], v[10:13], v[2:5]
	ds_read_b128 v[6:9], v74 offset:32960
	ds_read_b128 v[10:13], v75 offset:50368
	s_waitcnt lgkmcnt(0)
	v_mfma_f32_16x16x32_bf16 v[2:5], v[6:9], v[10:13], v[2:5]

.LBB0_1669:
	v_add_u32_e32 v18, s0, v124
	v_add_u32_e32 v20, 0x10000, v18
	ds_read_b128 v[38:41], v20
	v_add_u32_e32 v20, 0x10400, v18
	s_addk_i32 s0, 0x2000
	s_cmpk_lg_u32 s0, 0xe000
	s_waitcnt vmcnt(0) lgkmcnt(0)
	v_pk_add_f32 v[36:37], v[36:37], v[40:41]
	v_pk_add_f32 v[34:35], v[34:35], v[38:39]
	ds_read_b128 v[38:41], v20
	v_add_u32_e32 v20, 0x10800, v18
	s_waitcnt lgkmcnt(0)
	v_pk_add_f32 v[32:33], v[32:33], v[40:41]
	v_pk_add_f32 v[30:31], v[30:31], v[38:39]
	ds_read_b128 v[38:41], v20
	v_add_u32_e32 v20, 0x10c00, v18
	s_waitcnt lgkmcnt(0)
	v_pk_add_f32 v[28:29], v[28:29], v[40:41]
	v_pk_add_f32 v[26:27], v[26:27], v[38:39]
	ds_read_b128 v[38:41], v20
	v_add_u32_e32 v20, 0x11000, v18
	s_waitcnt lgkmcnt(0)
	v_pk_add_f32 v[24:25], v[24:25], v[40:41]
	v_pk_add_f32 v[22:23], v[22:23], v[38:39]
	ds_read_b128 v[38:41], v20
	v_add_u32_e32 v20, 0x11400, v18
	s_waitcnt lgkmcnt(0)
	v_pk_add_f32 v[16:17], v[16:17], v[40:41]
	v_pk_add_f32 v[14:15], v[14:15], v[38:39]
	ds_read_b128 v[38:41], v20
	v_add_u32_e32 v20, 0x11800, v18
	v_add_u32_e32 v18, 0x11c00, v18
	s_waitcnt lgkmcnt(0)
	v_pk_add_f32 v[12:13], v[12:13], v[40:41]
	v_pk_add_f32 v[10:11], v[10:11], v[38:39]
	ds_read_b128 v[38:41], v20
	s_waitcnt lgkmcnt(0)
	v_pk_add_f32 v[8:9], v[8:9], v[40:41]
	v_pk_add_f32 v[6:7], v[6:7], v[38:39]
	ds_read_b128 v[38:41], v18
	s_waitcnt lgkmcnt(0)
	v_pk_add_f32 v[4:5], v[4:5], v[40:41]
	v_pk_add_f32 v[2:3], v[2:3], v[38:39]
	s_cbranch_scc1 .LBB0_1669
	s_lshr_b32 s1, s26, 3
	s_ashr_i32 s0, s18, 12
	s_add_i32 s1, s1, 2
	s_cmp_lt_i32 s26, 0
	s_cselect_b32 s0, s0, s1
	s_ashr_i32 s1, s0, 31
	s_add_u32 s0, s0, s24
	s_addc_u32 s1, s1, 0
	v_lshl_add_u64 v[20:21], s[20:21], 0, v[70:71]
	s_mul_i32 s1, s1, 0xc000
	s_mul_hi_u32 s20, s0, 0xc000
	s_add_i32 s20, s20, s1
	s_mul_i32 s0, s0, 0xc000
	global_store_dwordx4 v[20:21], v[34:37], off
	global_store_dwordx4 v[20:21], v[30:33], off offset:1024
	global_store_dwordx4 v[20:21], v[26:29], off offset:2048
	global_store_dwordx4 v[20:21], v[22:25], off offset:3072
	v_add_co_u32_e32 v20, vcc, 0x1000, v20
	s_add_u32 s0, s5, s0
	s_nop 0
	v_addc_co_u32_e32 v21, vcc, 0, v21, vcc
	s_addc_u32 s1, s25, s20
	global_store_dwordx4 v[20:21], v[14:17], off
	global_store_dwordx4 v[20:21], v[10:13], off offset:1024
	global_store_dwordx4 v[20:21], v[6:9], off offset:2048
	global_store_dwordx4 v[20:21], v[2:5], off offset:3072
	v_lshl_add_u64 v[20:21], s[0:1], 0, v[70:71]
	v_add_co_u32_e32 v130, vcc, s78, v20
	global_load_dwordx4 v[38:41], v[72:73], off
	s_nop 0
	v_addc_co_u32_e32 v131, vcc, 0, v21, vcc
	global_load_dwordx4 v[42:45], v[130:131], off offset:-4096
	global_load_dwordx4 v[54:57], v[20:21], off
	s_mov_b64 s[0:1], 0x2000
	v_lshl_add_u64 v[46:47], v[20:21], 0, s[0:1]
	v_mul_f32_e32 v18, v35, v35
	v_mul_f32_e32 v125, v37, v37
	v_fmac_f32_e32 v18, v34, v34
	v_fmac_f32_e32 v125, v36, v36
	v_add_f32_e32 v18, v18, v125
	v_mul_f32_e32 v125, v31, v31
	v_fmac_f32_e32 v125, v30, v30
	s_lshl_b64 s[0:1], s[18:19], 12
	s_waitcnt vmcnt(1)
	v_pk_add_f32 v[44:45], v[44:45], 1.0 op_sel_hi:[1,0]
	v_pk_add_f32 v[42:43], v[42:43], 1.0 op_sel_hi:[1,0]
	v_pk_mul_f32 v[98:99], v[40:41], v[44:45]
	v_pk_mul_f32 v[102:103], v[38:39], v[42:43]
	global_load_dwordx4 v[38:41], v[72:73], off offset:1024
	global_load_dwordx4 v[42:45], v[46:47], off offset:1024
	global_load_dwordx4 v[62:65], v[20:21], off offset:1024
	s_waitcnt vmcnt(1)
	v_pk_add_f32 v[44:45], v[44:45], 1.0 op_sel_hi:[1,0]
	v_pk_add_f32 v[42:43], v[42:43], 1.0 op_sel_hi:[1,0]
	v_pk_mul_f32 v[106:107], v[40:41], v[44:45]
	v_pk_mul_f32 v[110:111], v[38:39], v[42:43]
	global_load_dwordx4 v[38:41], v[72:73], off offset:2048
	global_load_dwordx4 v[42:45], v[46:47], off offset:2048
	global_load_dwordx4 v[66:69], v[20:21], off offset:2048
	s_waitcnt vmcnt(1)
	v_pk_add_f32 v[44:45], v[44:45], 1.0 op_sel_hi:[1,0]
	v_pk_add_f32 v[42:43], v[42:43], 1.0 op_sel_hi:[1,0]
	v_pk_mul_f32 v[112:113], v[40:41], v[44:45]
	v_pk_mul_f32 v[114:115], v[38:39], v[42:43]
	global_load_dwordx4 v[38:41], v[72:73], off offset:3072
	global_load_dwordx4 v[42:45], v[46:47], off offset:3072
	global_load_dwordx4 v[58:61], v[20:21], off offset:3072
	v_add_co_u32_e32 v20, vcc, s3, v20
	s_waitcnt vmcnt(1)
	v_pk_add_f32 v[44:45], v[44:45], 1.0 op_sel_hi:[1,0]
	v_pk_add_f32 v[42:43], v[42:43], 1.0 op_sel_hi:[1,0]
	v_pk_mul_f32 v[104:105], v[40:41], v[44:45]
	v_pk_mul_f32 v[108:109], v[38:39], v[42:43]
	global_load_dwordx4 v[38:41], v[74:75], off
	global_load_dwordx4 v[42:45], v[130:131], off
	v_addc_co_u32_e32 v21, vcc, 0, v21, vcc
	global_load_dwordx4 v[50:53], v[20:21], off
	s_waitcnt vmcnt(1)
	v_pk_add_f32 v[44:45], v[44:45], 1.0 op_sel_hi:[1,0]
	v_pk_add_f32 v[42:43], v[42:43], 1.0 op_sel_hi:[1,0]
	v_pk_mul_f32 v[96:97], v[40:41], v[44:45]
	v_pk_mul_f32 v[100:101], v[38:39], v[42:43]
	global_load_dwordx4 v[38:41], v[76:77], off
	global_load_dwordx4 v[42:45], v[130:131], off offset:1024
	global_load_dwordx4 v[46:49], v[20:21], off offset:1024
	s_waitcnt vmcnt(1)
	v_pk_add_f32 v[44:45], v[44:45], 1.0 op_sel_hi:[1,0]
	v_pk_add_f32 v[42:43], v[42:43], 1.0 op_sel_hi:[1,0]
	v_pk_mul_f32 v[92:93], v[40:41], v[44:45]
	v_pk_mul_f32 v[94:95], v[38:39], v[42:43]
	global_load_dwordx4 v[38:41], v[78:79], off
	global_load_dwordx4 v[86:89], v[130:131], off offset:2048
	global_load_dwordx4 v[42:45], v[20:21], off offset:2048
	s_waitcnt vmcnt(1)
	v_pk_add_f32 v[88:89], v[88:89], 1.0 op_sel_hi:[1,0]
	v_pk_add_f32 v[86:87], v[86:87], 1.0 op_sel_hi:[1,0]
	v_pk_mul_f32 v[88:89], v[40:41], v[88:89]
	v_pk_mul_f32 v[90:91], v[38:39], v[86:87]
	global_load_dwordx4 v[126:129], v[80:81], off
	s_nop 0
	global_load_dwordx4 v[130:133], v[130:131], off offset:3072
	s_nop 0
	global_load_dwordx4 v[38:41], v[20:21], off offset:3072
	s_waitcnt vmcnt(1)
	v_pk_add_f32 v[86:87], v[130:131], 1.0 op_sel_hi:[1,0]
	s_nop 0
	v_pk_mul_f32 v[86:87], v[126:127], v[86:87]
	v_mul_f32_e32 v126, v33, v33
	v_fmac_f32_e32 v126, v32, v32
	v_add_f32_e32 v125, v125, v126
	v_add_f32_e32 v18, v18, v125
	v_mul_f32_e32 v125, v27, v27
	v_mul_f32_e32 v126, v29, v29
	v_fmac_f32_e32 v125, v26, v26
	v_fmac_f32_e32 v126, v28, v28
	v_add_f32_e32 v125, v125, v126
	v_add_f32_e32 v18, v18, v125
	v_mul_f32_e32 v125, v23, v23
	v_mul_f32_e32 v126, v25, v25
	v_fmac_f32_e32 v125, v22, v22
	v_fmac_f32_e32 v126, v24, v24
	v_add_f32_e32 v125, v125, v126
	v_add_f32_e32 v18, v18, v125
	v_mul_f32_e32 v125, v15, v15
	v_mul_f32_e32 v126, v17, v17
	v_fmac_f32_e32 v125, v14, v14
	v_fmac_f32_e32 v126, v16, v16
	v_add_f32_e32 v125, v125, v126
	v_add_f32_e32 v18, v18, v125
	v_mul_f32_e32 v125, v11, v11
	v_mul_f32_e32 v126, v13, v13
	v_fmac_f32_e32 v125, v10, v10
	v_fmac_f32_e32 v126, v12, v12
	v_add_f32_e32 v125, v125, v126
	v_add_f32_e32 v18, v18, v125
	v_mul_f32_e32 v125, v7, v7
	v_mul_f32_e32 v126, v9, v9
	v_fmac_f32_e32 v125, v6, v6
	v_fmac_f32_e32 v126, v8, v8
	v_add_f32_e32 v125, v125, v126
	v_add_f32_e32 v18, v18, v125
	v_mul_f32_e32 v125, v3, v3
	v_mul_f32_e32 v126, v5, v5
	v_fmac_f32_e32 v125, v2, v2
	v_fmac_f32_e32 v126, v4, v4
	v_add_f32_e32 v125, v125, v126
	v_add_f32_e32 v18, v18, v125
	v_and_b32_e32 v125, 64, v213
	v_add_u32_e32 v125, 64, v125
	v_xor_b32_e32 v126, 1, v213
	v_cmp_lt_i32_e32 vcc, v126, v125
	v_pk_add_f32 v[20:21], v[132:133], 1.0 op_sel_hi:[1,0]
	s_nop 0
	v_cndmask_b32_e32 v126, v213, v126, vcc
	v_lshlrev_b32_e32 v126, 2, v126
	ds_bpermute_b32 v126, v126, v18
	v_pk_mul_f32 v[20:21], v[128:129], v[20:21]
	s_waitcnt lgkmcnt(0)
	v_add_f32_e32 v18, v18, v126
	v_xor_b32_e32 v126, 2, v213
	v_cmp_lt_i32_e32 vcc, v126, v125
	s_nop 1
	v_cndmask_b32_e32 v126, v213, v126, vcc
	v_lshlrev_b32_e32 v126, 2, v126
	ds_bpermute_b32 v126, v126, v18
	s_waitcnt lgkmcnt(0)
	v_add_f32_e32 v18, v18, v126
	v_xor_b32_e32 v126, 4, v213
	v_cmp_lt_i32_e32 vcc, v126, v125
	s_nop 1
	v_cndmask_b32_e32 v126, v213, v126, vcc
	v_lshlrev_b32_e32 v126, 2, v126
	ds_bpermute_b32 v126, v126, v18
	s_waitcnt lgkmcnt(0)
	v_add_f32_e32 v18, v18, v126
	v_xor_b32_e32 v126, 8, v213
	v_cmp_lt_i32_e32 vcc, v126, v125
	s_nop 1
	v_cndmask_b32_e32 v126, v213, v126, vcc
	v_lshlrev_b32_e32 v126, 2, v126
	ds_bpermute_b32 v126, v126, v18
	s_waitcnt lgkmcnt(0)
	v_add_f32_e32 v18, v18, v126
	v_xor_b32_e32 v126, 16, v213
	v_cmp_lt_i32_e32 vcc, v126, v125
	s_nop 1
	v_cndmask_b32_e32 v126, v213, v126, vcc
	v_lshlrev_b32_e32 v126, 2, v126
	ds_bpermute_b32 v126, v126, v18
	s_waitcnt lgkmcnt(0)
	v_add_f32_e32 v18, v18, v126
	v_xor_b32_e32 v126, 32, v213
	v_cmp_lt_i32_e32 vcc, v126, v125
	s_nop 1
	v_cndmask_b32_e32 v125, v213, v126, vcc
	v_lshlrev_b32_e32 v125, 2, v125
	ds_bpermute_b32 v125, v125, v18
	s_waitcnt lgkmcnt(0)
	v_add_f32_e32 v18, v18, v125
	v_fmamk_f32 v18, v18, 0x3a000000, v165
	v_rsq_f32_e32 v18, v18
	s_nop 0
	v_mul_f32_e32 v34, v34, v18
	v_mul_f32_e32 v30, v30, v18
	v_mul_f32_e32 v26, v26, v18
	v_mul_f32_e32 v22, v22, v18
	v_mul_f32_e32 v14, v14, v18
	v_mul_f32_e32 v10, v10, v18
	v_mul_f32_e32 v6, v6, v18
	v_mul_f32_e32 v2, v2, v18
	v_fma_f32 v34, v102, v34, v54
	v_mul_f32_e32 v35, v35, v18
	v_mul_f32_e32 v37, v37, v18
	v_fma_f32 v30, v110, v30, v62
	v_mul_f32_e32 v31, v31, v18
	v_mul_f32_e32 v33, v33, v18
	v_fma_f32 v26, v114, v26, v66
	v_mul_f32_e32 v27, v27, v18
	v_mul_f32_e32 v29, v29, v18
	v_fma_f32 v22, v108, v22, v58
	v_mul_f32_e32 v23, v23, v18
	v_mul_f32_e32 v25, v25, v18
	v_fma_f32 v14, v100, v14, v50
	v_mul_f32_e32 v15, v15, v18
	v_mul_f32_e32 v17, v17, v18
	v_fma_f32 v10, v94, v10, v46
	v_mul_f32_e32 v11, v11, v18
	v_mul_f32_e32 v13, v13, v18
	v_fma_f32 v6, v90, v6, v42
	v_mul_f32_e32 v7, v7, v18
	v_mul_f32_e32 v9, v9, v18
	s_waitcnt vmcnt(0)
	v_fma_f32 v2, v86, v2, v38
	v_mul_f32_e32 v3, v3, v18
	v_mul_f32_e32 v5, v5, v18
	v_fma_f32 v35, v103, v35, v55
	v_fmac_f32_e32 v57, v99, v37
	v_cvt_pk_bf16_f32 v34, v34, v35
	v_fma_f32 v31, v111, v31, v63
	v_fmac_f32_e32 v65, v107, v33
	v_cvt_pk_bf16_f32 v30, v30, v31
	v_fma_f32 v27, v115, v27, v67
	v_fmac_f32_e32 v69, v113, v29
	v_cvt_pk_bf16_f32 v26, v26, v27
	v_fma_f32 v23, v109, v23, v59
	v_fmac_f32_e32 v61, v105, v25
	v_cvt_pk_bf16_f32 v22, v22, v23
	v_fma_f32 v15, v101, v15, v51
	v_fmac_f32_e32 v53, v97, v17
	v_cvt_pk_bf16_f32 v14, v14, v15
	v_fma_f32 v11, v95, v11, v47
	v_fmac_f32_e32 v49, v93, v13
	v_cvt_pk_bf16_f32 v10, v10, v11
	v_fma_f32 v7, v91, v7, v43
	v_fmac_f32_e32 v45, v89, v9
	v_cvt_pk_bf16_f32 v6, v6, v7
	v_fma_f32 v3, v87, v3, v39
	v_fmac_f32_e32 v41, v21, v5
	v_cvt_pk_bf16_f32 v2, v2, v3
	v_mul_f32_e32 v36, v36, v18
	v_mul_f32_e32 v32, v32, v18
	v_mul_f32_e32 v28, v28, v18
	v_mul_f32_e32 v24, v24, v18
	v_mul_f32_e32 v16, v16, v18
	v_mul_f32_e32 v12, v12, v18
	v_mul_f32_e32 v8, v8, v18
	v_mul_f32_e32 v4, v4, v18
	v_fma_f32 v36, v98, v36, v56
	v_fma_f32 v32, v106, v32, v64
	v_fma_f32 v28, v112, v28, v68
	v_fma_f32 v24, v104, v24, v60
	v_fma_f32 v16, v96, v16, v52
	v_fma_f32 v12, v92, v12, v48
	v_fma_f32 v8, v88, v8, v44
	v_fma_f32 v4, v20, v4, v40
	v_bfe_u32 v35, v36, 16, 1
	v_bfe_u32 v31, v32, 16, 1
	v_bfe_u32 v27, v28, 16, 1
	v_bfe_u32 v23, v24, 16, 1
	v_bfe_u32 v15, v16, 16, 1
	v_bfe_u32 v11, v12, 16, 1
	v_bfe_u32 v7, v8, 16, 1
	v_bfe_u32 v3, v4, 16, 1
	v_add3_u32 v35, v36, v35, s79
	v_bfe_u32 v36, v57, 16, 1
	v_add3_u32 v31, v32, v31, s79
	v_bfe_u32 v32, v65, 16, 1
	v_add3_u32 v27, v28, v27, s79
	v_bfe_u32 v28, v69, 16, 1
	v_add3_u32 v23, v24, v23, s79
	v_bfe_u32 v24, v61, 16, 1
	v_add3_u32 v15, v16, v15, s79
	v_bfe_u32 v16, v53, 16, 1
	v_add3_u32 v11, v12, v11, s79
	v_bfe_u32 v12, v49, 16, 1
	v_add3_u32 v7, v8, v7, s79
	v_bfe_u32 v8, v45, 16, 1
	v_add3_u32 v3, v4, v3, s79
	v_bfe_u32 v4, v41, 16, 1
	v_lshrrev_b32_e32 v35, 16, v35
	v_add3_u32 v36, v57, v36, s79
	v_lshrrev_b32_e32 v31, 16, v31
	v_add3_u32 v32, v65, v32, s79
	v_lshrrev_b32_e32 v27, 16, v27
	v_add3_u32 v28, v69, v28, s79
	v_lshrrev_b32_e32 v23, 16, v23
	v_add3_u32 v24, v61, v24, s79
	v_lshrrev_b32_e32 v15, 16, v15
	v_add3_u32 v16, v53, v16, s79
	v_lshrrev_b32_e32 v11, 16, v11
	v_add3_u32 v12, v49, v12, s79
	v_lshrrev_b32_e32 v7, 16, v7
	v_add3_u32 v8, v45, v8, s79
	v_lshrrev_b32_e32 v3, 16, v3
	v_add3_u32 v4, v41, v4, s79
	v_and_or_b32 v35, v36, s80, v35
	v_lshl_add_u64 v[36:37], v[82:83], 0, s[0:1]
	v_and_or_b32 v31, v32, s80, v31
	v_and_or_b32 v27, v28, s80, v27
	v_and_or_b32 v23, v24, s80, v23
	v_and_or_b32 v15, v16, s80, v15
	v_and_or_b32 v11, v12, s80, v11
	v_and_or_b32 v7, v8, s80, v7
	v_and_or_b32 v3, v4, s80, v3
	global_store_dwordx2 v[36:37], v[34:35], off
	global_store_dwordx2 v[36:37], v[30:31], off offset:512
	global_store_dwordx2 v[36:37], v[26:27], off offset:1024
	global_store_dwordx2 v[36:37], v[22:23], off offset:1536
	global_store_dwordx2 v[36:37], v[14:15], off offset:2048
	global_store_dwordx2 v[36:37], v[10:11], off offset:2560
	global_store_dwordx2 v[36:37], v[6:7], off offset:3072
	global_store_dwordx2 v[36:37], v[2:3], off offset:3584
	s_branch .LBB0_1656

.LBB0_1683:
	s_mov_b32 s0, 0x20400
	s_mov_b32 s0, 0x20408
	s_nop 0
	v_readlane_b32 s0, v250, 56
	s_mul_i32 s0, s0, 24
	v_readlane_b32 s1, v250, 57
	v_mov_b32_e32 v1, s0
	v_add_u32_e32 v1, s4, v1
	s_movk_i32 s0, 0x1fff
	v_cmp_lt_i32_e32 vcc, s0, v1
	s_and_b64 s[0:1], vcc, exec
	v_readfirstlane_b32 s0, v1
	s_cbranch_scc1 .LBB0_1687
	s_add_i32 s5, s4, 0xffffe000
	s_lshr_b32 s5, s5, 3
	s_ashr_i32 s1, s4, 12
	s_add_i32 s5, s5, 2
	s_cmpk_lt_i32 s4, 0x2000
	s_cselect_b32 s23, s1, s5
	v_readlane_b32 s1, v251, 24
	s_sub_i32 s14, s0, s1
	s_add_i32 s5, s14, 0xffffe000
	s_lshr_b32 s5, s5, 3
	s_ashr_i32 s1, s14, 12
	s_add_i32 s5, s5, 2
	s_cmpk_lt_i32 s14, 0x2000
	s_cselect_b32 s1, s1, s5
	s_cmp_lg_u32 s23, s1
	s_cbranch_scc1 .LBB0_1687
	v_readlane_b32 s1, v254, 12
	s_add_i32 s12, s14, s1
	s_add_i32 s5, s12, 0xffffe000
	s_lshr_b32 s5, s5, 3
	s_ashr_i32 s1, s12, 12
	s_add_i32 s5, s5, 2
	s_cmpk_lt_i32 s12, 0x2000
	s_cselect_b32 s20, s1, s5
	s_ashr_i32 s1, s0, 12
	s_cmp_lg_u32 s20, s1
	s_cbranch_scc1 .LBB0_1687
	s_add_u32 s21, s6, 0x100000
	s_addc_u32 s22, s7, 0
	s_ashr_i32 s5, s4, 31
	s_lshl_b64 s[16:17], s[4:5], 13
	s_add_u32 s26, s28, s16
	s_addc_u32 s27, s29, s17
	s_ashr_i32 s15, s14, 31
	s_lshl_b64 s[16:17], s[14:15], 13
	s_add_u32 s38, s28, s16
	s_addc_u32 s39, s29, s17
	v_lshlrev_b64 v[172:173], 4, v[170:171]
	s_ashr_i32 s13, s12, 31
	s_ashr_i32 s1, s0, 31
	s_waitcnt vmcnt(0)
	v_lshl_add_u64 v[2:3], s[26:27], 0, v[172:173]
	v_lshl_add_u64 v[4:5], s[38:39], 0, v[172:173]
	s_lshl_b64 s[16:17], s[12:13], 13
	s_lshl_b64 s[18:19], s[0:1], 13
	global_load_dwordx4 v[128:131], v[2:3], off
	global_load_dwordx4 v[96:99], v[4:5], off
	global_load_dwordx4 v[124:127], v[2:3], off offset:1024
	global_load_dwordx4 v[92:95], v[4:5], off offset:1024
	global_load_dwordx4 v[120:123], v[2:3], off offset:2048
	global_load_dwordx4 v[88:91], v[4:5], off offset:2048
	global_load_dwordx4 v[116:119], v[2:3], off offset:3072
	global_load_dwordx4 v[84:87], v[4:5], off offset:3072
	v_add_co_u32_e32 v2, vcc, s3, v2
	s_add_u32 s16, s28, s16
	s_nop 0
	v_addc_co_u32_e32 v3, vcc, 0, v3, vcc
	v_add_co_u32_e32 v4, vcc, s3, v4
	s_addc_u32 s17, s29, s17
	s_nop 0
	v_addc_co_u32_e32 v5, vcc, 0, v5, vcc
	s_add_u32 s18, s28, s18
	global_load_dwordx4 v[112:115], v[2:3], off
	global_load_dwordx4 v[80:83], v[4:5], off
	global_load_dwordx4 v[108:111], v[2:3], off offset:1024
	global_load_dwordx4 v[76:79], v[4:5], off offset:1024
	global_load_dwordx4 v[104:107], v[2:3], off offset:2048
	global_load_dwordx4 v[72:75], v[4:5], off offset:2048
	global_load_dwordx4 v[100:103], v[2:3], off offset:3072
	global_load_dwordx4 v[68:71], v[4:5], off offset:3072
	s_addc_u32 s19, s29, s19
	v_lshl_add_u64 v[2:3], s[16:17], 0, v[172:173]
	s_ashr_i32 s16, s23, 31
	s_add_u32 s17, s23, s24
	s_addc_u32 s16, s16, 0
	v_lshl_add_u64 v[4:5], s[18:19], 0, v[172:173]
	s_mul_i32 s16, s16, 0xc000
	s_mul_hi_u32 s18, s17, 0xc000
	global_load_dwordx4 v[64:67], v[2:3], off
	global_load_dwordx4 v[32:35], v[4:5], off
	global_load_dwordx4 v[60:63], v[2:3], off offset:1024
	global_load_dwordx4 v[28:31], v[4:5], off offset:1024
	global_load_dwordx4 v[56:59], v[2:3], off offset:2048
	global_load_dwordx4 v[24:27], v[4:5], off offset:2048
	global_load_dwordx4 v[52:55], v[2:3], off offset:3072
	global_load_dwordx4 v[20:23], v[4:5], off offset:3072
	v_add_co_u32_e32 v2, vcc, s3, v2
	s_add_i32 s18, s18, s16
	s_mul_i32 s17, s17, 0xc000
	v_addc_co_u32_e32 v3, vcc, 0, v3, vcc
	s_add_u32 s16, s21, s17
	v_add_co_u32_e32 v4, vcc, s3, v4
	s_addc_u32 s17, s22, s18
	s_nop 0
	v_addc_co_u32_e32 v5, vcc, 0, v5, vcc
	v_lshl_add_u64 v[132:133], s[16:17], 0, v[172:173]
	s_mov_b32 s19, 0x9000
	v_add_co_u32_e32 v160, vcc, s19, v132
	global_load_dwordx4 v[48:51], v[2:3], off
	s_nop 0
	v_addc_co_u32_e32 v161, vcc, 0, v133, vcc
	global_load_dwordx4 v[14:17], v[4:5], off
	global_load_dwordx4 v[44:47], v[2:3], off offset:1024
	global_load_dwordx4 v[10:13], v[4:5], off offset:1024
	global_load_dwordx4 v[40:43], v[2:3], off offset:2048
	global_load_dwordx4 v[6:9], v[4:5], off offset:2048
	global_load_dwordx4 v[36:39], v[2:3], off offset:3072
	s_nop 0
	global_load_dwordx4 v[2:5], v[4:5], off offset:3072
	v_lshl_add_u64 v[176:177], s[10:11], 0, v[172:173]
	global_load_dwordx4 v[140:143], v[160:161], off offset:-4096
	global_load_dwordx4 v[136:139], v[176:177], off
	s_movk_i32 s18, 0x7000
	v_add_co_u32_e32 v162, vcc, s18, v132
	s_mov_b64 s[26:27], 0x8000
	s_mov_b64 s[38:39], 0x6000
	v_addc_co_u32_e32 v163, vcc, 0, v133, vcc
	v_lshl_add_u64 v[152:153], v[132:133], 0, s[26:27]
	v_lshl_add_u64 v[156:157], v[132:133], 0, s[38:39]
	global_load_dwordx4 v[132:135], v[162:163], off offset:-4096
	v_add_co_u32_e32 v174, vcc, s3, v176
	s_lshl_b64 s[16:17], s[4:5], 12
	s_nop 0
	v_addc_co_u32_e32 v175, vcc, 0, v177, vcc
	s_add_u32 s16, s8, s16
	s_addc_u32 s17, s9, s17
	s_lshl_b64 s[14:15], s[14:15], 12
	s_add_u32 s14, s8, s14
	s_addc_u32 s15, s9, s15
	s_ashr_i32 s5, s20, 31
	s_mov_b64 s[84:85], 0x8000
	s_waitcnt vmcnt(32)
	v_mul_f32_e32 v167, v127, v127
	v_fmac_f32_e32 v167, v126, v126
	v_mul_f32_e32 v1, v129, v129
	v_mul_f32_e32 v18, v131, v131
	v_fmac_f32_e32 v1, v128, v128
	v_fmac_f32_e32 v18, v130, v130
	v_add_f32_e32 v1, v1, v18
	v_mul_f32_e32 v18, v125, v125
	v_fmac_f32_e32 v18, v124, v124
	v_add_f32_e32 v18, v18, v167
	v_add_f32_e32 v1, v1, v18
	s_waitcnt vmcnt(30)
	v_mul_f32_e32 v18, v121, v121
	v_mul_f32_e32 v167, v123, v123
	v_fmac_f32_e32 v18, v120, v120
	v_fmac_f32_e32 v167, v122, v122
	v_add_f32_e32 v18, v18, v167
	v_add_f32_e32 v1, v1, v18
	s_waitcnt vmcnt(28)
	v_mul_f32_e32 v18, v117, v117
	v_mul_f32_e32 v167, v119, v119
	v_fmac_f32_e32 v18, v116, v116
	v_fmac_f32_e32 v167, v118, v118
	v_add_f32_e32 v18, v18, v167
	v_add_f32_e32 v1, v1, v18
	s_waitcnt vmcnt(26)
	v_mul_f32_e32 v18, v113, v113
	v_mul_f32_e32 v167, v115, v115
	v_fmac_f32_e32 v18, v112, v112
	v_fmac_f32_e32 v167, v114, v114
	v_add_f32_e32 v18, v18, v167
	v_add_f32_e32 v1, v1, v18
	s_waitcnt vmcnt(24)
	v_mul_f32_e32 v18, v109, v109
	v_mul_f32_e32 v167, v111, v111
	v_fmac_f32_e32 v18, v108, v108
	v_fmac_f32_e32 v167, v110, v110
	v_add_f32_e32 v18, v18, v167
	v_add_f32_e32 v1, v1, v18
	s_waitcnt vmcnt(22)
	v_mul_f32_e32 v18, v105, v105
	v_mul_f32_e32 v167, v107, v107
	v_fmac_f32_e32 v18, v104, v104
	v_fmac_f32_e32 v167, v106, v106
	v_add_f32_e32 v18, v18, v167
	v_add_f32_e32 v1, v1, v18
	s_waitcnt vmcnt(20)
	v_mul_f32_e32 v18, v101, v101
	v_mul_f32_e32 v167, v103, v103
	v_fmac_f32_e32 v18, v100, v100
	v_fmac_f32_e32 v167, v102, v102
	v_add_f32_e32 v18, v18, v167
	v_add_f32_e32 v18, v1, v18
	v_mul_f32_e32 v1, v97, v97
	s_waitcnt vmcnt(2)
	v_pk_add_f32 v[142:143], v[142:143], 1.0 op_sel_hi:[1,0]
	v_pk_add_f32 v[140:141], v[140:141], 1.0 op_sel_hi:[1,0]
	s_waitcnt vmcnt(1)
	v_pk_mul_f32 v[178:179], v[138:139], v[142:143]
	v_pk_mul_f32 v[180:181], v[136:137], v[140:141]
	global_load_dwordx4 v[140:143], v[176:177], off offset:1024
	global_load_dwordx4 v[144:147], v[152:153], off offset:1024
	global_load_dwordx4 v[136:139], v[156:157], off offset:1024
	v_mul_f32_e32 v167, v99, v99
	v_fmac_f32_e32 v1, v96, v96
	v_fmac_f32_e32 v167, v98, v98
	v_add_f32_e32 v1, v1, v167
	v_mul_f32_e32 v167, v93, v93
	v_fmac_f32_e32 v167, v92, v92
	s_waitcnt vmcnt(1)
	v_pk_add_f32 v[146:147], v[146:147], 1.0 op_sel_hi:[1,0]
	v_pk_add_f32 v[144:145], v[144:145], 1.0 op_sel_hi:[1,0]
	v_pk_mul_f32 v[182:183], v[142:143], v[146:147]
	v_pk_mul_f32 v[184:185], v[140:141], v[144:145]
	global_load_dwordx4 v[144:147], v[176:177], off offset:2048
	global_load_dwordx4 v[148:151], v[152:153], off offset:2048
	global_load_dwordx4 v[140:143], v[156:157], off offset:2048
	s_waitcnt vmcnt(1)
	v_pk_add_f32 v[150:151], v[150:151], 1.0 op_sel_hi:[1,0]
	v_pk_add_f32 v[148:149], v[148:149], 1.0 op_sel_hi:[1,0]
	v_pk_mul_f32 v[186:187], v[146:147], v[150:151]
	v_pk_mul_f32 v[188:189], v[144:145], v[148:149]
	global_load_dwordx4 v[148:151], v[176:177], off offset:3072
	s_nop 0
	global_load_dwordx4 v[152:155], v[152:153], off offset:3072
	s_nop 0
	global_load_dwordx4 v[144:147], v[156:157], off offset:3072
	s_waitcnt vmcnt(1)
	v_pk_add_f32 v[154:155], v[154:155], 1.0 op_sel_hi:[1,0]
	v_pk_add_f32 v[152:153], v[152:153], 1.0 op_sel_hi:[1,0]
	v_pk_mul_f32 v[190:191], v[150:151], v[154:155]
	v_pk_mul_f32 v[192:193], v[148:149], v[152:153]
	global_load_dwordx4 v[152:155], v[174:175], off
	global_load_dwordx4 v[156:159], v[160:161], off
	global_load_dwordx4 v[148:151], v[162:163], off
	s_waitcnt vmcnt(1)
	v_pk_add_f32 v[158:159], v[158:159], 1.0 op_sel_hi:[1,0]
	v_pk_add_f32 v[156:157], v[156:157], 1.0 op_sel_hi:[1,0]
	v_pk_mul_f32 v[194:195], v[154:155], v[158:159]
	v_pk_mul_f32 v[198:199], v[152:153], v[156:157]
	global_load_dwordx4 v[156:159], v[174:175], off offset:1024
	global_load_dwordx4 v[200:203], v[160:161], off offset:1024
	global_load_dwordx4 v[152:155], v[162:163], off offset:1024
	s_waitcnt vmcnt(1)
	v_pk_add_f32 v[168:169], v[202:203], 1.0 op_sel_hi:[1,0]
	v_pk_add_f32 v[200:201], v[200:201], 1.0 op_sel_hi:[1,0]
	v_pk_mul_f32 v[196:197], v[158:159], v[168:169]
	v_pk_mul_f32 v[200:201], v[156:157], v[200:201]
	global_load_dwordx4 v[204:207], v[174:175], off offset:2048
	global_load_dwordx4 v[220:223], v[160:161], off offset:2048
	global_load_dwordx4 v[156:159], v[162:163], off offset:2048
	s_waitcnt vmcnt(1)
	v_pk_add_f32 v[168:169], v[222:223], 1.0 op_sel_hi:[1,0]
	v_pk_add_f32 v[208:209], v[220:221], 1.0 op_sel_hi:[1,0]
	v_pk_mul_f32 v[202:203], v[206:207], v[168:169]
	v_pk_mul_f32 v[204:205], v[204:205], v[208:209]
	global_load_dwordx4 v[220:223], v[174:175], off offset:3072
	global_load_dwordx4 v[206:209], v[160:161], off offset:3072
	s_nop 0
	global_load_dwordx4 v[160:163], v[162:163], off offset:3072
	s_waitcnt vmcnt(1)
	v_pk_add_f32 v[168:169], v[208:209], 1.0 op_sel_hi:[1,0]
	v_pk_add_f32 v[208:209], v[206:207], 1.0 op_sel_hi:[1,0]
	v_pk_mul_f32 v[206:207], v[222:223], v[168:169]
	v_mul_f32_e32 v168, v95, v95
	v_fmac_f32_e32 v168, v94, v94
	v_add_f32_e32 v167, v167, v168
	v_add_f32_e32 v1, v1, v167
	v_mul_f32_e32 v167, v89, v89
	v_mul_f32_e32 v168, v91, v91
	v_fmac_f32_e32 v167, v88, v88
	v_fmac_f32_e32 v168, v90, v90
	v_add_f32_e32 v167, v167, v168
	v_add_f32_e32 v1, v1, v167
	v_mul_f32_e32 v167, v85, v85
	v_mul_f32_e32 v168, v87, v87
	v_fmac_f32_e32 v167, v84, v84
	v_fmac_f32_e32 v168, v86, v86
	v_add_f32_e32 v167, v167, v168
	v_add_f32_e32 v1, v1, v167
	v_mul_f32_e32 v167, v81, v81
	v_mul_f32_e32 v168, v83, v83
	v_fmac_f32_e32 v167, v80, v80
	v_fmac_f32_e32 v168, v82, v82
	v_add_f32_e32 v167, v167, v168
	v_add_f32_e32 v1, v1, v167
	v_mul_f32_e32 v167, v77, v77
	v_mul_f32_e32 v168, v79, v79
	v_fmac_f32_e32 v167, v76, v76
	v_fmac_f32_e32 v168, v78, v78
	v_add_f32_e32 v167, v167, v168
	v_add_f32_e32 v1, v1, v167
	v_mul_f32_e32 v167, v73, v73
	v_mul_f32_e32 v168, v75, v75
	v_fmac_f32_e32 v167, v72, v72
	v_fmac_f32_e32 v168, v74, v74
	v_add_f32_e32 v167, v167, v168
	v_add_f32_e32 v1, v1, v167
	v_mul_f32_e32 v167, v69, v69
	v_mul_f32_e32 v168, v71, v71
	v_fmac_f32_e32 v167, v68, v68
	v_fmac_f32_e32 v168, v70, v70
	v_add_f32_e32 v167, v167, v168
	v_add_f32_e32 v167, v1, v167
	v_and_b32_e32 v1, 64, v213
	v_add_u32_e32 v168, 64, v1
	v_xor_b32_e32 v1, 1, v213
	v_cmp_lt_i32_e32 vcc, v1, v168
	v_pk_mul_f32 v[208:209], v[220:221], v[208:209]
	s_nop 0
	v_cndmask_b32_e32 v1, v213, v1, vcc
	v_lshlrev_b32_e32 v1, 2, v1
	ds_bpermute_b32 v169, v1, v18
	s_waitcnt lgkmcnt(0)
	v_add_f32_e32 v169, v18, v169
	ds_bpermute_b32 v18, v1, v167
	s_waitcnt lgkmcnt(0)
	v_add_f32_e32 v167, v167, v18
	v_xor_b32_e32 v18, 2, v213
	v_cmp_lt_i32_e32 vcc, v18, v168
	s_nop 1
	v_cndmask_b32_e32 v18, v213, v18, vcc
	v_lshlrev_b32_e32 v18, 2, v18
	ds_bpermute_b32 v218, v18, v169
	s_waitcnt lgkmcnt(0)
	v_add_f32_e32 v169, v169, v218
	ds_bpermute_b32 v218, v18, v167
	s_waitcnt lgkmcnt(0)
	v_add_f32_e32 v218, v167, v218
	v_xor_b32_e32 v167, 4, v213
	v_cmp_lt_i32_e32 vcc, v167, v168
	s_nop 1
	v_cndmask_b32_e32 v167, v213, v167, vcc
	v_lshlrev_b32_e32 v167, 2, v167
	ds_bpermute_b32 v219, v167, v169
	s_waitcnt lgkmcnt(0)
	v_add_f32_e32 v169, v169, v219
	ds_bpermute_b32 v219, v167, v218
	s_waitcnt lgkmcnt(0)
	v_add_f32_e32 v218, v218, v219
	v_xor_b32_e32 v219, 8, v213
	v_cmp_lt_i32_e32 vcc, v219, v168
	s_nop 1
	v_cndmask_b32_e32 v219, v213, v219, vcc
	v_lshlrev_b32_e32 v220, 2, v219
	ds_bpermute_b32 v219, v220, v169
	s_waitcnt lgkmcnt(0)
	v_add_f32_e32 v169, v169, v219
	ds_bpermute_b32 v219, v220, v218
	s_waitcnt lgkmcnt(0)
	v_add_f32_e32 v218, v218, v219
	v_xor_b32_e32 v219, 16, v213
	v_cmp_lt_i32_e32 vcc, v219, v168
	s_nop 1
	v_cndmask_b32_e32 v219, v213, v219, vcc
	v_lshlrev_b32_e32 v221, 2, v219
	ds_bpermute_b32 v219, v221, v169
	s_waitcnt lgkmcnt(0)
	v_add_f32_e32 v169, v169, v219
	ds_bpermute_b32 v219, v221, v218
	s_waitcnt lgkmcnt(0)
	v_add_f32_e32 v218, v218, v219
	v_xor_b32_e32 v219, 32, v213
	v_cmp_lt_i32_e32 vcc, v219, v168
	s_nop 1
	v_cndmask_b32_e32 v168, v213, v219, vcc
	v_lshlrev_b32_e32 v222, 2, v168
	ds_bpermute_b32 v168, v222, v169
	s_waitcnt lgkmcnt(0)
	v_add_f32_e32 v168, v169, v168
	v_fmamk_f32 v168, v168, 0x3a000000, v165
	v_rsq_f32_e32 v219, v168
	ds_bpermute_b32 v169, v222, v218
	v_mul_f32_e32 v128, v128, v219
	v_mul_f32_e32 v130, v130, v219
	v_fma_f32 v128, v180, v128, v132
	v_mul_f32_e32 v129, v129, v219
	v_fma_f32 v168, v178, v130, v134
	v_mul_f32_e32 v130, v131, v219
	v_fma_f32 v129, v181, v129, v133
	v_fma_f32 v131, v179, v130, v135
	v_cvt_pk_bf16_f32 v130, v128, v129
	v_cvt_pk_bf16_f32 v131, v168, v131
	v_lshlrev_b64 v[128:129], 3, v[170:171]
	v_mul_f32_e32 v124, v124, v219
	s_waitcnt lgkmcnt(0)
	v_add_f32_e32 v218, v218, v169
	v_lshl_add_u64 v[168:169], s[16:17], 0, v[128:129]
	v_fma_f32 v124, v184, v124, v136
	v_mul_f32_e32 v125, v125, v219
	global_store_dwordx2 v[168:169], v[130:131], off
	v_fma_f32 v125, v185, v125, v137
	v_cvt_pk_bf16_f32 v124, v124, v125
	v_mul_f32_e32 v126, v126, v219
	s_nop 0
	s_nop 0
	v_fma_f32 v126, v182, v126, v138
	v_mul_f32_e32 v127, v127, v219
	v_fma_f32 v127, v183, v127, v139
	v_bfe_u32 v125, v126, 16, 1
	v_add3_u32 v125, v126, v125, s79
	v_bfe_u32 v126, v127, 16, 1
	v_lshrrev_b32_e32 v125, 16, v125
	v_add3_u32 v126, v127, v126, s79
	v_mul_f32_e32 v120, v120, v219
	v_and_or_b32 v125, v126, s80, v125
	v_fma_f32 v120, v188, v120, v140
	v_mul_f32_e32 v121, v121, v219
	global_store_dwordx2 v[168:169], v[124:125], off offset:512
	v_fma_f32 v121, v189, v121, v141
	v_cvt_pk_bf16_f32 v120, v120, v121
	v_mul_f32_e32 v122, v122, v219
	s_nop 0
	s_nop 0
	v_fma_f32 v122, v186, v122, v142
	v_mul_f32_e32 v123, v123, v219
	v_fma_f32 v123, v187, v123, v143
	v_bfe_u32 v121, v122, 16, 1
	v_add3_u32 v121, v122, v121, s79
	v_bfe_u32 v122, v123, 16, 1
	v_lshrrev_b32_e32 v121, 16, v121
	v_add3_u32 v122, v123, v122, s79
	v_mul_f32_e32 v116, v116, v219
	v_and_or_b32 v121, v122, s80, v121
	v_fma_f32 v116, v192, v116, v144
	v_mul_f32_e32 v117, v117, v219
	global_store_dwordx2 v[168:169], v[120:121], off offset:1024
	v_fma_f32 v117, v193, v117, v145
	v_cvt_pk_bf16_f32 v116, v116, v117
	v_mul_f32_e32 v118, v118, v219
	s_nop 0
	s_nop 0
	v_fma_f32 v118, v190, v118, v146
	v_mul_f32_e32 v119, v119, v219
	v_fma_f32 v119, v191, v119, v147
	v_bfe_u32 v117, v118, 16, 1
	v_add3_u32 v117, v118, v117, s79
	v_bfe_u32 v118, v119, 16, 1
	v_lshrrev_b32_e32 v117, 16, v117
	v_add3_u32 v118, v119, v118, s79
	v_mul_f32_e32 v112, v112, v219
	v_and_or_b32 v117, v118, s80, v117
	v_fma_f32 v112, v198, v112, v148
	v_mul_f32_e32 v113, v113, v219
	global_store_dwordx2 v[168:169], v[116:117], off offset:1536
	v_fma_f32 v113, v199, v113, v149
	v_cvt_pk_bf16_f32 v112, v112, v113
	v_mul_f32_e32 v114, v114, v219
	s_nop 0
	s_nop 0
	v_fma_f32 v114, v194, v114, v150
	v_mul_f32_e32 v115, v115, v219
	v_fma_f32 v115, v195, v115, v151
	v_bfe_u32 v113, v114, 16, 1
	v_add3_u32 v113, v114, v113, s79
	v_bfe_u32 v114, v115, 16, 1
	v_lshrrev_b32_e32 v113, 16, v113
	v_add3_u32 v114, v115, v114, s79
	v_mul_f32_e32 v108, v108, v219
	v_and_or_b32 v113, v114, s80, v113
	v_fma_f32 v108, v200, v108, v152
	v_mul_f32_e32 v109, v109, v219
	global_store_dwordx2 v[168:169], v[112:113], off offset:2048
	v_fma_f32 v109, v201, v109, v153
	v_cvt_pk_bf16_f32 v108, v108, v109
	v_mul_f32_e32 v110, v110, v219
	s_nop 0
	s_nop 0
	v_fma_f32 v110, v196, v110, v154
	v_mul_f32_e32 v111, v111, v219
	v_fma_f32 v111, v197, v111, v155
	v_bfe_u32 v109, v110, 16, 1
	v_add3_u32 v109, v110, v109, s79
	v_bfe_u32 v110, v111, 16, 1
	v_lshrrev_b32_e32 v109, 16, v109
	v_add3_u32 v110, v111, v110, s79
	v_mul_f32_e32 v104, v104, v219
	v_and_or_b32 v109, v110, s80, v109
	v_fma_f32 v104, v204, v104, v156
	v_mul_f32_e32 v105, v105, v219
	global_store_dwordx2 v[168:169], v[108:109], off offset:2560
	v_fma_f32 v105, v205, v105, v157
	v_cvt_pk_bf16_f32 v104, v104, v105
	v_mul_f32_e32 v106, v106, v219
	s_nop 0
	s_nop 0
	v_fma_f32 v106, v202, v106, v158
	v_mul_f32_e32 v107, v107, v219
	v_fma_f32 v107, v203, v107, v159
	v_bfe_u32 v105, v106, 16, 1
	v_add3_u32 v105, v106, v105, s79
	v_bfe_u32 v106, v107, 16, 1
	v_lshrrev_b32_e32 v105, 16, v105
	v_add3_u32 v106, v107, v106, s79
	v_mul_f32_e32 v100, v100, v219
	v_and_or_b32 v105, v106, s80, v105
	s_waitcnt vmcnt(6)
	v_fma_f32 v100, v208, v100, v160
	v_mul_f32_e32 v101, v101, v219
	global_store_dwordx2 v[168:169], v[104:105], off offset:3072
	v_fma_f32 v101, v209, v101, v161
	v_cvt_pk_bf16_f32 v100, v100, v101
	v_mul_f32_e32 v102, v102, v219
	s_nop 0
	s_nop 0
	v_fma_f32 v102, v206, v102, v162
	v_mul_f32_e32 v103, v103, v219
	v_fma_f32 v103, v207, v103, v163
	v_bfe_u32 v101, v102, 16, 1
	v_add3_u32 v101, v102, v101, s79
	v_bfe_u32 v102, v103, 16, 1
	v_lshrrev_b32_e32 v101, 16, v101
	v_add3_u32 v102, v103, v102, s79
	v_and_or_b32 v101, v102, s80, v101
	global_store_dwordx2 v[168:169], v[100:101], off offset:3584
	v_fmamk_f32 v100, v218, 0x3a000000, v165
	v_rsq_f32_e32 v100, v100
	s_nop 0
	v_mul_f32_e32 v96, v96, v100
	v_fma_f32 v96, v180, v96, v132
	v_mul_f32_e32 v97, v97, v100
	v_mul_f32_e32 v99, v99, v100
	v_fma_f32 v97, v181, v97, v133
	v_fmac_f32_e32 v135, v179, v99
	v_cvt_pk_bf16_f32 v96, v96, v97
	v_mul_f32_e32 v98, v98, v100
	v_fma_f32 v98, v178, v98, v134
	v_bfe_u32 v97, v98, 16, 1
	v_mul_f32_e32 v68, v68, v100
	v_add3_u32 v97, v98, v97, s79
	v_bfe_u32 v98, v135, 16, 1
	v_fma_f32 v68, v208, v68, v160
	v_mul_f32_e32 v69, v69, v100
	v_mul_f32_e32 v71, v71, v100
	v_lshrrev_b32_e32 v97, 16, v97
	v_add3_u32 v98, v135, v98, s79
	v_mul_f32_e32 v92, v92, v100
	v_mul_f32_e32 v88, v88, v100
	v_mul_f32_e32 v84, v84, v100
	v_mul_f32_e32 v80, v80, v100
	v_mul_f32_e32 v76, v76, v100
	v_mul_f32_e32 v72, v72, v100
	v_fma_f32 v69, v209, v69, v161
	v_fmac_f32_e32 v163, v207, v71
	v_cvt_pk_bf16_f32 v68, v68, v69
	v_and_or_b32 v97, v98, s80, v97
	v_lshl_add_u64 v[98:99], s[14:15], 0, v[128:129]
	v_fma_f32 v92, v184, v92, v136
	v_mul_f32_e32 v93, v93, v100
	v_mul_f32_e32 v95, v95, v100
	v_fma_f32 v88, v188, v88, v140
	v_mul_f32_e32 v89, v89, v100
	v_mul_f32_e32 v91, v91, v100
	v_fma_f32 v84, v192, v84, v144
	v_mul_f32_e32 v85, v85, v100
	v_mul_f32_e32 v87, v87, v100
	v_fma_f32 v80, v198, v80, v148
	v_mul_f32_e32 v81, v81, v100
	v_mul_f32_e32 v83, v83, v100
	v_fma_f32 v76, v200, v76, v152
	v_mul_f32_e32 v77, v77, v100
	v_mul_f32_e32 v79, v79, v100
	v_fma_f32 v72, v204, v72, v156
	v_mul_f32_e32 v73, v73, v100
	v_mul_f32_e32 v75, v75, v100
	v_mul_f32_e32 v70, v70, v100
	s_add_u32 s14, s20, s24
	v_fma_f32 v93, v185, v93, v137
	v_fmac_f32_e32 v139, v183, v95
	v_cvt_pk_bf16_f32 v92, v92, v93
	v_fma_f32 v89, v189, v89, v141
	v_fmac_f32_e32 v143, v187, v91
	v_cvt_pk_bf16_f32 v88, v88, v89
	v_fma_f32 v85, v193, v85, v145
	v_fmac_f32_e32 v147, v191, v87
	v_cvt_pk_bf16_f32 v84, v84, v85
	v_fma_f32 v81, v199, v81, v149
	v_fmac_f32_e32 v151, v195, v83
	v_cvt_pk_bf16_f32 v80, v80, v81
	v_fma_f32 v77, v201, v77, v153
	v_fmac_f32_e32 v155, v197, v79
	v_cvt_pk_bf16_f32 v76, v76, v77
	v_fma_f32 v73, v205, v73, v157
	v_fmac_f32_e32 v159, v203, v75
	v_cvt_pk_bf16_f32 v72, v72, v73
	v_fma_f32 v70, v206, v70, v162
	s_addc_u32 s5, s5, 0
	v_mul_f32_e32 v94, v94, v100
	v_mul_f32_e32 v90, v90, v100
	v_mul_f32_e32 v86, v86, v100
	v_mul_f32_e32 v82, v82, v100
	v_mul_f32_e32 v78, v78, v100
	v_mul_f32_e32 v74, v74, v100
	v_bfe_u32 v69, v70, 16, 1
	s_mul_i32 s5, s5, 0xc000
	s_mul_hi_u32 s15, s14, 0xc000
	v_fma_f32 v94, v182, v94, v138
	v_fma_f32 v90, v186, v90, v142
	v_fma_f32 v86, v190, v86, v146
	v_fma_f32 v82, v194, v82, v150
	v_fma_f32 v78, v196, v78, v154
	v_fma_f32 v74, v202, v74, v158
	v_add3_u32 v69, v70, v69, s79
	v_bfe_u32 v70, v163, 16, 1
	s_add_i32 s15, s15, s5
	s_mul_i32 s14, s14, 0xc000
	v_bfe_u32 v93, v94, 16, 1
	v_bfe_u32 v89, v90, 16, 1
	v_bfe_u32 v85, v86, 16, 1
	v_bfe_u32 v81, v82, 16, 1
	v_bfe_u32 v77, v78, 16, 1
	v_bfe_u32 v73, v74, 16, 1
	v_lshrrev_b32_e32 v69, 16, v69
	v_add3_u32 v70, v163, v70, s79
	s_add_u32 s14, s21, s14
	v_add3_u32 v93, v94, v93, s79
	v_bfe_u32 v94, v139, 16, 1
	v_add3_u32 v89, v90, v89, s79
	v_bfe_u32 v90, v143, 16, 1
	v_add3_u32 v85, v86, v85, s79
	v_bfe_u32 v86, v147, 16, 1
	v_add3_u32 v81, v82, v81, s79
	v_bfe_u32 v82, v151, 16, 1
	v_add3_u32 v77, v78, v77, s79
	v_bfe_u32 v78, v155, 16, 1
	v_add3_u32 v73, v74, v73, s79
	v_bfe_u32 v74, v159, 16, 1
	v_and_or_b32 v69, v70, s80, v69
	s_addc_u32 s15, s22, s15
	v_lshrrev_b32_e32 v93, 16, v93
	v_add3_u32 v94, v139, v94, s79
	v_lshrrev_b32_e32 v89, 16, v89
	v_add3_u32 v90, v143, v90, s79
	v_lshrrev_b32_e32 v85, 16, v85
	v_add3_u32 v86, v147, v86, s79
	v_lshrrev_b32_e32 v81, 16, v81
	v_add3_u32 v82, v151, v82, s79
	v_lshrrev_b32_e32 v77, 16, v77
	v_add3_u32 v78, v155, v78, s79
	v_lshrrev_b32_e32 v73, 16, v73
	v_add3_u32 v74, v159, v74, s79
	global_store_dwordx2 v[98:99], v[68:69], off offset:3584
	v_lshl_add_u64 v[68:69], s[14:15], 0, v[172:173]
	global_store_dwordx2 v[98:99], v[96:97], off
	v_and_or_b32 v93, v94, s80, v93
	v_and_or_b32 v89, v90, s80, v89
	v_and_or_b32 v85, v86, s80, v85
	v_and_or_b32 v81, v82, s80, v81
	v_and_or_b32 v77, v78, s80, v77
	v_and_or_b32 v73, v74, s80, v73
	v_add_co_u32_e32 v96, vcc, s19, v68
	global_store_dwordx2 v[98:99], v[92:93], off offset:512
	global_store_dwordx2 v[98:99], v[88:89], off offset:1024
	global_store_dwordx2 v[98:99], v[84:85], off offset:1536
	global_store_dwordx2 v[98:99], v[80:81], off offset:2048
	global_store_dwordx2 v[98:99], v[76:77], off offset:2560
	global_store_dwordx2 v[98:99], v[72:73], off offset:3072
	v_addc_co_u32_e32 v97, vcc, 0, v69, vcc
	global_load_dwordx4 v[76:79], v[96:97], off offset:-4096
	global_load_dwordx4 v[72:75], v[176:177], off
	v_add_co_u32_e32 v98, vcc, s18, v68
	v_lshl_add_u64 v[88:89], v[68:69], 0, s[26:27]
	s_nop 0
	v_addc_co_u32_e32 v99, vcc, 0, v69, vcc
	v_lshl_add_u64 v[92:93], v[68:69], 0, s[38:39]
	global_load_dwordx4 v[68:71], v[98:99], off offset:-4096
	s_lshl_b64 s[12:13], s[12:13], 12
	s_add_u32 s12, s8, s12
	s_addc_u32 s13, s9, s13
	s_lshl_b64 s[0:1], s[0:1], 12
	s_add_u32 s0, s8, s0
	s_addc_u32 s1, s9, s1
	s_waitcnt vmcnt(2)
	v_pk_add_f32 v[78:79], v[78:79], 1.0 op_sel_hi:[1,0]
	v_pk_add_f32 v[76:77], v[76:77], 1.0 op_sel_hi:[1,0]
	s_waitcnt vmcnt(1)
	v_pk_mul_f32 v[100:101], v[74:75], v[78:79]
	v_pk_mul_f32 v[102:103], v[72:73], v[76:77]
	global_load_dwordx4 v[76:79], v[176:177], off offset:1024
	global_load_dwordx4 v[80:83], v[88:89], off offset:1024
	global_load_dwordx4 v[72:75], v[92:93], off offset:1024
	s_waitcnt vmcnt(1)
	v_pk_add_f32 v[82:83], v[82:83], 1.0 op_sel_hi:[1,0]
	v_pk_add_f32 v[80:81], v[80:81], 1.0 op_sel_hi:[1,0]
	v_pk_mul_f32 v[104:105], v[78:79], v[82:83]
	v_pk_mul_f32 v[106:107], v[76:77], v[80:81]
	global_load_dwordx4 v[80:83], v[176:177], off offset:2048
	global_load_dwordx4 v[84:87], v[88:89], off offset:2048
	global_load_dwordx4 v[76:79], v[92:93], off offset:2048
	s_waitcnt vmcnt(1)
	v_pk_add_f32 v[86:87], v[86:87], 1.0 op_sel_hi:[1,0]
	v_pk_add_f32 v[84:85], v[84:85], 1.0 op_sel_hi:[1,0]
	v_pk_mul_f32 v[108:109], v[82:83], v[86:87]
	v_pk_mul_f32 v[110:111], v[80:81], v[84:85]
	global_load_dwordx4 v[84:87], v[176:177], off offset:3072
	s_nop 0
	global_load_dwordx4 v[88:91], v[88:89], off offset:3072
	s_nop 0
	global_load_dwordx4 v[80:83], v[92:93], off offset:3072
	s_waitcnt vmcnt(1)
	v_pk_add_f32 v[90:91], v[90:91], 1.0 op_sel_hi:[1,0]
	v_pk_add_f32 v[88:89], v[88:89], 1.0 op_sel_hi:[1,0]
	v_pk_mul_f32 v[112:113], v[86:87], v[90:91]
	v_pk_mul_f32 v[114:115], v[84:85], v[88:89]
	global_load_dwordx4 v[88:91], v[174:175], off
	global_load_dwordx4 v[92:95], v[96:97], off
	global_load_dwordx4 v[84:87], v[98:99], off
	s_waitcnt vmcnt(1)
	v_pk_add_f32 v[94:95], v[94:95], 1.0 op_sel_hi:[1,0]
	v_pk_add_f32 v[92:93], v[92:93], 1.0 op_sel_hi:[1,0]
	v_pk_mul_f32 v[116:117], v[90:91], v[94:95]
	v_pk_mul_f32 v[120:121], v[88:89], v[92:93]
	global_load_dwordx4 v[92:95], v[174:175], off offset:1024
	global_load_dwordx4 v[122:125], v[96:97], off offset:1024
	global_load_dwordx4 v[88:91], v[98:99], off offset:1024
	s_waitcnt vmcnt(1)
	v_pk_add_f32 v[118:119], v[124:125], 1.0 op_sel_hi:[1,0]
	v_pk_add_f32 v[122:123], v[122:123], 1.0 op_sel_hi:[1,0]
	v_pk_mul_f32 v[118:119], v[94:95], v[118:119]
	v_pk_mul_f32 v[122:123], v[92:93], v[122:123]
	global_load_dwordx4 v[130:133], v[174:175], off offset:2048
	global_load_dwordx4 v[124:127], v[96:97], off offset:2048
	global_load_dwordx4 v[92:95], v[98:99], off offset:2048
	s_waitcnt vmcnt(1)
	v_pk_add_f32 v[126:127], v[126:127], 1.0 op_sel_hi:[1,0]
	v_pk_add_f32 v[134:135], v[124:125], 1.0 op_sel_hi:[1,0]
	v_pk_mul_f32 v[124:125], v[132:133], v[126:127]
	v_pk_mul_f32 v[126:127], v[130:131], v[134:135]
	global_load_dwordx4 v[132:135], v[174:175], off offset:3072
	global_load_dwordx4 v[136:139], v[96:97], off offset:3072
	s_nop 0
	global_load_dwordx4 v[96:99], v[98:99], off offset:3072
	s_waitcnt vmcnt(1)
	v_pk_add_f32 v[130:131], v[138:139], 1.0 op_sel_hi:[1,0]
	s_nop 0
	v_pk_mul_f32 v[130:131], v[134:135], v[130:131]
	v_mul_f32_e32 v134, v65, v65
	v_mul_f32_e32 v135, v67, v67
	v_pk_add_f32 v[136:137], v[136:137], 1.0 op_sel_hi:[1,0]
	v_fmac_f32_e32 v134, v64, v64
	v_fmac_f32_e32 v135, v66, v66
	v_pk_mul_f32 v[132:133], v[132:133], v[136:137]
	v_add_f32_e32 v134, v134, v135
	v_mul_f32_e32 v135, v61, v61
	v_mul_f32_e32 v136, v63, v63
	v_fmac_f32_e32 v135, v60, v60
	v_fmac_f32_e32 v136, v62, v62
	v_add_f32_e32 v135, v135, v136
	v_add_f32_e32 v134, v134, v135
	v_mul_f32_e32 v135, v57, v57
	v_mul_f32_e32 v136, v59, v59
	v_fmac_f32_e32 v135, v56, v56
	v_fmac_f32_e32 v136, v58, v58
	v_add_f32_e32 v135, v135, v136
	v_add_f32_e32 v134, v134, v135
	v_mul_f32_e32 v135, v53, v53
	v_mul_f32_e32 v136, v55, v55
	v_fmac_f32_e32 v135, v52, v52
	v_fmac_f32_e32 v136, v54, v54
	v_add_f32_e32 v135, v135, v136
	v_add_f32_e32 v134, v134, v135
	v_mul_f32_e32 v135, v49, v49
	v_mul_f32_e32 v136, v51, v51
	v_fmac_f32_e32 v135, v48, v48
	v_fmac_f32_e32 v136, v50, v50
	v_add_f32_e32 v135, v135, v136
	v_add_f32_e32 v134, v134, v135
	v_mul_f32_e32 v135, v45, v45
	v_mul_f32_e32 v136, v47, v47
	v_fmac_f32_e32 v135, v44, v44
	v_fmac_f32_e32 v136, v46, v46
	v_add_f32_e32 v135, v135, v136
	v_add_f32_e32 v134, v134, v135
	v_mul_f32_e32 v135, v41, v41
	v_mul_f32_e32 v136, v43, v43
	v_fmac_f32_e32 v135, v40, v40
	v_fmac_f32_e32 v136, v42, v42
	v_add_f32_e32 v135, v135, v136
	v_add_f32_e32 v134, v134, v135
	v_mul_f32_e32 v135, v37, v37
	v_mul_f32_e32 v136, v39, v39
	v_fmac_f32_e32 v135, v36, v36
	v_fmac_f32_e32 v136, v38, v38
	v_add_f32_e32 v135, v135, v136
	v_add_f32_e32 v134, v134, v135
	v_mul_f32_e32 v135, v33, v33
	v_mul_f32_e32 v136, v35, v35
	v_fmac_f32_e32 v135, v32, v32
	v_fmac_f32_e32 v136, v34, v34
	v_add_f32_e32 v135, v135, v136
	v_mul_f32_e32 v136, v29, v29
	v_mul_f32_e32 v137, v31, v31
	v_fmac_f32_e32 v136, v28, v28
	v_fmac_f32_e32 v137, v30, v30
	v_add_f32_e32 v136, v136, v137
	v_add_f32_e32 v135, v135, v136
	v_mul_f32_e32 v136, v25, v25
	v_mul_f32_e32 v137, v27, v27
	v_fmac_f32_e32 v136, v24, v24
	v_fmac_f32_e32 v137, v26, v26
	v_add_f32_e32 v136, v136, v137
	v_add_f32_e32 v135, v135, v136
	v_mul_f32_e32 v136, v21, v21
	v_mul_f32_e32 v137, v23, v23
	v_fmac_f32_e32 v136, v20, v20
	v_fmac_f32_e32 v137, v22, v22
	v_add_f32_e32 v136, v136, v137
	v_add_f32_e32 v135, v135, v136
	v_mul_f32_e32 v136, v15, v15
	v_mul_f32_e32 v137, v17, v17
	v_fmac_f32_e32 v136, v14, v14
	v_fmac_f32_e32 v137, v16, v16
	v_add_f32_e32 v136, v136, v137
	v_add_f32_e32 v135, v135, v136
	v_mul_f32_e32 v136, v11, v11
	v_mul_f32_e32 v137, v13, v13
	v_fmac_f32_e32 v136, v10, v10
	v_fmac_f32_e32 v137, v12, v12
	v_add_f32_e32 v136, v136, v137
	v_add_f32_e32 v135, v135, v136
	v_mul_f32_e32 v136, v7, v7
	v_mul_f32_e32 v137, v9, v9
	v_fmac_f32_e32 v136, v6, v6
	v_fmac_f32_e32 v137, v8, v8
	v_add_f32_e32 v136, v136, v137
	v_add_f32_e32 v135, v135, v136
	v_mul_f32_e32 v136, v3, v3
	v_mul_f32_e32 v137, v5, v5
	v_fmac_f32_e32 v136, v2, v2
	v_fmac_f32_e32 v137, v4, v4
	v_add_f32_e32 v136, v136, v137
	v_add_f32_e32 v135, v135, v136
	ds_bpermute_b32 v136, v1, v134
	ds_bpermute_b32 v1, v1, v135
	s_waitcnt lgkmcnt(1)
	v_add_f32_e32 v134, v134, v136
	s_waitcnt lgkmcnt(0)
	v_add_f32_e32 v1, v135, v1
	ds_bpermute_b32 v135, v18, v134
	ds_bpermute_b32 v18, v18, v1
	s_waitcnt lgkmcnt(1)
	v_add_f32_e32 v134, v134, v135
	s_waitcnt lgkmcnt(0)
	v_add_f32_e32 v1, v1, v18
	ds_bpermute_b32 v18, v167, v134
	s_waitcnt lgkmcnt(0)
	v_add_f32_e32 v18, v134, v18
	ds_bpermute_b32 v134, v167, v1
	s_waitcnt lgkmcnt(0)
	v_add_f32_e32 v1, v1, v134
	ds_bpermute_b32 v134, v220, v18
	s_waitcnt lgkmcnt(0)
	v_add_f32_e32 v18, v18, v134
	ds_bpermute_b32 v134, v220, v1
	s_waitcnt lgkmcnt(0)
	v_add_f32_e32 v1, v1, v134
	ds_bpermute_b32 v134, v221, v18
	s_waitcnt lgkmcnt(0)
	v_add_f32_e32 v18, v18, v134
	ds_bpermute_b32 v134, v221, v1
	s_waitcnt lgkmcnt(0)
	v_add_f32_e32 v1, v1, v134
	ds_bpermute_b32 v134, v222, v18
	s_waitcnt lgkmcnt(0)
	v_add_f32_e32 v18, v18, v134
	v_fmamk_f32 v18, v18, 0x3a000000, v165
	v_rsq_f32_e32 v18, v18
	ds_bpermute_b32 v134, v222, v1
	v_mul_f32_e32 v64, v64, v18
	v_fma_f32 v64, v102, v64, v68
	v_mul_f32_e32 v65, v65, v18
	s_waitcnt lgkmcnt(0)
	v_add_f32_e32 v1, v1, v134
	v_fma_f32 v65, v103, v65, v69
	v_cvt_pk_bf16_f32 v64, v64, v65
	v_mul_f32_e32 v66, v66, v18
	v_fma_f32 v66, v100, v66, v70
	v_mul_f32_e32 v67, v67, v18
	v_fma_f32 v67, v101, v67, v71
	v_bfe_u32 v65, v66, 16, 1
	v_add3_u32 v65, v66, v65, s79
	v_bfe_u32 v66, v67, 16, 1
	v_lshrrev_b32_e32 v65, 16, v65
	v_add3_u32 v66, v67, v66, s79
	v_mul_f32_e32 v60, v60, v18
	v_and_or_b32 v65, v66, s80, v65
	v_lshl_add_u64 v[66:67], s[12:13], 0, v[128:129]
	v_fma_f32 v60, v106, v60, v72
	v_mul_f32_e32 v61, v61, v18
	global_store_dwordx2 v[66:67], v[64:65], off
	v_fma_f32 v61, v107, v61, v73
	v_cvt_pk_bf16_f32 v60, v60, v61
	v_mul_f32_e32 v62, v62, v18
	s_nop 0
	s_nop 0
	v_mul_f32_e32 v36, v36, v18
	v_fma_f32 v62, v104, v62, v74
	v_mul_f32_e32 v63, v63, v18
	s_waitcnt vmcnt(1)
	v_fma_f32 v36, v132, v36, v96
	v_mul_f32_e32 v37, v37, v18
	v_fma_f32 v63, v105, v63, v75
	v_bfe_u32 v61, v62, 16, 1
	v_mul_f32_e32 v56, v56, v18
	v_mul_f32_e32 v57, v57, v18
	v_mul_f32_e32 v58, v58, v18
	v_mul_f32_e32 v59, v59, v18
	v_mul_f32_e32 v52, v52, v18
	v_mul_f32_e32 v53, v53, v18
	v_mul_f32_e32 v54, v54, v18
	v_mul_f32_e32 v55, v55, v18
	v_mul_f32_e32 v48, v48, v18
	v_mul_f32_e32 v49, v49, v18
	v_mul_f32_e32 v50, v50, v18
	v_mul_f32_e32 v51, v51, v18
	v_mul_f32_e32 v44, v44, v18
	v_mul_f32_e32 v45, v45, v18
	v_mul_f32_e32 v46, v46, v18
	v_mul_f32_e32 v47, v47, v18
	v_mul_f32_e32 v40, v40, v18
	v_mul_f32_e32 v41, v41, v18
	v_mul_f32_e32 v42, v42, v18
	v_mul_f32_e32 v43, v43, v18
	v_fma_f32 v37, v133, v37, v97
	v_mul_f32_e32 v38, v38, v18
	v_mul_f32_e32 v18, v39, v18
	v_cvt_pk_bf16_f32 v36, v36, v37
	v_add3_u32 v61, v62, v61, s79
	v_bfe_u32 v62, v63, 16, 1
	v_fmamk_f32 v1, v1, 0x3a000000, v165
	v_lshrrev_b32_e32 v61, 16, v61
	v_add3_u32 v62, v63, v62, s79
	v_fma_f32 v38, v130, v38, v98
	v_rsq_f32_e32 v1, v1
	v_and_or_b32 v61, v62, s80, v61
	v_fma_f32 v56, v110, v56, v76
	v_fma_f32 v18, v131, v18, v99
	s_nop 0
	v_bfe_u32 v37, v38, 16, 1
	global_store_dwordx2 v[66:67], v[60:61], off offset:512
	v_fma_f32 v57, v111, v57, v77
	v_cvt_pk_bf16_f32 v56, v56, v57
	v_add3_u32 v37, v38, v37, s79
	v_bfe_u32 v38, v18, 16, 1
	s_nop 0
	s_nop 0
	v_lshrrev_b32_e32 v37, 16, v37
	v_add3_u32 v18, v18, v38, s79
	v_fma_f32 v58, v108, v58, v78
	v_and_or_b32 v37, v18, s80, v37
	v_mul_f32_e32 v18, v32, v1
	v_fma_f32 v59, v109, v59, v79
	v_bfe_u32 v57, v58, 16, 1
	v_fma_f32 v18, v102, v18, v68
	v_mul_f32_e32 v32, v33, v1
	v_mul_f32_e32 v33, v34, v1
	v_mul_f32_e32 v34, v35, v1
	v_add3_u32 v57, v58, v57, s79
	v_bfe_u32 v58, v59, 16, 1
	v_fma_f32 v32, v103, v32, v69
	v_fmac_f32_e32 v71, v101, v34
	v_cvt_pk_bf16_f32 v32, v18, v32
	v_lshrrev_b32_e32 v57, 16, v57
	v_add3_u32 v58, v59, v58, s79
	v_and_or_b32 v57, v58, s80, v57
	v_fma_f32 v52, v114, v52, v80
	v_fma_f32 v33, v100, v33, v70
	global_store_dwordx2 v[66:67], v[56:57], off offset:1024
	v_fma_f32 v53, v115, v53, v81
	v_cvt_pk_bf16_f32 v52, v52, v53
	s_nop 0
	v_bfe_u32 v18, v33, 16, 1
	s_nop 0
	s_nop 0
	v_add3_u32 v18, v33, v18, s79
	v_bfe_u32 v33, v71, 16, 1
	v_fma_f32 v54, v112, v54, v82
	v_lshrrev_b32_e32 v18, 16, v18
	v_add3_u32 v33, v71, v33, s79
	v_fma_f32 v55, v113, v55, v83
	v_bfe_u32 v53, v54, 16, 1
	v_and_or_b32 v33, v33, s80, v18
	v_mul_f32_e32 v18, v28, v1
	v_add3_u32 v53, v54, v53, s79
	v_bfe_u32 v54, v55, 16, 1
	v_fma_f32 v18, v106, v18, v72
	v_mul_f32_e32 v28, v29, v1
	v_mul_f32_e32 v29, v30, v1
	v_mul_f32_e32 v30, v31, v1
	v_lshrrev_b32_e32 v53, 16, v53
	v_add3_u32 v54, v55, v54, s79
	v_fma_f32 v28, v107, v28, v73
	v_fmac_f32_e32 v75, v105, v30
	v_cvt_pk_bf16_f32 v28, v18, v28
	v_and_or_b32 v53, v54, s80, v53
	v_fma_f32 v48, v120, v48, v84
	global_store_dwordx2 v[66:67], v[52:53], off offset:1536
	v_fma_f32 v49, v121, v49, v85
	v_cvt_pk_bf16_f32 v48, v48, v49
	v_fma_f32 v29, v104, v29, v74
	s_nop 0
	s_nop 0
	s_nop 0
	v_bfe_u32 v18, v29, 16, 1
	v_fma_f32 v50, v116, v50, v86
	v_add3_u32 v18, v29, v18, s79
	v_bfe_u32 v29, v75, 16, 1
	v_fma_f32 v51, v117, v51, v87
	v_bfe_u32 v49, v50, 16, 1
	v_lshrrev_b32_e32 v18, 16, v18
	v_add3_u32 v29, v75, v29, s79
	v_add3_u32 v49, v50, v49, s79
	v_bfe_u32 v50, v51, 16, 1
	v_and_or_b32 v29, v29, s80, v18
	v_mul_f32_e32 v18, v24, v1
	v_lshrrev_b32_e32 v49, 16, v49
	v_add3_u32 v50, v51, v50, s79
	v_fma_f32 v18, v110, v18, v76
	v_mul_f32_e32 v24, v25, v1
	v_mul_f32_e32 v25, v26, v1
	v_mul_f32_e32 v26, v27, v1
	v_and_or_b32 v49, v50, s80, v49
	v_fma_f32 v44, v122, v44, v88
	v_fma_f32 v24, v111, v24, v77
	v_fmac_f32_e32 v79, v109, v26
	v_cvt_pk_bf16_f32 v24, v18, v24
	global_store_dwordx2 v[66:67], v[48:49], off offset:2048
	v_fma_f32 v45, v123, v45, v89
	v_cvt_pk_bf16_f32 v44, v44, v45
	s_nop 0
	s_nop 0
	s_nop 0
	s_nop 0
	v_fma_f32 v25, v108, v25, v78
	v_fma_f32 v46, v118, v46, v90
	v_bfe_u32 v18, v25, 16, 1
	v_fma_f32 v47, v119, v47, v91
	v_bfe_u32 v45, v46, 16, 1
	v_add3_u32 v18, v25, v18, s79
	v_bfe_u32 v25, v79, 16, 1
	v_add3_u32 v45, v46, v45, s79
	v_bfe_u32 v46, v47, 16, 1
	v_lshrrev_b32_e32 v18, 16, v18
	v_add3_u32 v25, v79, v25, s79
	v_lshrrev_b32_e32 v45, 16, v45
	v_add3_u32 v46, v47, v46, s79
	v_and_or_b32 v25, v25, s80, v18
	v_mul_f32_e32 v18, v20, v1
	v_mul_f32_e32 v14, v14, v1
	v_mul_f32_e32 v10, v10, v1
	v_mul_f32_e32 v6, v6, v1
	v_mul_f32_e32 v2, v2, v1
	v_and_or_b32 v45, v46, s80, v45
	v_fma_f32 v40, v126, v40, v92
	v_fma_f32 v18, v114, v18, v80
	v_mul_f32_e32 v20, v21, v1
	v_mul_f32_e32 v21, v22, v1
	v_mul_f32_e32 v22, v23, v1
	v_fma_f32 v14, v120, v14, v84
	v_mul_f32_e32 v15, v15, v1
	v_mul_f32_e32 v16, v16, v1
	v_mul_f32_e32 v17, v17, v1
	v_fma_f32 v10, v122, v10, v88
	v_mul_f32_e32 v11, v11, v1
	v_mul_f32_e32 v12, v12, v1
	v_mul_f32_e32 v13, v13, v1
	v_fma_f32 v6, v126, v6, v92
	v_mul_f32_e32 v7, v7, v1
	v_mul_f32_e32 v8, v8, v1
	v_mul_f32_e32 v9, v9, v1
	v_fma_f32 v2, v132, v2, v96
	v_mul_f32_e32 v3, v3, v1
	v_mul_f32_e32 v4, v4, v1
	v_mul_f32_e32 v1, v5, v1
	global_store_dwordx2 v[66:67], v[44:45], off offset:2560
	v_fma_f32 v41, v127, v41, v93
	v_fma_f32 v43, v125, v43, v95
	v_cvt_pk_bf16_f32 v40, v40, v41
	v_fma_f32 v20, v115, v20, v81
	v_fmac_f32_e32 v83, v113, v22
	v_cvt_pk_bf16_f32 v20, v18, v20
	v_fma_f32 v15, v121, v15, v85
	v_fmac_f32_e32 v87, v117, v17
	v_cvt_pk_bf16_f32 v14, v14, v15
	v_fma_f32 v11, v123, v11, v89
	v_fmac_f32_e32 v91, v119, v13
	v_cvt_pk_bf16_f32 v10, v10, v11
	v_fma_f32 v7, v127, v7, v93
	v_fmac_f32_e32 v95, v125, v9
	v_cvt_pk_bf16_f32 v6, v6, v7
	v_fma_f32 v3, v133, v3, v97
	v_fmac_f32_e32 v99, v131, v1
	v_bfe_u32 v1, v2, 16, 1
	v_add3_u32 v1, v2, v1, s79
	v_bfe_u32 v2, v3, 16, 1
	v_fma_f32 v42, v124, v42, v94
	v_fma_f32 v21, v112, v21, v82
	v_fma_f32 v16, v116, v16, v86
	v_fma_f32 v12, v118, v12, v90
	v_fma_f32 v8, v124, v8, v94
	v_fma_f32 v4, v130, v4, v98
	v_lshrrev_b32_e32 v1, 16, v1
	v_add3_u32 v2, v3, v2, s79
	v_bfe_u32 v41, v42, 16, 1
	v_bfe_u32 v18, v21, 16, 1
	v_bfe_u32 v15, v16, 16, 1
	v_bfe_u32 v11, v12, 16, 1
	v_bfe_u32 v7, v8, 16, 1
	v_and_or_b32 v2, v2, s80, v1
	v_cvt_pk_bf16_f32 v3, v4, v99
	v_add3_u32 v41, v42, v41, s79
	v_bfe_u32 v42, v43, 16, 1
	v_add3_u32 v18, v21, v18, s79
	v_bfe_u32 v21, v83, 16, 1
	v_add3_u32 v15, v16, v15, s79
	v_bfe_u32 v16, v87, 16, 1
	v_add3_u32 v11, v12, v11, s79
	v_bfe_u32 v12, v91, 16, 1
	v_add3_u32 v7, v8, v7, s79
	v_bfe_u32 v8, v95, 16, 1
	v_lshrrev_b32_e32 v41, 16, v41
	v_add3_u32 v42, v43, v42, s79
	v_lshl_add_u64 v[34:35], s[0:1], 0, v[128:129]
	v_lshrrev_b32_e32 v18, 16, v18
	v_add3_u32 v21, v83, v21, s79
	v_lshrrev_b32_e32 v15, 16, v15
	v_add3_u32 v16, v87, v16, s79
	v_lshrrev_b32_e32 v11, 16, v11
	v_add3_u32 v12, v91, v12, s79
	v_lshrrev_b32_e32 v7, 16, v7
	v_add3_u32 v8, v95, v8, s79
	s_nop 0
	s_nop 0
	v_readlane_b32 s0, v251, 8
	v_and_or_b32 v41, v42, s80, v41
	v_and_or_b32 v21, v21, s80, v18
	v_and_or_b32 v15, v16, s80, v15
	v_and_or_b32 v11, v12, s80, v11
	v_and_or_b32 v7, v8, s80, v7
	s_nop 0
	s_add_i32 s4, s4, s0
	global_store_dwordx2 v[66:67], v[40:41], off offset:3072
	global_store_dwordx2 v[66:67], v[36:37], off offset:3584
	global_store_dwordx2 v[34:35], v[32:33], off
	global_store_dwordx2 v[34:35], v[28:29], off offset:512
	global_store_dwordx2 v[34:35], v[24:25], off offset:1024
	global_store_dwordx2 v[34:35], v[20:21], off offset:1536
	global_store_dwordx2 v[34:35], v[14:15], off offset:2048
	global_store_dwordx2 v[34:35], v[10:11], off offset:2560
	global_store_dwordx2 v[34:35], v[6:7], off offset:3072
	global_store_dwordx2 v[34:35], v[2:3], off offset:3584

.LBB0_1692:
	s_ashr_i32 s1, s8, 31
	s_add_u32 s6, s8, s24
	s_addc_u32 s1, s1, 0
	s_mul_i32 s1, s1, 0xc000
	s_mul_hi_u32 s7, s6, 0xc000
	s_add_i32 s7, s7, s1
	s_mul_i32 s6, s6, 0xc000
	s_add_u32 s6, s12, s6
	s_waitcnt vmcnt(0)
	v_add_co_u32_e32 v2, vcc, 0x1000, v72
	s_addc_u32 s7, s13, s7
	s_nop 0
	v_addc_co_u32_e32 v3, vcc, 0, v73, vcc
	v_lshl_add_u64 v[66:67], s[6:7], 0, v[100:101]
	v_add_co_u32_e32 v64, vcc, s78, v66
	global_load_dwordx4 v[32:35], v[72:73], off
	global_load_dwordx4 v[28:31], v[72:73], off offset:1024
	global_load_dwordx4 v[24:27], v[72:73], off offset:2048
	global_load_dwordx4 v[20:23], v[72:73], off offset:3072
	v_addc_co_u32_e32 v65, vcc, 0, v67, vcc
	global_load_dwordx4 v[14:17], v[2:3], off
	global_load_dwordx4 v[10:13], v[2:3], off offset:1024
	global_load_dwordx4 v[6:9], v[2:3], off offset:2048
	s_nop 0
	global_load_dwordx4 v[2:5], v[2:3], off offset:3072
	s_mov_b64 s[6:7], 0x2000
	global_load_dwordx4 v[40:43], v[102:103], off
	global_load_dwordx4 v[44:47], v[64:65], off offset:-4096
	global_load_dwordx4 v[36:39], v[66:67], off
	v_lshl_add_u64 v[56:57], v[66:67], 0, s[6:7]
	s_lshl_b64 s[6:7], s[4:5], 12
	s_waitcnt vmcnt(10)
	v_mul_f32_e32 v1, v33, v33
	v_mul_f32_e32 v18, v35, v35
	v_fmac_f32_e32 v1, v32, v32
	v_fmac_f32_e32 v18, v34, v34
	v_add_f32_e32 v1, v1, v18
	s_waitcnt vmcnt(9)
	v_mul_f32_e32 v18, v29, v29
	v_fmac_f32_e32 v18, v28, v28
	s_waitcnt vmcnt(1)
	v_pk_add_f32 v[46:47], v[46:47], 1.0 op_sel_hi:[1,0]
	v_pk_add_f32 v[44:45], v[44:45], 1.0 op_sel_hi:[1,0]
	v_pk_mul_f32 v[68:69], v[42:43], v[46:47]
	v_pk_mul_f32 v[70:71], v[40:41], v[44:45]
	global_load_dwordx4 v[44:47], v[102:103], off offset:1024
	global_load_dwordx4 v[48:51], v[56:57], off offset:1024
	global_load_dwordx4 v[40:43], v[66:67], off offset:1024
	s_waitcnt vmcnt(1)
	v_pk_add_f32 v[50:51], v[50:51], 1.0 op_sel_hi:[1,0]
	v_pk_add_f32 v[48:49], v[48:49], 1.0 op_sel_hi:[1,0]
	v_pk_mul_f32 v[74:75], v[46:47], v[50:51]
	v_pk_mul_f32 v[76:77], v[44:45], v[48:49]
	global_load_dwordx4 v[48:51], v[102:103], off offset:2048
	global_load_dwordx4 v[52:55], v[56:57], off offset:2048
	global_load_dwordx4 v[44:47], v[66:67], off offset:2048
	s_waitcnt vmcnt(1)
	v_pk_add_f32 v[54:55], v[54:55], 1.0 op_sel_hi:[1,0]
	v_pk_add_f32 v[52:53], v[52:53], 1.0 op_sel_hi:[1,0]
	v_pk_mul_f32 v[78:79], v[50:51], v[54:55]
	v_pk_mul_f32 v[82:83], v[48:49], v[52:53]
	global_load_dwordx4 v[52:55], v[102:103], off offset:3072
	s_nop 0
	global_load_dwordx4 v[56:59], v[56:57], off offset:3072
	s_nop 0
	global_load_dwordx4 v[48:51], v[66:67], off offset:3072
	v_add_co_u32_e32 v66, vcc, s3, v66
	s_waitcnt vmcnt(1)
	v_pk_add_f32 v[58:59], v[58:59], 1.0 op_sel_hi:[1,0]
	v_pk_add_f32 v[56:57], v[56:57], 1.0 op_sel_hi:[1,0]
	v_pk_mul_f32 v[80:81], v[54:55], v[58:59]
	v_pk_mul_f32 v[84:85], v[52:53], v[56:57]
	global_load_dwordx4 v[56:59], v[104:105], off
	global_load_dwordx4 v[60:63], v[64:65], off
	v_addc_co_u32_e32 v67, vcc, 0, v67, vcc
	global_load_dwordx4 v[52:55], v[66:67], off
	s_waitcnt vmcnt(1)
	v_pk_add_f32 v[62:63], v[62:63], 1.0 op_sel_hi:[1,0]
	v_pk_add_f32 v[60:61], v[60:61], 1.0 op_sel_hi:[1,0]
	v_pk_mul_f32 v[86:87], v[58:59], v[62:63]
	v_pk_mul_f32 v[88:89], v[56:57], v[60:61]
	global_load_dwordx4 v[60:63], v[106:107], off
	global_load_dwordx4 v[90:93], v[64:65], off offset:1024
	global_load_dwordx4 v[56:59], v[66:67], off offset:1024
	s_waitcnt vmcnt(1)
	v_pk_add_f32 v[92:93], v[92:93], 1.0 op_sel_hi:[1,0]
	v_pk_add_f32 v[94:95], v[90:91], 1.0 op_sel_hi:[1,0]
	v_pk_mul_f32 v[90:91], v[62:63], v[92:93]
	v_pk_mul_f32 v[92:93], v[60:61], v[94:95]
	global_load_dwordx4 v[96:99], v[108:109], off
	global_load_dwordx4 v[116:119], v[64:65], off offset:2048
	global_load_dwordx4 v[60:63], v[66:67], off offset:2048
	s_waitcnt vmcnt(1)
	v_pk_add_f32 v[116:117], v[116:117], 1.0 op_sel_hi:[1,0]
	v_pk_add_f32 v[94:95], v[118:119], 1.0 op_sel_hi:[1,0]
	v_pk_mul_f32 v[96:97], v[96:97], v[116:117]
	global_load_dwordx4 v[116:119], v[110:111], off
	global_load_dwordx4 v[120:123], v[64:65], off offset:3072
	s_nop 0
	global_load_dwordx4 v[64:67], v[66:67], off offset:3072
	v_pk_mul_f32 v[94:95], v[98:99], v[94:95]
	s_waitcnt vmcnt(1)
	v_pk_add_f32 v[98:99], v[122:123], 1.0 op_sel_hi:[1,0]
	s_nop 0
	v_pk_mul_f32 v[98:99], v[118:119], v[98:99]
	v_mul_f32_e32 v118, v31, v31
	v_fmac_f32_e32 v118, v30, v30
	v_add_f32_e32 v18, v18, v118
	v_add_f32_e32 v1, v1, v18
	v_mul_f32_e32 v18, v25, v25
	v_mul_f32_e32 v118, v27, v27
	v_fmac_f32_e32 v18, v24, v24
	v_fmac_f32_e32 v118, v26, v26
	v_add_f32_e32 v18, v18, v118
	v_add_f32_e32 v1, v1, v18
	v_mul_f32_e32 v18, v21, v21
	v_mul_f32_e32 v118, v23, v23
	v_fmac_f32_e32 v18, v20, v20
	v_fmac_f32_e32 v118, v22, v22
	v_add_f32_e32 v18, v18, v118
	v_add_f32_e32 v1, v1, v18
	v_mul_f32_e32 v18, v15, v15
	v_mul_f32_e32 v118, v17, v17
	v_fmac_f32_e32 v18, v14, v14
	v_fmac_f32_e32 v118, v16, v16
	v_add_f32_e32 v18, v18, v118
	v_add_f32_e32 v1, v1, v18
	v_mul_f32_e32 v18, v11, v11
	v_mul_f32_e32 v118, v13, v13
	v_fmac_f32_e32 v18, v10, v10
	v_fmac_f32_e32 v118, v12, v12
	v_add_f32_e32 v18, v18, v118
	v_add_f32_e32 v1, v1, v18
	v_mul_f32_e32 v18, v7, v7
	v_mul_f32_e32 v118, v9, v9
	v_fmac_f32_e32 v18, v6, v6
	v_fmac_f32_e32 v118, v8, v8
	v_add_f32_e32 v18, v18, v118
	v_add_f32_e32 v1, v1, v18
	v_mul_f32_e32 v18, v3, v3
	v_mul_f32_e32 v118, v5, v5
	v_fmac_f32_e32 v18, v2, v2
	v_fmac_f32_e32 v118, v4, v4
	v_add_f32_e32 v18, v18, v118
	v_add_f32_e32 v1, v1, v18
	v_and_b32_e32 v18, 64, v213
	v_add_u32_e32 v18, 64, v18
	v_xor_b32_e32 v118, 1, v213
	v_cmp_lt_i32_e32 vcc, v118, v18
	v_pk_add_f32 v[120:121], v[120:121], 1.0 op_sel_hi:[1,0]
	s_nop 0
	v_cndmask_b32_e32 v118, v213, v118, vcc
	v_lshlrev_b32_e32 v118, 2, v118
	ds_bpermute_b32 v118, v118, v1
	v_pk_mul_f32 v[116:117], v[116:117], v[120:121]
	s_waitcnt lgkmcnt(0)
	v_add_f32_e32 v1, v1, v118
	v_xor_b32_e32 v118, 2, v213
	v_cmp_lt_i32_e32 vcc, v118, v18
	s_nop 1
	v_cndmask_b32_e32 v118, v213, v118, vcc
	v_lshlrev_b32_e32 v118, 2, v118
	ds_bpermute_b32 v118, v118, v1
	s_waitcnt lgkmcnt(0)
	v_add_f32_e32 v1, v1, v118
	v_xor_b32_e32 v118, 4, v213
	v_cmp_lt_i32_e32 vcc, v118, v18
	s_nop 1
	v_cndmask_b32_e32 v118, v213, v118, vcc
	v_lshlrev_b32_e32 v118, 2, v118
	ds_bpermute_b32 v118, v118, v1
	s_waitcnt lgkmcnt(0)
	v_add_f32_e32 v1, v1, v118
	v_xor_b32_e32 v118, 8, v213
	v_cmp_lt_i32_e32 vcc, v118, v18
	s_nop 1
	v_cndmask_b32_e32 v118, v213, v118, vcc
	v_lshlrev_b32_e32 v118, 2, v118
	ds_bpermute_b32 v118, v118, v1
	s_waitcnt lgkmcnt(0)
	v_add_f32_e32 v1, v1, v118
	v_xor_b32_e32 v118, 16, v213
	v_cmp_lt_i32_e32 vcc, v118, v18
	s_nop 1
	v_cndmask_b32_e32 v118, v213, v118, vcc
	v_lshlrev_b32_e32 v118, 2, v118
	ds_bpermute_b32 v118, v118, v1
	s_waitcnt lgkmcnt(0)
	v_add_f32_e32 v1, v1, v118
	v_xor_b32_e32 v118, 32, v213
	v_cmp_lt_i32_e32 vcc, v118, v18
	s_nop 1
	v_cndmask_b32_e32 v18, v213, v118, vcc
	v_lshlrev_b32_e32 v18, 2, v18
	ds_bpermute_b32 v18, v18, v1
	s_waitcnt lgkmcnt(0)
	v_add_f32_e32 v1, v1, v18
	v_fmamk_f32 v1, v1, 0x3a000000, v165
	v_rsq_f32_e32 v1, v1
	s_nop 0
	v_mul_f32_e32 v18, v32, v1
	v_fma_f32 v18, v70, v18, v36
	v_mul_f32_e32 v32, v33, v1
	v_mul_f32_e32 v33, v34, v1
	v_mul_f32_e32 v34, v35, v1
	v_fma_f32 v32, v71, v32, v37
	v_fmac_f32_e32 v39, v69, v34
	v_cvt_pk_bf16_f32 v32, v18, v32
	v_fma_f32 v33, v68, v33, v38
	v_bfe_u32 v18, v33, 16, 1
	v_add3_u32 v18, v33, v18, s79
	v_bfe_u32 v33, v39, 16, 1
	v_lshrrev_b32_e32 v18, 16, v18
	v_add3_u32 v33, v39, v33, s79
	v_and_or_b32 v33, v33, s80, v18
	v_mul_f32_e32 v18, v28, v1
	v_fma_f32 v18, v76, v18, v40
	v_mul_f32_e32 v28, v29, v1
	v_mul_f32_e32 v29, v30, v1
	v_mul_f32_e32 v30, v31, v1
	v_fma_f32 v28, v77, v28, v41
	v_fmac_f32_e32 v43, v75, v30
	v_cvt_pk_bf16_f32 v28, v18, v28
	v_fma_f32 v29, v74, v29, v42
	v_bfe_u32 v18, v29, 16, 1
	v_add3_u32 v18, v29, v18, s79
	v_bfe_u32 v29, v43, 16, 1
	v_lshrrev_b32_e32 v18, 16, v18
	v_add3_u32 v29, v43, v29, s79
	v_and_or_b32 v29, v29, s80, v18
	v_mul_f32_e32 v18, v24, v1
	v_fma_f32 v18, v82, v18, v44
	v_mul_f32_e32 v24, v25, v1
	v_mul_f32_e32 v25, v26, v1
	v_mul_f32_e32 v26, v27, v1
	v_fma_f32 v24, v83, v24, v45
	v_fmac_f32_e32 v47, v79, v26
	v_cvt_pk_bf16_f32 v24, v18, v24
	v_fma_f32 v25, v78, v25, v46
	v_bfe_u32 v18, v25, 16, 1
	v_add3_u32 v18, v25, v18, s79
	v_bfe_u32 v25, v47, 16, 1
	v_lshrrev_b32_e32 v18, 16, v18
	v_add3_u32 v25, v47, v25, s79
	v_and_or_b32 v25, v25, s80, v18
	v_mul_f32_e32 v18, v20, v1
	v_mul_f32_e32 v14, v14, v1
	v_mul_f32_e32 v10, v10, v1
	v_mul_f32_e32 v6, v6, v1
	v_mul_f32_e32 v2, v2, v1
	v_fma_f32 v18, v84, v18, v48
	v_mul_f32_e32 v20, v21, v1
	v_mul_f32_e32 v21, v22, v1
	v_mul_f32_e32 v22, v23, v1
	v_fma_f32 v14, v88, v14, v52
	v_mul_f32_e32 v15, v15, v1
	v_mul_f32_e32 v16, v16, v1
	v_mul_f32_e32 v17, v17, v1
	v_fma_f32 v10, v92, v10, v56
	v_mul_f32_e32 v11, v11, v1
	v_mul_f32_e32 v12, v12, v1
	v_mul_f32_e32 v13, v13, v1
	v_fma_f32 v6, v96, v6, v60
	v_mul_f32_e32 v7, v7, v1
	v_mul_f32_e32 v8, v8, v1
	v_mul_f32_e32 v9, v9, v1
	s_waitcnt vmcnt(0)
	v_fma_f32 v2, v116, v2, v64
	v_mul_f32_e32 v3, v3, v1
	v_mul_f32_e32 v4, v4, v1
	v_mul_f32_e32 v1, v5, v1
	v_fma_f32 v20, v85, v20, v49
	v_fmac_f32_e32 v51, v81, v22
	v_cvt_pk_bf16_f32 v20, v18, v20
	v_fma_f32 v15, v89, v15, v53
	v_fmac_f32_e32 v55, v87, v17
	v_cvt_pk_bf16_f32 v14, v14, v15
	v_fma_f32 v11, v93, v11, v57
	v_fmac_f32_e32 v59, v91, v13
	v_cvt_pk_bf16_f32 v10, v10, v11
	v_fma_f32 v7, v97, v7, v61
	v_fmac_f32_e32 v63, v95, v9
	v_cvt_pk_bf16_f32 v6, v6, v7
	v_fma_f32 v3, v117, v3, v65
	v_fmac_f32_e32 v67, v99, v1
	v_bfe_u32 v1, v2, 16, 1
	v_add3_u32 v1, v2, v1, s79
	v_bfe_u32 v2, v3, 16, 1
	v_fma_f32 v21, v80, v21, v50
	v_fma_f32 v16, v86, v16, v54
	v_fma_f32 v12, v90, v12, v58
	v_fma_f32 v8, v94, v8, v62
	v_fma_f32 v4, v98, v4, v66
	v_lshrrev_b32_e32 v1, 16, v1
	v_add3_u32 v2, v3, v2, s79
	v_bfe_u32 v18, v21, 16, 1
	v_bfe_u32 v15, v16, 16, 1
	v_bfe_u32 v11, v12, 16, 1
	v_bfe_u32 v7, v8, 16, 1
	v_and_or_b32 v2, v2, s80, v1
	v_cvt_pk_bf16_f32 v3, v4, v67
	v_add3_u32 v18, v21, v18, s79
	v_bfe_u32 v21, v51, 16, 1
	v_add3_u32 v15, v16, v15, s79
	v_bfe_u32 v16, v55, 16, 1
	v_add3_u32 v11, v12, v11, s79
	v_bfe_u32 v12, v59, 16, 1
	v_add3_u32 v7, v8, v7, s79
	v_bfe_u32 v8, v63, 16, 1
	v_lshrrev_b32_e32 v18, 16, v18
	v_add3_u32 v21, v51, v21, s79
	v_lshrrev_b32_e32 v15, 16, v15
	v_add3_u32 v16, v55, v16, s79
	v_lshrrev_b32_e32 v11, 16, v11
	v_add3_u32 v12, v59, v12, s79
	v_lshrrev_b32_e32 v7, 16, v7
	v_add3_u32 v8, v63, v8, s79
	v_lshl_add_u64 v[34:35], v[112:113], 0, s[6:7]
	v_and_or_b32 v21, v21, s80, v18
	v_and_or_b32 v15, v16, s80, v15
	v_and_or_b32 v11, v12, s80, v11
	v_and_or_b32 v7, v8, s80, v7
	global_store_dwordx2 v[34:35], v[32:33], off
	global_store_dwordx2 v[34:35], v[28:29], off offset:512
	global_store_dwordx2 v[34:35], v[24:25], off offset:1024
	global_store_dwordx2 v[34:35], v[20:21], off offset:1536
	global_store_dwordx2 v[34:35], v[14:15], off offset:2048
	global_store_dwordx2 v[34:35], v[10:11], off offset:2560
	global_store_dwordx2 v[34:35], v[6:7], off offset:3072
	global_store_dwordx2 v[34:35], v[2:3], off offset:3584
	s_cbranch_execnz .LBB0_1689
.LBB0_1693:
	s_ashr_i32 s1, s0, 31
	s_lshl_b64 s[6:7], s[0:1], 13
	s_waitcnt vmcnt(0)
	v_lshl_add_u64 v[2:3], v[114:115], 0, s[6:7]
	s_ashr_i32 s6, s8, 31
	s_add_u32 s7, s8, s24
	s_addc_u32 s6, s6, 0
	s_mul_i32 s6, s6, 0xc000
	s_mul_hi_u32 s8, s7, 0xc000
	v_add_co_u32_e32 v4, vcc, 0x1000, v72
	s_add_i32 s8, s8, s6
	s_mul_i32 s7, s7, 0xc000
	v_addc_co_u32_e32 v5, vcc, 0, v73, vcc
	s_add_u32 s6, s12, s7
	global_load_dwordx4 v[84:87], v[72:73], off
	global_load_dwordx4 v[32:35], v[2:3], off
	global_load_dwordx4 v[76:79], v[72:73], off offset:1024
	global_load_dwordx4 v[28:31], v[2:3], off offset:1024
	global_load_dwordx4 v[68:71], v[72:73], off offset:2048
	global_load_dwordx4 v[24:27], v[2:3], off offset:2048
	global_load_dwordx4 v[56:59], v[72:73], off offset:3072
	global_load_dwordx4 v[20:23], v[2:3], off offset:3072
	v_add_co_u32_e32 v2, vcc, 0x1000, v2
	s_addc_u32 s7, s13, s8
	s_nop 0
	v_addc_co_u32_e32 v3, vcc, 0, v3, vcc
	v_lshl_add_u64 v[98:99], s[6:7], 0, v[100:101]
	v_add_co_u32_e32 v96, vcc, s78, v98
	global_load_dwordx4 v[48:51], v[4:5], off
	s_nop 0
	v_addc_co_u32_e32 v97, vcc, 0, v99, vcc
	global_load_dwordx4 v[14:17], v[2:3], off
	global_load_dwordx4 v[44:47], v[4:5], off offset:1024
	global_load_dwordx4 v[10:13], v[2:3], off offset:1024
	global_load_dwordx4 v[40:43], v[4:5], off offset:2048
	global_load_dwordx4 v[6:9], v[2:3], off offset:2048
	global_load_dwordx4 v[36:39], v[4:5], off offset:3072
	s_nop 0
	global_load_dwordx4 v[2:5], v[2:3], off offset:3072
	s_mov_b64 s[6:7], 0x2000
	global_load_dwordx4 v[60:63], v[102:103], off
	global_load_dwordx4 v[64:67], v[96:97], off offset:-4096
	global_load_dwordx4 v[52:55], v[98:99], off
	v_lshl_add_u64 v[88:89], v[98:99], 0, s[6:7]
	s_lshl_b64 s[6:7], s[4:5], 12
	s_lshl_b64 s[0:1], s[0:1], 12
	s_waitcnt vmcnt(18)
	v_mul_f32_e32 v1, v85, v85
	v_mul_f32_e32 v18, v87, v87
	v_fmac_f32_e32 v1, v84, v84
	v_fmac_f32_e32 v18, v86, v86
	v_add_f32_e32 v1, v1, v18
	s_waitcnt vmcnt(16)
	v_mul_f32_e32 v18, v77, v77
	v_fmac_f32_e32 v18, v76, v76
	s_waitcnt vmcnt(1)
	v_pk_add_f32 v[66:67], v[66:67], 1.0 op_sel_hi:[1,0]
	v_pk_add_f32 v[64:65], v[64:65], 1.0 op_sel_hi:[1,0]
	v_pk_mul_f32 v[116:117], v[62:63], v[66:67]
	v_pk_mul_f32 v[118:119], v[60:61], v[64:65]
	global_load_dwordx4 v[64:67], v[102:103], off offset:1024
	global_load_dwordx4 v[72:75], v[88:89], off offset:1024
	global_load_dwordx4 v[60:63], v[98:99], off offset:1024
	s_waitcnt vmcnt(1)
	v_pk_add_f32 v[74:75], v[74:75], 1.0 op_sel_hi:[1,0]
	v_pk_add_f32 v[72:73], v[72:73], 1.0 op_sel_hi:[1,0]
	v_pk_mul_f32 v[120:121], v[66:67], v[74:75]
	v_pk_mul_f32 v[122:123], v[64:65], v[72:73]
	global_load_dwordx4 v[72:75], v[102:103], off offset:2048
	global_load_dwordx4 v[80:83], v[88:89], off offset:2048
	global_load_dwordx4 v[64:67], v[98:99], off offset:2048
	s_waitcnt vmcnt(1)
	v_pk_add_f32 v[82:83], v[82:83], 1.0 op_sel_hi:[1,0]
	v_pk_add_f32 v[80:81], v[80:81], 1.0 op_sel_hi:[1,0]
	v_pk_mul_f32 v[124:125], v[74:75], v[82:83]
	v_pk_mul_f32 v[126:127], v[72:73], v[80:81]
	global_load_dwordx4 v[80:83], v[102:103], off offset:3072
	s_nop 0
	global_load_dwordx4 v[88:91], v[88:89], off offset:3072
	s_nop 0
	global_load_dwordx4 v[72:75], v[98:99], off offset:3072
	v_add_co_u32_e32 v98, vcc, s3, v98
	s_waitcnt vmcnt(1)
	v_pk_add_f32 v[90:91], v[90:91], 1.0 op_sel_hi:[1,0]
	v_pk_add_f32 v[88:89], v[88:89], 1.0 op_sel_hi:[1,0]
	v_pk_mul_f32 v[128:129], v[82:83], v[90:91]
	v_pk_mul_f32 v[130:131], v[80:81], v[88:89]
	global_load_dwordx4 v[88:91], v[104:105], off
	global_load_dwordx4 v[92:95], v[96:97], off
	v_addc_co_u32_e32 v99, vcc, 0, v99, vcc
	global_load_dwordx4 v[80:83], v[98:99], off
	s_waitcnt vmcnt(1)
	v_pk_add_f32 v[94:95], v[94:95], 1.0 op_sel_hi:[1,0]
	v_pk_add_f32 v[92:93], v[92:93], 1.0 op_sel_hi:[1,0]
	v_pk_mul_f32 v[132:133], v[90:91], v[94:95]
	v_pk_mul_f32 v[134:135], v[88:89], v[92:93]
	global_load_dwordx4 v[92:95], v[106:107], off
	global_load_dwordx4 v[136:139], v[96:97], off offset:1024
	global_load_dwordx4 v[88:91], v[98:99], off offset:1024
	s_waitcnt vmcnt(1)
	v_pk_add_f32 v[138:139], v[138:139], 1.0 op_sel_hi:[1,0]
	v_pk_add_f32 v[140:141], v[136:137], 1.0 op_sel_hi:[1,0]
	v_pk_mul_f32 v[136:137], v[94:95], v[138:139]
	v_pk_mul_f32 v[138:139], v[92:93], v[140:141]
	global_load_dwordx4 v[142:145], v[108:109], off
	global_load_dwordx4 v[146:149], v[96:97], off offset:2048
	global_load_dwordx4 v[92:95], v[98:99], off offset:2048
	s_waitcnt vmcnt(1)
	v_pk_add_f32 v[146:147], v[146:147], 1.0 op_sel_hi:[1,0]
	v_pk_add_f32 v[140:141], v[148:149], 1.0 op_sel_hi:[1,0]
	v_pk_mul_f32 v[142:143], v[142:143], v[146:147]
	global_load_dwordx4 v[146:149], v[110:111], off
	global_load_dwordx4 v[150:153], v[96:97], off offset:3072
	s_nop 0
	global_load_dwordx4 v[96:99], v[98:99], off offset:3072
	v_pk_mul_f32 v[140:141], v[144:145], v[140:141]
	s_waitcnt vmcnt(1)
	v_pk_add_f32 v[144:145], v[152:153], 1.0 op_sel_hi:[1,0]
	s_nop 0
	v_pk_mul_f32 v[144:145], v[148:149], v[144:145]
	v_mul_f32_e32 v148, v79, v79
	v_fmac_f32_e32 v148, v78, v78
	v_add_f32_e32 v18, v18, v148
	v_add_f32_e32 v1, v1, v18
	v_mul_f32_e32 v18, v69, v69
	v_mul_f32_e32 v148, v71, v71
	v_fmac_f32_e32 v18, v68, v68
	v_fmac_f32_e32 v148, v70, v70
	v_add_f32_e32 v18, v18, v148
	v_add_f32_e32 v1, v1, v18
	v_mul_f32_e32 v18, v57, v57
	v_mul_f32_e32 v148, v59, v59
	v_fmac_f32_e32 v18, v56, v56
	v_fmac_f32_e32 v148, v58, v58
	v_add_f32_e32 v18, v18, v148
	v_add_f32_e32 v1, v1, v18
	v_mul_f32_e32 v18, v49, v49
	v_mul_f32_e32 v148, v51, v51
	v_fmac_f32_e32 v18, v48, v48
	v_fmac_f32_e32 v148, v50, v50
	v_add_f32_e32 v18, v18, v148
	v_add_f32_e32 v1, v1, v18
	v_mul_f32_e32 v18, v45, v45
	v_mul_f32_e32 v148, v47, v47
	v_fmac_f32_e32 v18, v44, v44
	v_fmac_f32_e32 v148, v46, v46
	v_add_f32_e32 v18, v18, v148
	v_add_f32_e32 v1, v1, v18
	v_mul_f32_e32 v18, v41, v41
	v_mul_f32_e32 v148, v43, v43
	v_fmac_f32_e32 v18, v40, v40
	v_fmac_f32_e32 v148, v42, v42
	v_add_f32_e32 v18, v18, v148
	v_add_f32_e32 v1, v1, v18
	v_mul_f32_e32 v18, v37, v37
	v_mul_f32_e32 v148, v39, v39
	v_fmac_f32_e32 v18, v36, v36
	v_fmac_f32_e32 v148, v38, v38
	v_add_f32_e32 v18, v18, v148
	v_add_f32_e32 v1, v1, v18
	v_mul_f32_e32 v18, v33, v33
	v_mul_f32_e32 v148, v35, v35
	v_fmac_f32_e32 v18, v32, v32
	v_fmac_f32_e32 v148, v34, v34
	v_add_f32_e32 v18, v18, v148
	v_mul_f32_e32 v148, v29, v29
	v_mul_f32_e32 v149, v31, v31
	v_fmac_f32_e32 v148, v28, v28
	v_fmac_f32_e32 v149, v30, v30
	v_add_f32_e32 v148, v148, v149
	v_add_f32_e32 v18, v18, v148
	v_mul_f32_e32 v148, v25, v25
	v_mul_f32_e32 v149, v27, v27
	v_fmac_f32_e32 v148, v24, v24
	v_fmac_f32_e32 v149, v26, v26
	v_add_f32_e32 v148, v148, v149
	v_add_f32_e32 v18, v18, v148
	v_mul_f32_e32 v148, v21, v21
	v_mul_f32_e32 v149, v23, v23
	v_fmac_f32_e32 v148, v20, v20
	v_fmac_f32_e32 v149, v22, v22
	v_add_f32_e32 v148, v148, v149
	v_add_f32_e32 v18, v18, v148
	v_mul_f32_e32 v148, v15, v15
	v_mul_f32_e32 v149, v17, v17
	v_fmac_f32_e32 v148, v14, v14
	v_fmac_f32_e32 v149, v16, v16
	v_add_f32_e32 v148, v148, v149
	v_add_f32_e32 v18, v18, v148
	v_mul_f32_e32 v148, v11, v11
	v_mul_f32_e32 v149, v13, v13
	v_fmac_f32_e32 v148, v10, v10
	v_fmac_f32_e32 v149, v12, v12
	v_add_f32_e32 v148, v148, v149
	v_add_f32_e32 v18, v18, v148
	v_mul_f32_e32 v148, v7, v7
	v_mul_f32_e32 v149, v9, v9
	v_fmac_f32_e32 v148, v6, v6
	v_fmac_f32_e32 v149, v8, v8
	v_add_f32_e32 v148, v148, v149
	v_add_f32_e32 v18, v18, v148
	v_mul_f32_e32 v148, v3, v3
	v_mul_f32_e32 v149, v5, v5
	v_fmac_f32_e32 v148, v2, v2
	v_fmac_f32_e32 v149, v4, v4
	v_add_f32_e32 v148, v148, v149
	v_add_f32_e32 v18, v18, v148
	v_and_b32_e32 v148, 64, v213
	v_add_u32_e32 v148, 64, v148
	v_xor_b32_e32 v149, 1, v213
	v_cmp_lt_i32_e32 vcc, v149, v148
	v_pk_add_f32 v[150:151], v[150:151], 1.0 op_sel_hi:[1,0]
	s_nop 0
	v_cndmask_b32_e32 v149, v213, v149, vcc
	v_lshlrev_b32_e32 v149, 2, v149
	v_pk_mul_f32 v[146:147], v[146:147], v[150:151]
	ds_bpermute_b32 v150, v149, v1
	ds_bpermute_b32 v149, v149, v18
	s_waitcnt lgkmcnt(1)
	v_add_f32_e32 v1, v1, v150
	s_waitcnt lgkmcnt(0)
	v_add_f32_e32 v18, v18, v149
	v_xor_b32_e32 v149, 2, v213
	v_cmp_lt_i32_e32 vcc, v149, v148
	s_nop 1
	v_cndmask_b32_e32 v149, v213, v149, vcc
	v_lshlrev_b32_e32 v149, 2, v149
	ds_bpermute_b32 v150, v149, v1
	ds_bpermute_b32 v149, v149, v18
	s_waitcnt lgkmcnt(1)
	v_add_f32_e32 v1, v1, v150
	s_waitcnt lgkmcnt(0)
	v_add_f32_e32 v18, v18, v149
	v_xor_b32_e32 v149, 4, v213
	v_cmp_lt_i32_e32 vcc, v149, v148
	s_nop 1
	v_cndmask_b32_e32 v149, v213, v149, vcc
	v_lshlrev_b32_e32 v149, 2, v149
	ds_bpermute_b32 v150, v149, v1
	ds_bpermute_b32 v149, v149, v18
	s_waitcnt lgkmcnt(1)
	v_add_f32_e32 v1, v1, v150
	s_waitcnt lgkmcnt(0)
	v_add_f32_e32 v18, v18, v149
	v_xor_b32_e32 v149, 8, v213
	v_cmp_lt_i32_e32 vcc, v149, v148
	s_nop 1
	v_cndmask_b32_e32 v149, v213, v149, vcc
	v_lshlrev_b32_e32 v149, 2, v149
	ds_bpermute_b32 v150, v149, v1
	ds_bpermute_b32 v149, v149, v18
	s_waitcnt lgkmcnt(1)
	v_add_f32_e32 v1, v1, v150
	s_waitcnt lgkmcnt(0)
	v_add_f32_e32 v18, v18, v149
	v_xor_b32_e32 v149, 16, v213
	v_cmp_lt_i32_e32 vcc, v149, v148
	s_nop 1
	v_cndmask_b32_e32 v149, v213, v149, vcc
	v_lshlrev_b32_e32 v149, 2, v149
	ds_bpermute_b32 v150, v149, v1
	ds_bpermute_b32 v149, v149, v18
	s_waitcnt lgkmcnt(1)
	v_add_f32_e32 v1, v1, v150
	s_waitcnt lgkmcnt(0)
	v_add_f32_e32 v18, v18, v149
	v_xor_b32_e32 v149, 32, v213
	v_cmp_lt_i32_e32 vcc, v149, v148
	s_nop 1
	v_cndmask_b32_e32 v148, v213, v149, vcc
	v_lshlrev_b32_e32 v148, 2, v148
	ds_bpermute_b32 v149, v148, v1
	ds_bpermute_b32 v148, v148, v18
	s_waitcnt lgkmcnt(1)
	v_add_f32_e32 v1, v1, v149
	v_fmamk_f32 v1, v1, 0x3a000000, v165
	v_rsq_f32_e32 v1, v1
	s_waitcnt lgkmcnt(0)
	v_add_f32_e32 v18, v18, v148
	v_mul_f32_e32 v84, v84, v1
	v_fma_f32 v84, v118, v84, v52
	v_mul_f32_e32 v85, v85, v1
	v_fma_f32 v85, v119, v85, v53
	v_cvt_pk_bf16_f32 v84, v84, v85
	v_mul_f32_e32 v86, v86, v1
	v_fma_f32 v86, v116, v86, v54
	v_mul_f32_e32 v87, v87, v1
	v_fma_f32 v87, v117, v87, v55
	v_bfe_u32 v85, v86, 16, 1
	v_mul_f32_e32 v36, v36, v1
	v_add3_u32 v85, v86, v85, s79
	v_bfe_u32 v86, v87, 16, 1
	s_waitcnt vmcnt(0)
	v_fma_f32 v36, v146, v36, v96
	v_mul_f32_e32 v37, v37, v1
	v_lshrrev_b32_e32 v85, 16, v85
	v_add3_u32 v86, v87, v86, s79
	v_mul_f32_e32 v76, v76, v1
	v_mul_f32_e32 v77, v77, v1
	v_mul_f32_e32 v78, v78, v1
	v_mul_f32_e32 v79, v79, v1
	v_mul_f32_e32 v68, v68, v1
	v_mul_f32_e32 v69, v69, v1
	v_mul_f32_e32 v70, v70, v1
	v_mul_f32_e32 v71, v71, v1
	v_mul_f32_e32 v56, v56, v1
	v_mul_f32_e32 v57, v57, v1
	v_mul_f32_e32 v58, v58, v1
	v_mul_f32_e32 v59, v59, v1
	v_mul_f32_e32 v48, v48, v1
	v_mul_f32_e32 v49, v49, v1
	v_mul_f32_e32 v50, v50, v1
	v_mul_f32_e32 v51, v51, v1
	v_mul_f32_e32 v44, v44, v1
	v_mul_f32_e32 v45, v45, v1
	v_mul_f32_e32 v46, v46, v1
	v_mul_f32_e32 v47, v47, v1
	v_mul_f32_e32 v40, v40, v1
	v_mul_f32_e32 v41, v41, v1
	v_mul_f32_e32 v42, v42, v1
	v_mul_f32_e32 v43, v43, v1
	v_fma_f32 v37, v147, v37, v97
	v_mul_f32_e32 v38, v38, v1
	v_mul_f32_e32 v1, v39, v1
	v_cvt_pk_bf16_f32 v36, v36, v37
	v_and_or_b32 v85, v86, s80, v85
	v_lshl_add_u64 v[86:87], v[112:113], 0, s[6:7]
	v_fma_f32 v76, v122, v76, v60
	global_store_dwordx2 v[86:87], v[84:85], off
	v_fma_f32 v77, v123, v77, v61
	v_cvt_pk_bf16_f32 v76, v76, v77
	v_fma_f32 v38, v144, v38, v98
	s_nop 0
	s_nop 0
	s_nop 0
	v_fma_f32 v1, v145, v1, v99
	v_bfe_u32 v37, v38, 16, 1
	v_fma_f32 v78, v120, v78, v62
	v_add3_u32 v37, v38, v37, s79
	v_bfe_u32 v38, v1, 16, 1
	v_fma_f32 v79, v121, v79, v63
	v_bfe_u32 v77, v78, 16, 1
	v_lshrrev_b32_e32 v37, 16, v37
	v_add3_u32 v1, v1, v38, s79
	v_add3_u32 v77, v78, v77, s79
	v_bfe_u32 v78, v79, 16, 1
	v_and_or_b32 v37, v1, s80, v37
	v_fmamk_f32 v1, v18, 0x3a000000, v165
	v_lshrrev_b32_e32 v77, 16, v77
	v_add3_u32 v78, v79, v78, s79
	v_rsq_f32_e32 v1, v1
	v_and_or_b32 v77, v78, s80, v77
	v_fma_f32 v68, v126, v68, v64
	global_store_dwordx2 v[86:87], v[76:77], off offset:512
	v_fma_f32 v69, v127, v69, v65
	v_cvt_pk_bf16_f32 v68, v68, v69
	s_nop 0
	s_nop 0
	v_fma_f32 v70, v124, v70, v66
	s_nop 0
	v_mul_f32_e32 v18, v32, v1
	v_fma_f32 v71, v125, v71, v67
	v_bfe_u32 v69, v70, 16, 1
	v_fma_f32 v18, v118, v18, v52
	v_mul_f32_e32 v32, v33, v1
	v_mul_f32_e32 v33, v34, v1
	v_mul_f32_e32 v34, v35, v1
	v_add3_u32 v69, v70, v69, s79
	v_bfe_u32 v70, v71, 16, 1
	v_fma_f32 v32, v119, v32, v53
	v_fmac_f32_e32 v55, v117, v34
	v_cvt_pk_bf16_f32 v32, v18, v32
	v_lshrrev_b32_e32 v69, 16, v69
	v_add3_u32 v70, v71, v70, s79
	v_and_or_b32 v69, v70, s80, v69
	v_fma_f32 v56, v130, v56, v72
	v_fma_f32 v33, v116, v33, v54
	global_store_dwordx2 v[86:87], v[68:69], off offset:1024
	v_fma_f32 v57, v131, v57, v73
	v_cvt_pk_bf16_f32 v56, v56, v57
	s_nop 0
	v_bfe_u32 v18, v33, 16, 1
	s_nop 0
	s_nop 0
	v_add3_u32 v18, v33, v18, s79
	v_bfe_u32 v33, v55, 16, 1
	v_fma_f32 v58, v128, v58, v74
	v_lshrrev_b32_e32 v18, 16, v18
	v_add3_u32 v33, v55, v33, s79
	v_fma_f32 v59, v129, v59, v75
	v_bfe_u32 v57, v58, 16, 1
	v_and_or_b32 v33, v33, s80, v18
	v_mul_f32_e32 v18, v28, v1
	v_add3_u32 v57, v58, v57, s79
	v_bfe_u32 v58, v59, 16, 1
	v_fma_f32 v18, v122, v18, v60
	v_mul_f32_e32 v28, v29, v1
	v_mul_f32_e32 v29, v30, v1
	v_mul_f32_e32 v30, v31, v1
	v_lshrrev_b32_e32 v57, 16, v57
	v_add3_u32 v58, v59, v58, s79
	v_fma_f32 v28, v123, v28, v61
	v_fmac_f32_e32 v63, v121, v30
	v_cvt_pk_bf16_f32 v28, v18, v28
	v_and_or_b32 v57, v58, s80, v57
	v_fma_f32 v48, v134, v48, v80
	global_store_dwordx2 v[86:87], v[56:57], off offset:1536
	v_fma_f32 v49, v135, v49, v81
	v_cvt_pk_bf16_f32 v48, v48, v49
	v_fma_f32 v29, v120, v29, v62
	s_nop 0
	s_nop 0
	s_nop 0
	v_bfe_u32 v18, v29, 16, 1
	v_fma_f32 v50, v132, v50, v82
	v_add3_u32 v18, v29, v18, s79
	v_bfe_u32 v29, v63, 16, 1
	v_fma_f32 v51, v133, v51, v83
	v_bfe_u32 v49, v50, 16, 1
	v_lshrrev_b32_e32 v18, 16, v18
	v_add3_u32 v29, v63, v29, s79
	v_add3_u32 v49, v50, v49, s79
	v_bfe_u32 v50, v51, 16, 1
	v_and_or_b32 v29, v29, s80, v18
	v_mul_f32_e32 v18, v24, v1
	v_lshrrev_b32_e32 v49, 16, v49
	v_add3_u32 v50, v51, v50, s79
	v_fma_f32 v18, v126, v18, v64
	v_mul_f32_e32 v24, v25, v1
	v_mul_f32_e32 v25, v26, v1
	v_mul_f32_e32 v26, v27, v1
	v_and_or_b32 v49, v50, s80, v49
	v_fma_f32 v44, v138, v44, v88
	v_fma_f32 v24, v127, v24, v65
	v_fmac_f32_e32 v67, v125, v26
	v_cvt_pk_bf16_f32 v24, v18, v24
	global_store_dwordx2 v[86:87], v[48:49], off offset:2048
	v_fma_f32 v45, v139, v45, v89
	v_cvt_pk_bf16_f32 v44, v44, v45
	s_nop 0
	s_nop 0
	s_nop 0
	s_nop 0
	v_fma_f32 v25, v124, v25, v66
	v_fma_f32 v46, v136, v46, v90
	v_bfe_u32 v18, v25, 16, 1
	v_fma_f32 v47, v137, v47, v91
	v_bfe_u32 v45, v46, 16, 1
	v_add3_u32 v18, v25, v18, s79
	v_bfe_u32 v25, v67, 16, 1
	v_add3_u32 v45, v46, v45, s79
	v_bfe_u32 v46, v47, 16, 1
	v_lshrrev_b32_e32 v18, 16, v18
	v_add3_u32 v25, v67, v25, s79
	v_lshrrev_b32_e32 v45, 16, v45
	v_add3_u32 v46, v47, v46, s79
	v_and_or_b32 v25, v25, s80, v18
	v_mul_f32_e32 v18, v20, v1
	v_mul_f32_e32 v14, v14, v1
	v_mul_f32_e32 v10, v10, v1
	v_mul_f32_e32 v6, v6, v1
	v_mul_f32_e32 v2, v2, v1
	v_and_or_b32 v45, v46, s80, v45
	v_fma_f32 v40, v142, v40, v92
	v_fma_f32 v18, v130, v18, v72
	v_mul_f32_e32 v20, v21, v1
	v_mul_f32_e32 v21, v22, v1
	v_mul_f32_e32 v22, v23, v1
	v_fma_f32 v14, v134, v14, v80
	v_mul_f32_e32 v15, v15, v1
	v_mul_f32_e32 v16, v16, v1
	v_mul_f32_e32 v17, v17, v1
	v_fma_f32 v10, v138, v10, v88
	v_mul_f32_e32 v11, v11, v1
	v_mul_f32_e32 v12, v12, v1
	v_mul_f32_e32 v13, v13, v1
	v_fma_f32 v6, v142, v6, v92
	v_mul_f32_e32 v7, v7, v1
	v_mul_f32_e32 v8, v8, v1
	v_mul_f32_e32 v9, v9, v1
	v_fma_f32 v2, v146, v2, v96
	v_mul_f32_e32 v3, v3, v1
	v_mul_f32_e32 v4, v4, v1
	v_mul_f32_e32 v1, v5, v1
	global_store_dwordx2 v[86:87], v[44:45], off offset:2560
	v_fma_f32 v41, v143, v41, v93
	v_fma_f32 v43, v141, v43, v95
	v_cvt_pk_bf16_f32 v40, v40, v41
	v_fma_f32 v20, v131, v20, v73
	v_fmac_f32_e32 v75, v129, v22
	v_cvt_pk_bf16_f32 v20, v18, v20
	v_fma_f32 v15, v135, v15, v81
	v_fmac_f32_e32 v83, v133, v17
	v_cvt_pk_bf16_f32 v14, v14, v15
	v_fma_f32 v11, v139, v11, v89
	v_fmac_f32_e32 v91, v137, v13
	v_cvt_pk_bf16_f32 v10, v10, v11
	v_fma_f32 v7, v143, v7, v93
	v_fmac_f32_e32 v95, v141, v9
	v_cvt_pk_bf16_f32 v6, v6, v7
	v_fma_f32 v3, v147, v3, v97
	v_fmac_f32_e32 v99, v145, v1
	v_bfe_u32 v1, v2, 16, 1
	v_add3_u32 v1, v2, v1, s79
	v_bfe_u32 v2, v3, 16, 1
	v_fma_f32 v42, v140, v42, v94
	v_fma_f32 v21, v128, v21, v74
	v_fma_f32 v16, v132, v16, v82
	v_fma_f32 v12, v136, v12, v90
	v_fma_f32 v8, v140, v8, v94
	v_fma_f32 v4, v144, v4, v98
	v_lshrrev_b32_e32 v1, 16, v1
	v_add3_u32 v2, v3, v2, s79
	v_bfe_u32 v41, v42, 16, 1
	v_bfe_u32 v18, v21, 16, 1
	v_bfe_u32 v15, v16, 16, 1
	v_bfe_u32 v11, v12, 16, 1
	v_bfe_u32 v7, v8, 16, 1
	v_and_or_b32 v2, v2, s80, v1
	v_cvt_pk_bf16_f32 v3, v4, v99
	v_add3_u32 v41, v42, v41, s79
	v_bfe_u32 v42, v43, 16, 1
	v_add3_u32 v18, v21, v18, s79
	v_bfe_u32 v21, v75, 16, 1
	v_add3_u32 v15, v16, v15, s79
	v_bfe_u32 v16, v83, 16, 1
	v_add3_u32 v11, v12, v11, s79
	v_bfe_u32 v12, v91, 16, 1
	v_add3_u32 v7, v8, v7, s79
	v_bfe_u32 v8, v95, 16, 1
	v_lshrrev_b32_e32 v41, 16, v41
	v_add3_u32 v42, v43, v42, s79
	v_lshl_add_u64 v[34:35], v[112:113], 0, s[0:1]
	v_lshrrev_b32_e32 v18, 16, v18
	v_add3_u32 v21, v75, v21, s79
	v_lshrrev_b32_e32 v15, 16, v15
	v_add3_u32 v16, v83, v16, s79
	v_lshrrev_b32_e32 v11, 16, v11
	v_add3_u32 v12, v91, v12, s79
	v_lshrrev_b32_e32 v7, 16, v7
	v_add3_u32 v8, v95, v8, s79
	s_nop 0
	s_nop 0
	v_readlane_b32 s0, v251, 24
	v_and_or_b32 v41, v42, s80, v41
	v_and_or_b32 v21, v21, s80, v18
	v_and_or_b32 v15, v16, s80, v15
	v_and_or_b32 v11, v12, s80, v11
	v_and_or_b32 v7, v8, s80, v7
	s_nop 0
	s_add_i32 s0, s0, s4
	global_store_dwordx2 v[86:87], v[40:41], off offset:3072
	global_store_dwordx2 v[86:87], v[36:37], off offset:3584
	global_store_dwordx2 v[34:35], v[32:33], off
	global_store_dwordx2 v[34:35], v[28:29], off offset:512
	global_store_dwordx2 v[34:35], v[24:25], off offset:1024
	global_store_dwordx2 v[34:35], v[20:21], off offset:1536
	global_store_dwordx2 v[34:35], v[14:15], off offset:2048
	global_store_dwordx2 v[34:35], v[10:11], off offset:2560
	global_store_dwordx2 v[34:35], v[6:7], off offset:3072
	global_store_dwordx2 v[34:35], v[2:3], off offset:3584
	s_branch .LBB0_1689

.LBB0_1776:
	s_add_i32 s13, s12, s10
	s_cmpk_gt_i32 s13, 0x5aff
	s_cbranch_scc1 .LBB0_1775
	s_cmpk_gt_i32 s13, 0x12ff
	s_mov_b64 s[10:11], -1
	s_cbranch_scc0 .LBB0_1787
	s_cmpk_gt_u32 s13, 0x1aff
	s_cbranch_scc0 .LBB0_1784
	s_cmpk_gt_u32 s13, 0x3aff
	s_cbranch_scc0 .LBB0_1781
	s_and_b32 s10, s13, 0x7fffffc0
	s_addk_i32 s10, 0xc500
	s_lshl_b32 s11, s13, 5
	s_and_b32 s14, s11, 0x7e0
	v_add_u32_e32 v24, s10, v1
	s_lshl_b32 s90, s14, 2
	v_ashrrev_i32_e32 v25, 31, v24
	v_lshl_add_u64 v[32:33], v[6:7], 0, s[90:91]
	v_lshlrev_b64 v[24:25], 13, v[24:25]
	v_lshl_add_u64 v[24:25], v[32:33], 0, v[24:25]
	v_add_co_u32_e32 v32, vcc, 0x4000, v24
	global_load_dword v5, v[24:25], off nt
	s_nop 0
	v_addc_co_u32_e32 v33, vcc, 0, v25, vcc
	global_load_dword v11, v[32:33], off nt
	v_add_co_u32_e32 v32, vcc, 0x8000, v24
	s_mov_b32 s11, 0xc000
	s_nop 0
	v_addc_co_u32_e32 v33, vcc, 0, v25, vcc
	global_load_dword v18, v[32:33], off nt
	v_add_co_u32_e32 v32, vcc, s11, v24
	s_mov_b32 s11, 0x10000
	s_nop 0
	v_addc_co_u32_e32 v33, vcc, 0, v25, vcc
	global_load_dword v31, v[32:33], off nt
	v_add_co_u32_e32 v32, vcc, s11, v24
	s_mov_b32 s11, 0x14000
	s_nop 0
	v_addc_co_u32_e32 v33, vcc, 0, v25, vcc
	global_load_dword v34, v[32:33], off nt
	v_add_co_u32_e32 v32, vcc, s11, v24
	s_mov_b32 s11, 0x18000
	s_nop 0
	v_addc_co_u32_e32 v33, vcc, 0, v25, vcc
	global_load_dword v35, v[32:33], off nt
	v_add_co_u32_e32 v32, vcc, s11, v24
	s_mov_b32 s11, 0x1c000
	s_nop 0
	v_addc_co_u32_e32 v33, vcc, 0, v25, vcc
	global_load_dword v36, v[32:33], off nt
	v_add_co_u32_e32 v32, vcc, s11, v24
	s_mov_b32 s11, 0x20000
	s_nop 0
	v_addc_co_u32_e32 v33, vcc, 0, v25, vcc
	global_load_dword v37, v[32:33], off nt
	v_add_co_u32_e32 v32, vcc, s11, v24
	s_mov_b32 s11, 0x58000
	s_nop 0
	v_addc_co_u32_e32 v33, vcc, 0, v25, vcc
	global_load_dword v38, v[32:33], off nt
	v_add_co_u32_e32 v32, vcc, s19, v24
	s_lshr_b32 s90, s10, 6
	s_nop 0
	v_addc_co_u32_e32 v33, vcc, 0, v25, vcc
	global_load_dword v39, v[32:33], off nt
	v_add_co_u32_e32 v32, vcc, s20, v24
	s_nop 1
	v_addc_co_u32_e32 v33, vcc, 0, v25, vcc
	global_load_dword v40, v[32:33], off nt
	v_add_co_u32_e32 v32, vcc, s21, v24
	s_nop 1
	v_addc_co_u32_e32 v33, vcc, 0, v25, vcc
	global_load_dword v41, v[32:33], off nt
	v_add_co_u32_e32 v32, vcc, s22, v24
	s_nop 1
	v_addc_co_u32_e32 v33, vcc, 0, v25, vcc
	global_load_dword v42, v[32:33], off nt
	v_add_co_u32_e32 v32, vcc, s23, v24
	s_nop 1
	v_addc_co_u32_e32 v33, vcc, 0, v25, vcc
	global_load_dword v43, v[32:33], off nt
	v_add_co_u32_e32 v32, vcc, s24, v24
	s_nop 1
	v_addc_co_u32_e32 v33, vcc, 0, v25, vcc
	global_load_dword v44, v[32:33], off nt
	v_add_co_u32_e32 v32, vcc, s25, v24
	s_nop 1
	v_addc_co_u32_e32 v33, vcc, 0, v25, vcc
	global_load_dword v45, v[32:33], off nt
	v_add_co_u32_e32 v32, vcc, s26, v24
	s_nop 1
	v_addc_co_u32_e32 v33, vcc, 0, v25, vcc
	global_load_dword v46, v[32:33], off nt
	v_add_co_u32_e32 v32, vcc, s27, v24
	s_nop 1
	v_addc_co_u32_e32 v33, vcc, 0, v25, vcc
	global_load_dword v47, v[32:33], off nt
	v_add_co_u32_e32 v32, vcc, s43, v24
	s_nop 1
	v_addc_co_u32_e32 v33, vcc, 0, v25, vcc
	global_load_dword v48, v[32:33], off nt
	v_add_co_u32_e32 v32, vcc, s44, v24
	s_nop 1
	v_addc_co_u32_e32 v33, vcc, 0, v25, vcc
	global_load_dword v49, v[32:33], off nt
	v_add_co_u32_e32 v32, vcc, s45, v24
	s_nop 1
	v_addc_co_u32_e32 v33, vcc, 0, v25, vcc
	global_load_dword v50, v[32:33], off nt
	v_add_co_u32_e32 v32, vcc, s46, v24
	s_nop 1
	v_addc_co_u32_e32 v33, vcc, 0, v25, vcc
	global_load_dword v51, v[32:33], off nt
	v_add_co_u32_e32 v32, vcc, s11, v24
	s_mov_b32 s11, 0x5c000
	s_nop 0
	v_addc_co_u32_e32 v33, vcc, 0, v25, vcc
	global_load_dword v52, v[32:33], off nt
	v_add_co_u32_e32 v32, vcc, s11, v24
	s_mov_b32 s11, 0x60000
	s_nop 0
	v_addc_co_u32_e32 v33, vcc, 0, v25, vcc
	global_load_dword v53, v[32:33], off nt
	v_add_co_u32_e32 v32, vcc, s11, v24
	s_mov_b32 s11, 0x64000
	s_nop 0
	v_addc_co_u32_e32 v33, vcc, 0, v25, vcc
	global_load_dword v54, v[32:33], off nt
	v_add_co_u32_e32 v32, vcc, s11, v24
	s_mov_b32 s11, 0x68000
	s_nop 0
	v_addc_co_u32_e32 v33, vcc, 0, v25, vcc
	global_load_dword v55, v[32:33], off nt
	v_add_co_u32_e32 v32, vcc, s11, v24
	s_mov_b32 s11, 0x6c000
	s_nop 0
	v_addc_co_u32_e32 v33, vcc, 0, v25, vcc
	global_load_dword v56, v[32:33], off nt
	v_add_co_u32_e32 v32, vcc, s11, v24
	s_mov_b32 s11, 0x70000
	s_nop 0
	v_addc_co_u32_e32 v33, vcc, 0, v25, vcc
	global_load_dword v57, v[32:33], off nt
	v_add_co_u32_e32 v32, vcc, s11, v24
	s_mov_b32 s11, 0x74000
	s_nop 0
	v_addc_co_u32_e32 v33, vcc, 0, v25, vcc
	global_load_dword v58, v[32:33], off nt
	v_add_co_u32_e32 v32, vcc, s11, v24
	s_mov_b32 s11, 0x78000
	s_nop 0
	v_addc_co_u32_e32 v33, vcc, 0, v25, vcc
	global_load_dword v59, v[32:33], off nt
	v_add_co_u32_e32 v32, vcc, s11, v24
	s_mov_b32 s11, 0x7c000
	s_nop 0
	v_addc_co_u32_e32 v33, vcc, 0, v25, vcc
	v_add_co_u32_e32 v24, vcc, s11, v24
	global_load_dword v32, v[32:33], off nt
	s_nop 0
	v_addc_co_u32_e32 v25, vcc, 0, v25, vcc
	global_load_dword v24, v[24:25], off nt
	s_waitcnt vmcnt(0)
	ds_write2_b32 v3, v5, v11 offset1:66
	ds_write2_b32 v3, v18, v31 offset0:132 offset1:198
	v_add_u32_e32 v5, 0x400, v3
	ds_write2_b32 v5, v34, v35 offset0:8 offset1:74
	ds_write2_b32 v5, v36, v37 offset0:140 offset1:206
	v_add_u32_e32 v5, 0x800, v3
	ds_write2_b32 v5, v38, v39 offset0:16 offset1:82
	ds_write2_b32 v5, v40, v41 offset0:148 offset1:214
	v_add_u32_e32 v5, 0xc00, v3
	ds_write2_b32 v5, v42, v43 offset0:24 offset1:90
	ds_write2_b32 v5, v44, v45 offset0:156 offset1:222
	v_add_u32_e32 v5, 0x1000, v3
	ds_write2_b32 v5, v46, v47 offset0:32 offset1:98
	ds_write2_b32 v5, v48, v49 offset0:164 offset1:230
	v_add_u32_e32 v5, 0x1400, v3
	ds_write2_b32 v5, v50, v51 offset0:40 offset1:106
	ds_write2_b32 v5, v52, v53 offset0:172 offset1:238
	v_add_u32_e32 v5, 0x1800, v3
	ds_write2_b32 v5, v54, v55 offset0:48 offset1:114
	ds_write2_b32 v5, v56, v57 offset0:180 offset1:246
	v_add_u32_e32 v5, 0x1c00, v3
	ds_write2_b32 v5, v58, v59 offset0:56 offset1:122
	ds_write2_b32 v5, v32, v24 offset0:188 offset1:254
	s_waitcnt lgkmcnt(0)
	v_and_b32_e32 v70, 3, v146
	v_mul_u32_u24_e32 v70, 0x420, v70
	v_lshrrev_b32_e32 v71, 4, v146
	v_lshl_add_u32 v70, v71, 5, v70
	v_bfe_u32 v71, v146, 2, 2
	v_lshl_add_u32 v70, v71, 2, v70
	s_lshl_b32 s100, s42, 14
	v_add_u32_e32 v70, s100, v70
	v_add_u32_e32 v71, 0x1080, v70
	ds_read2_b32 v[24:25], v70 offset0:33 offset1:37
	ds_read2_b32 v[36:37], v70 offset1:4
	ds_read2_b32 v[38:39], v70 offset0:66 offset1:70
	ds_read2_b32 v[40:41], v70 offset0:99 offset1:103
	ds_read2_b32 v[42:43], v70 offset0:132 offset1:136
	ds_read2_b32 v[44:45], v70 offset0:165 offset1:169
	ds_read2_b32 v[46:47], v70 offset0:198 offset1:202
	ds_read2_b32 v[48:49], v70 offset0:231 offset1:235
	s_waitcnt lgkmcnt(7)
	v_bfe_u32 v11, v24, 16, 1
	s_waitcnt lgkmcnt(6)
	v_bfe_u32 v5, v36, 16, 1
	v_add3_u32 v5, v36, v5, s79
	v_lshrrev_b32_e32 v5, 16, v5
	v_add3_u32 v11, v24, v11, s79
	v_and_or_b32 v32, v11, s80, v5
	s_waitcnt lgkmcnt(5)
	v_bfe_u32 v5, v38, 16, 1
	v_add3_u32 v5, v38, v5, s79
	s_waitcnt lgkmcnt(4)
	v_bfe_u32 v11, v40, 16, 1
	v_lshrrev_b32_e32 v5, 16, v5
	v_add3_u32 v11, v40, v11, s79
	v_and_or_b32 v33, v11, s80, v5
	s_waitcnt lgkmcnt(3)
	v_bfe_u32 v5, v42, 16, 1
	v_add3_u32 v5, v42, v5, s79
	s_waitcnt lgkmcnt(2)
	v_bfe_u32 v11, v44, 16, 1
	v_lshrrev_b32_e32 v5, 16, v5
	v_add3_u32 v11, v44, v11, s79
	v_and_or_b32 v34, v11, s80, v5
	s_waitcnt lgkmcnt(1)
	v_bfe_u32 v5, v46, 16, 1
	v_add3_u32 v5, v46, v5, s79
	s_waitcnt lgkmcnt(0)
	v_bfe_u32 v11, v48, 16, 1
	v_lshrrev_b32_e32 v5, 16, v5
	v_add3_u32 v11, v48, v11, s79
	v_and_or_b32 v35, v11, s80, v5
	v_add_u32_e32 v5, s14, v26
	v_ashrrev_i32_e32 v50, 8, v5
	v_ashrrev_i32_e32 v51, 31, v50
	v_lshlrev_b64 v[50:51], 22, v[50:51]
	s_lshl_b64 s[10:11], s[90:91], 15
	s_lshr_b32 s100, s14, 8
	s_lshl_b32 s100, s100, 22
	s_bfe_u32 s101, s14, 0x10007
	s_lshl_b32 s101, s101, 14
	s_add_i32 s100, s100, s101
	s_bfe_u32 s101, s14, 0x20005
	s_lshl_b32 s101, s101, 12
	s_add_i32 s100, s100, s101
	v_lshrrev_b32_e32 v62, 5, v146
	v_lshlrev_b32_e32 v62, 5, v62
	v_lshlrev_b32_e32 v64, 4, v146
	v_xor_b32_e32 v62, v62, v64
	v_add_u32_e32 v62, s100, v62
	v_mov_b32_e32 v63, v19
	v_lshl_add_u64 v[68:69], s[0:1], 0, v[62:63]
	v_lshl_add_u64 v[68:69], v[68:69], 0, s[10:11]
	v_lshl_add_u64 v[50:51], s[0:1], 0, v[50:51]
	v_lshlrev_b32_e32 v5, 7, v5
	v_lshl_add_u64 v[50:51], v[50:51], 0, s[10:11]
	v_and_b32_e32 v18, 0x7f80, v5
	v_cvt_pk_bf16_f32 v5, v37, v25
	v_lshl_add_u64 v[50:51], v[50:51], 0, v[18:19]
	v_mov_b32_e32 v11, v19
	v_lshl_add_u64 v[50:51], v[50:51], 0, v[10:11]
	global_store_dwordx4 v[68:69], v[32:35], off nt
	s_nop 1
	v_mov_b32_e32 v32, v5
	v_cvt_pk_bf16_f32 v33, v39, v41
	s_nop 0
	s_nop 0
	s_nop 0
	v_cvt_pk_bf16_f32 v34, v43, v45
	v_cvt_pk_bf16_f32 v35, v47, v49
	v_add_u32_e32 v5, s14, v28
	v_ashrrev_i32_e32 v24, 8, v5
	v_ashrrev_i32_e32 v25, 31, v24
	v_lshlrev_b64 v[24:25], 22, v[24:25]
	v_lshl_add_u64 v[24:25], s[0:1], 0, v[24:25]
	v_lshlrev_b32_e32 v5, 7, v5
	v_lshl_add_u64 v[24:25], v[24:25], 0, s[10:11]
	v_and_b32_e32 v18, 0x7f80, v5
	v_lshl_add_u64 v[24:25], v[24:25], 0, v[18:19]
	v_lshl_add_u64 v[24:25], v[24:25], 0, v[10:11]
	global_store_dwordx4 v[68:69], v[32:35], off offset:2048 nt
	ds_read2_b32 v[24:25], v71 offset1:4
	ds_read2_b32 v[36:37], v71 offset0:33 offset1:37
	ds_read2_b32 v[38:39], v71 offset0:66 offset1:70
	ds_read2_b32 v[40:41], v71 offset0:99 offset1:103
	ds_read2_b32 v[42:43], v71 offset0:132 offset1:136
	ds_read2_b32 v[44:45], v71 offset0:165 offset1:169
	ds_read2_b32 v[46:47], v71 offset0:198 offset1:202
	ds_read2_b32 v[48:49], v71 offset0:231 offset1:235
	s_waitcnt lgkmcnt(7)
	v_bfe_u32 v5, v24, 16, 1
	v_add3_u32 v5, v24, v5, s79
	s_waitcnt lgkmcnt(6)
	v_bfe_u32 v18, v36, 16, 1
	v_lshrrev_b32_e32 v5, 16, v5
	v_add3_u32 v18, v36, v18, s79
	v_and_or_b32 v32, v18, s80, v5
	s_waitcnt lgkmcnt(5)
	v_bfe_u32 v5, v38, 16, 1
	v_add3_u32 v5, v38, v5, s79
	s_waitcnt lgkmcnt(4)
	v_bfe_u32 v18, v40, 16, 1
	v_lshrrev_b32_e32 v5, 16, v5
	v_add3_u32 v18, v40, v18, s79
	v_and_or_b32 v33, v18, s80, v5
	s_waitcnt lgkmcnt(3)
	v_bfe_u32 v5, v42, 16, 1
	v_add3_u32 v5, v42, v5, s79
	s_waitcnt lgkmcnt(2)
	v_bfe_u32 v18, v44, 16, 1
	v_lshrrev_b32_e32 v5, 16, v5
	v_add3_u32 v18, v44, v18, s79
	v_and_or_b32 v34, v18, s80, v5
	s_waitcnt lgkmcnt(1)
	v_bfe_u32 v5, v46, 16, 1
	v_add3_u32 v5, v46, v5, s79
	s_waitcnt lgkmcnt(0)
	v_bfe_u32 v18, v48, 16, 1
	v_lshrrev_b32_e32 v5, 16, v5
	v_add3_u32 v18, v48, v18, s79
	v_and_or_b32 v35, v18, s80, v5
	v_add_u32_e32 v5, s14, v29
	v_ashrrev_i32_e32 v50, 8, v5
	v_ashrrev_i32_e32 v51, 31, v50
	v_lshlrev_b64 v[50:51], 22, v[50:51]
	v_lshl_add_u64 v[50:51], s[0:1], 0, v[50:51]
	v_lshlrev_b32_e32 v5, 7, v5
	v_lshl_add_u64 v[50:51], v[50:51], 0, s[10:11]
	v_and_b32_e32 v18, 0x7f80, v5
	v_cvt_pk_bf16_f32 v5, v25, v37
	v_lshl_add_u64 v[50:51], v[50:51], 0, v[18:19]
	v_lshl_add_u64 v[50:51], v[50:51], 0, v[10:11]
	global_store_dwordx4 v[68:69], v[32:35], off offset:1024 nt
	s_nop 1
	v_mov_b32_e32 v32, v5
	v_cvt_pk_bf16_f32 v33, v39, v41
	s_nop 0
	s_nop 0
	s_nop 0
	v_cvt_pk_bf16_f32 v34, v43, v45
	v_cvt_pk_bf16_f32 v35, v47, v49
	v_add_u32_e32 v5, s14, v30
	v_ashrrev_i32_e32 v24, 8, v5
	v_ashrrev_i32_e32 v25, 31, v24
	v_lshlrev_b64 v[24:25], 22, v[24:25]
	v_lshl_add_u64 v[24:25], s[0:1], 0, v[24:25]
	v_lshlrev_b32_e32 v5, 7, v5
	v_lshl_add_u64 v[24:25], v[24:25], 0, s[10:11]
	v_and_b32_e32 v18, 0x7f80, v5
	v_lshl_add_u64 v[24:25], v[24:25], 0, v[18:19]
	v_lshl_add_u64 v[24:25], v[24:25], 0, v[10:11]
	global_store_dwordx4 v[68:69], v[32:35], off offset:3072 nt
	s_waitcnt lgkmcnt(0)
	s_mov_b64 s[10:11], 0
.LBB0_1781:
	s_andn2_b64 vcc, exec, s[10:11]
	s_cbranch_vccnz .LBB0_1783
	s_add_i32 s10, s13, 0xffffe500
	s_lshr_b32 s10, s10, 2
	s_and_b32 s11, s10, 0x3fffffc0
	s_lshl_b32 s10, s13, 5
	s_and_b32 s10, s10, 0x1fe0
	v_add_u32_e32 v24, s11, v1
	s_lshl_b32 s90, s10, 2
	v_ashrrev_i32_e32 v25, 31, v24
	v_lshl_add_u64 v[32:33], v[8:9], 0, s[90:91]
	v_lshlrev_b64 v[24:25], 15, v[24:25]
	v_lshl_add_u64 v[24:25], v[32:33], 0, v[24:25]
	v_add_co_u32_e32 v32, vcc, 0x10000, v24
	global_load_dword v5, v[24:25], off nt
	s_nop 0
	v_addc_co_u32_e32 v33, vcc, 0, v25, vcc
	global_load_dword v11, v[32:33], off nt
	v_add_co_u32_e32 v32, vcc, 0x20000, v24
	s_lshl_b32 s90, s11, 1
	s_nop 0
	v_addc_co_u32_e32 v33, vcc, 0, v25, vcc
	global_load_dword v18, v[32:33], off nt
	v_add_co_u32_e32 v32, vcc, 0x30000, v24
	s_nop 1
	v_addc_co_u32_e32 v33, vcc, 0, v25, vcc
	global_load_dword v31, v[32:33], off nt
	v_add_co_u32_e32 v32, vcc, 0x40000, v24
	s_nop 1
	v_addc_co_u32_e32 v33, vcc, 0, v25, vcc
	global_load_dword v34, v[32:33], off nt
	v_add_co_u32_e32 v32, vcc, 0x50000, v24
	s_nop 1
	v_addc_co_u32_e32 v33, vcc, 0, v25, vcc
	global_load_dword v35, v[32:33], off nt
	v_add_co_u32_e32 v32, vcc, 0x60000, v24
	s_nop 1
	v_addc_co_u32_e32 v33, vcc, 0, v25, vcc
	global_load_dword v36, v[32:33], off nt
	v_add_co_u32_e32 v32, vcc, 0x70000, v24
	s_nop 1
	v_addc_co_u32_e32 v33, vcc, 0, v25, vcc
	global_load_dword v37, v[32:33], off nt
	v_add_co_u32_e32 v32, vcc, 0x80000, v24
	s_nop 1
	v_addc_co_u32_e32 v33, vcc, 0, v25, vcc
	global_load_dword v38, v[32:33], off nt
	v_add_co_u32_e32 v32, vcc, 0x90000, v24
	s_nop 1
	v_addc_co_u32_e32 v33, vcc, 0, v25, vcc
	global_load_dword v39, v[32:33], off nt
	v_add_co_u32_e32 v32, vcc, 0xa0000, v24
	s_nop 1
	v_addc_co_u32_e32 v33, vcc, 0, v25, vcc
	global_load_dword v40, v[32:33], off nt
	v_add_co_u32_e32 v32, vcc, 0xb0000, v24
	s_nop 1
	v_addc_co_u32_e32 v33, vcc, 0, v25, vcc
	global_load_dword v41, v[32:33], off nt
	v_add_co_u32_e32 v32, vcc, 0xc0000, v24
	s_nop 1
	v_addc_co_u32_e32 v33, vcc, 0, v25, vcc
	global_load_dword v42, v[32:33], off nt
	v_add_co_u32_e32 v32, vcc, 0xd0000, v24
	s_nop 1
	v_addc_co_u32_e32 v33, vcc, 0, v25, vcc
	global_load_dword v43, v[32:33], off nt
	v_add_co_u32_e32 v32, vcc, 0xe0000, v24
	s_nop 1
	v_addc_co_u32_e32 v33, vcc, 0, v25, vcc
	global_load_dword v44, v[32:33], off nt
	v_add_co_u32_e32 v32, vcc, 0xf0000, v24
	s_nop 1
	v_addc_co_u32_e32 v33, vcc, 0, v25, vcc
	global_load_dword v45, v[32:33], off nt
	v_add_co_u32_e32 v32, vcc, 0x100000, v24
	s_nop 1
	v_addc_co_u32_e32 v33, vcc, 0, v25, vcc
	global_load_dword v46, v[32:33], off nt
	v_add_co_u32_e32 v32, vcc, 0x110000, v24
	s_nop 1
	v_addc_co_u32_e32 v33, vcc, 0, v25, vcc
	global_load_dword v47, v[32:33], off nt
	v_add_co_u32_e32 v32, vcc, 0x120000, v24
	s_nop 1
	v_addc_co_u32_e32 v33, vcc, 0, v25, vcc
	global_load_dword v48, v[32:33], off nt
	v_add_co_u32_e32 v32, vcc, 0x130000, v24
	s_nop 1
	v_addc_co_u32_e32 v33, vcc, 0, v25, vcc
	global_load_dword v49, v[32:33], off nt
	v_add_co_u32_e32 v32, vcc, 0x140000, v24
	s_nop 1
	v_addc_co_u32_e32 v33, vcc, 0, v25, vcc
	global_load_dword v50, v[32:33], off nt
	v_add_co_u32_e32 v32, vcc, 0x150000, v24
	s_nop 1
	v_addc_co_u32_e32 v33, vcc, 0, v25, vcc
	global_load_dword v51, v[32:33], off nt
	v_add_co_u32_e32 v32, vcc, 0x160000, v24
	s_nop 1
	v_addc_co_u32_e32 v33, vcc, 0, v25, vcc
	global_load_dword v52, v[32:33], off nt
	v_add_co_u32_e32 v32, vcc, 0x170000, v24
	s_nop 1
	v_addc_co_u32_e32 v33, vcc, 0, v25, vcc
	global_load_dword v53, v[32:33], off nt
	v_add_co_u32_e32 v32, vcc, 0x180000, v24
	s_nop 1
	v_addc_co_u32_e32 v33, vcc, 0, v25, vcc
	global_load_dword v54, v[32:33], off nt
	v_add_co_u32_e32 v32, vcc, 0x190000, v24
	s_nop 1
	v_addc_co_u32_e32 v33, vcc, 0, v25, vcc
	global_load_dword v55, v[32:33], off nt
	v_add_co_u32_e32 v32, vcc, 0x1a0000, v24
	s_nop 1
	v_addc_co_u32_e32 v33, vcc, 0, v25, vcc
	global_load_dword v56, v[32:33], off nt
	v_add_co_u32_e32 v32, vcc, 0x1b0000, v24
	s_nop 1
	v_addc_co_u32_e32 v33, vcc, 0, v25, vcc
	global_load_dword v57, v[32:33], off nt
	v_add_co_u32_e32 v32, vcc, 0x1c0000, v24
	s_nop 1
	v_addc_co_u32_e32 v33, vcc, 0, v25, vcc
	global_load_dword v58, v[32:33], off nt
	v_add_co_u32_e32 v32, vcc, 0x1d0000, v24
	s_nop 1
	v_addc_co_u32_e32 v33, vcc, 0, v25, vcc
	global_load_dword v59, v[32:33], off nt
	v_add_co_u32_e32 v32, vcc, 0x1e0000, v24
	s_nop 1
	v_addc_co_u32_e32 v33, vcc, 0, v25, vcc
	v_add_co_u32_e32 v24, vcc, 0x1f0000, v24
	global_load_dword v32, v[32:33], off nt
	s_nop 0
	v_addc_co_u32_e32 v25, vcc, 0, v25, vcc
	global_load_dword v24, v[24:25], off nt
	s_waitcnt vmcnt(0)
	ds_write2_b32 v3, v5, v11 offset1:66
	ds_write2_b32 v3, v18, v31 offset0:132 offset1:198
	v_add_u32_e32 v5, 0x400, v3
	ds_write2_b32 v5, v34, v35 offset0:8 offset1:74
	ds_write2_b32 v5, v36, v37 offset0:140 offset1:206
	v_add_u32_e32 v5, 0x800, v3
	ds_write2_b32 v5, v38, v39 offset0:16 offset1:82
	ds_write2_b32 v5, v40, v41 offset0:148 offset1:214
	v_add_u32_e32 v5, 0xc00, v3
	ds_write2_b32 v5, v42, v43 offset0:24 offset1:90
	ds_write2_b32 v5, v44, v45 offset0:156 offset1:222
	v_add_u32_e32 v5, 0x1000, v3
	ds_write2_b32 v5, v46, v47 offset0:32 offset1:98
	ds_write2_b32 v5, v48, v49 offset0:164 offset1:230
	v_add_u32_e32 v5, 0x1400, v3
	ds_write2_b32 v5, v50, v51 offset0:40 offset1:106
	ds_write2_b32 v5, v52, v53 offset0:172 offset1:238
	v_add_u32_e32 v5, 0x1800, v3
	ds_write2_b32 v5, v54, v55 offset0:48 offset1:114
	ds_write2_b32 v5, v56, v57 offset0:180 offset1:246
	v_add_u32_e32 v5, 0x1c00, v3
	ds_write2_b32 v5, v58, v59 offset0:56 offset1:122
	ds_write2_b32 v5, v32, v24 offset0:188 offset1:254
	s_waitcnt lgkmcnt(0)
	ds_read2_b32 v[36:37], v27 offset0:33 offset1:41
	ds_read2_b32 v[38:39], v27 offset1:8
	ds_read2_b32 v[40:41], v27 offset0:66 offset1:74
	ds_read2_b32 v[42:43], v27 offset0:99 offset1:107
	ds_read2_b32 v[44:45], v27 offset0:132 offset1:140
	ds_read2_b32 v[46:47], v27 offset0:165 offset1:173
	ds_read2_b32 v[48:49], v27 offset0:198 offset1:206
	ds_read2_b32 v[50:51], v27 offset0:231 offset1:239
	s_waitcnt lgkmcnt(7)
	v_bfe_u32 v11, v36, 16, 1
	s_waitcnt lgkmcnt(6)
	v_bfe_u32 v5, v38, 16, 1
	v_add3_u32 v5, v38, v5, s79
	v_lshrrev_b32_e32 v5, 16, v5
	v_add3_u32 v11, v36, v11, s79
	v_and_or_b32 v32, v11, s80, v5
	s_waitcnt lgkmcnt(5)
	v_bfe_u32 v5, v40, 16, 1
	v_add3_u32 v5, v40, v5, s79
	s_waitcnt lgkmcnt(4)
	v_bfe_u32 v11, v42, 16, 1
	v_lshrrev_b32_e32 v5, 16, v5
	v_add3_u32 v11, v42, v11, s79
	v_and_or_b32 v33, v11, s80, v5
	s_waitcnt lgkmcnt(3)
	v_bfe_u32 v5, v44, 16, 1
	v_add3_u32 v5, v44, v5, s79
	s_waitcnt lgkmcnt(2)
	v_bfe_u32 v11, v46, 16, 1
	v_lshrrev_b32_e32 v5, 16, v5
	v_add3_u32 v11, v46, v11, s79
	v_and_or_b32 v34, v11, s80, v5
	s_waitcnt lgkmcnt(1)
	v_bfe_u32 v5, v48, 16, 1
	v_add3_u32 v5, v48, v5, s79
	s_waitcnt lgkmcnt(0)
	v_bfe_u32 v11, v50, 16, 1
	v_lshrrev_b32_e32 v5, 16, v5
	v_add3_u32 v11, v50, v11, s79
	v_add_u32_e32 v52, s10, v26
	v_and_or_b32 v35, v11, s80, v5
	v_ashrrev_i32_e32 v53, 31, v52
	v_cvt_pk_bf16_f32 v5, v39, v37
	v_lshl_add_u64 v[24:25], v[12:13], 0, s[90:91]
	v_lshlrev_b64 v[52:53], 12, v[52:53]
	v_lshl_add_u64 v[52:53], v[24:25], 0, v[52:53]
	global_store_dwordx4 v[52:53], v[32:35], off nt
	v_add_u32_e32 v36, s10, v28
	v_ashrrev_i32_e32 v37, 31, v36
	v_mov_b32_e32 v32, v5
	v_cvt_pk_bf16_f32 v33, v41, v43
	s_nop 0
	s_nop 0
	v_cvt_pk_bf16_f32 v34, v45, v47
	v_cvt_pk_bf16_f32 v35, v49, v51
	v_lshlrev_b64 v[36:37], 12, v[36:37]
	v_lshl_add_u64 v[36:37], v[24:25], 0, v[36:37]
	global_store_dwordx4 v[36:37], v[32:35], off nt
	ds_read2_b32 v[36:37], v27 offset0:49 offset1:57
	ds_read2_b32 v[38:39], v27 offset0:16 offset1:24
	ds_read2_b32 v[40:41], v27 offset0:82 offset1:90
	ds_read2_b32 v[42:43], v27 offset0:115 offset1:123
	ds_read2_b32 v[44:45], v27 offset0:148 offset1:156
	ds_read2_b32 v[46:47], v27 offset0:181 offset1:189
	ds_read2_b32 v[48:49], v27 offset0:214 offset1:222
	ds_read2_b32 v[50:51], v27 offset0:247 offset1:255
	s_waitcnt lgkmcnt(7)
	v_bfe_u32 v11, v36, 16, 1
	s_waitcnt lgkmcnt(6)
	v_bfe_u32 v5, v38, 16, 1
	v_add3_u32 v5, v38, v5, s79
	v_lshrrev_b32_e32 v5, 16, v5
	v_add3_u32 v11, v36, v11, s79
	v_and_or_b32 v32, v11, s80, v5
	s_waitcnt lgkmcnt(5)
	v_bfe_u32 v5, v40, 16, 1
	v_add3_u32 v5, v40, v5, s79
	s_waitcnt lgkmcnt(4)
	v_bfe_u32 v11, v42, 16, 1
	v_lshrrev_b32_e32 v5, 16, v5
	v_add3_u32 v11, v42, v11, s79
	v_and_or_b32 v33, v11, s80, v5
	s_waitcnt lgkmcnt(3)
	v_bfe_u32 v5, v44, 16, 1
	v_add3_u32 v5, v44, v5, s79
	s_waitcnt lgkmcnt(2)
	v_bfe_u32 v11, v46, 16, 1
	v_lshrrev_b32_e32 v5, 16, v5
	v_add3_u32 v11, v46, v11, s79
	v_and_or_b32 v34, v11, s80, v5
	s_waitcnt lgkmcnt(1)
	v_bfe_u32 v5, v48, 16, 1
	v_add3_u32 v5, v48, v5, s79
	s_waitcnt lgkmcnt(0)
	v_bfe_u32 v11, v50, 16, 1
	v_lshrrev_b32_e32 v5, 16, v5
	v_add3_u32 v11, v50, v11, s79
	v_add_u32_e32 v52, s10, v29
	v_and_or_b32 v35, v11, s80, v5
	v_ashrrev_i32_e32 v53, 31, v52
	v_cvt_pk_bf16_f32 v5, v39, v37
	v_lshlrev_b64 v[52:53], 12, v[52:53]
	v_lshl_add_u64 v[52:53], v[24:25], 0, v[52:53]
	global_store_dwordx4 v[52:53], v[32:35], off nt
	v_add_u32_e32 v36, s10, v30
	v_ashrrev_i32_e32 v37, 31, v36
	v_mov_b32_e32 v32, v5
	v_cvt_pk_bf16_f32 v33, v41, v43
	s_nop 0
	s_nop 0
	v_cvt_pk_bf16_f32 v34, v45, v47
	v_cvt_pk_bf16_f32 v35, v49, v51
	v_lshlrev_b64 v[36:37], 12, v[36:37]
	v_lshl_add_u64 v[24:25], v[24:25], 0, v[36:37]
	global_store_dwordx4 v[24:25], v[32:35], off nt
	s_waitcnt lgkmcnt(0)

.LBB0_1784:
	s_andn2_b64 vcc, exec, s[10:11]
	s_cbranch_vccnz .LBB0_1786
	s_and_b32 s10, s13, 0x1fc0
	s_addk_i32 s10, 0xed00
	s_lshl_b32 s11, s13, 5
	s_and_b32 s14, s11, 0x7e0
	v_add_u32_e32 v24, s10, v1
	s_lshl_b32 s90, s14, 2
	v_ashrrev_i32_e32 v25, 31, v24
	v_lshl_add_u64 v[32:33], v[14:15], 0, s[90:91]
	v_lshlrev_b64 v[24:25], 13, v[24:25]
	v_lshl_add_u64 v[24:25], v[32:33], 0, v[24:25]
	v_add_co_u32_e32 v32, vcc, 0x4000, v24
	global_load_dword v5, v[24:25], off nt
	s_nop 0
	v_addc_co_u32_e32 v33, vcc, 0, v25, vcc
	global_load_dword v11, v[32:33], off nt
	v_add_co_u32_e32 v32, vcc, 0x8000, v24
	s_mov_b32 s11, 0xc000
	s_nop 0
	v_addc_co_u32_e32 v33, vcc, 0, v25, vcc
	global_load_dword v18, v[32:33], off nt
	v_add_co_u32_e32 v32, vcc, s11, v24
	s_mov_b32 s11, 0x10000
	s_nop 0
	v_addc_co_u32_e32 v33, vcc, 0, v25, vcc
	global_load_dword v31, v[32:33], off nt
	v_add_co_u32_e32 v32, vcc, s11, v24
	s_mov_b32 s11, 0x14000
	s_nop 0
	v_addc_co_u32_e32 v33, vcc, 0, v25, vcc
	global_load_dword v34, v[32:33], off nt
	v_add_co_u32_e32 v32, vcc, s11, v24
	s_mov_b32 s11, 0x18000
	s_nop 0
	v_addc_co_u32_e32 v33, vcc, 0, v25, vcc
	global_load_dword v35, v[32:33], off nt
	v_add_co_u32_e32 v32, vcc, s11, v24
	s_mov_b32 s11, 0x1c000
	s_nop 0
	v_addc_co_u32_e32 v33, vcc, 0, v25, vcc
	global_load_dword v36, v[32:33], off nt
	v_add_co_u32_e32 v32, vcc, s11, v24
	s_mov_b32 s11, 0x20000
	s_nop 0
	v_addc_co_u32_e32 v33, vcc, 0, v25, vcc
	global_load_dword v37, v[32:33], off nt
	v_add_co_u32_e32 v32, vcc, s11, v24
	s_mov_b32 s11, 0x58000
	s_nop 0
	v_addc_co_u32_e32 v33, vcc, 0, v25, vcc
	global_load_dword v38, v[32:33], off nt
	v_add_co_u32_e32 v32, vcc, s19, v24
	s_nop 1
	v_addc_co_u32_e32 v33, vcc, 0, v25, vcc
	global_load_dword v39, v[32:33], off nt
	v_add_co_u32_e32 v32, vcc, s20, v24
	s_nop 1
	v_addc_co_u32_e32 v33, vcc, 0, v25, vcc
	global_load_dword v40, v[32:33], off nt
	v_add_co_u32_e32 v32, vcc, s21, v24
	s_nop 1
	v_addc_co_u32_e32 v33, vcc, 0, v25, vcc
	global_load_dword v41, v[32:33], off nt
	v_add_co_u32_e32 v32, vcc, s22, v24
	s_nop 1
	v_addc_co_u32_e32 v33, vcc, 0, v25, vcc
	global_load_dword v42, v[32:33], off nt
	v_add_co_u32_e32 v32, vcc, s23, v24
	s_nop 1
	v_addc_co_u32_e32 v33, vcc, 0, v25, vcc
	global_load_dword v43, v[32:33], off nt
	v_add_co_u32_e32 v32, vcc, s24, v24
	s_nop 1
	v_addc_co_u32_e32 v33, vcc, 0, v25, vcc
	global_load_dword v44, v[32:33], off nt
	v_add_co_u32_e32 v32, vcc, s25, v24
	s_nop 1
	v_addc_co_u32_e32 v33, vcc, 0, v25, vcc
	global_load_dword v45, v[32:33], off nt
	v_add_co_u32_e32 v32, vcc, s26, v24
	s_nop 1
	v_addc_co_u32_e32 v33, vcc, 0, v25, vcc
	global_load_dword v46, v[32:33], off nt
	v_add_co_u32_e32 v32, vcc, s27, v24
	s_nop 1
	v_addc_co_u32_e32 v33, vcc, 0, v25, vcc
	global_load_dword v47, v[32:33], off nt
	v_add_co_u32_e32 v32, vcc, s43, v24
	s_nop 1
	v_addc_co_u32_e32 v33, vcc, 0, v25, vcc
	global_load_dword v48, v[32:33], off nt
	v_add_co_u32_e32 v32, vcc, s44, v24
	s_nop 1
	v_addc_co_u32_e32 v33, vcc, 0, v25, vcc
	global_load_dword v49, v[32:33], off nt
	v_add_co_u32_e32 v32, vcc, s45, v24
	s_nop 1
	v_addc_co_u32_e32 v33, vcc, 0, v25, vcc
	global_load_dword v50, v[32:33], off nt
	v_add_co_u32_e32 v32, vcc, s46, v24
	s_nop 1
	v_addc_co_u32_e32 v33, vcc, 0, v25, vcc
	global_load_dword v51, v[32:33], off nt
	v_add_co_u32_e32 v32, vcc, s11, v24
	s_mov_b32 s11, 0x5c000
	s_nop 0
	v_addc_co_u32_e32 v33, vcc, 0, v25, vcc
	global_load_dword v52, v[32:33], off nt
	v_add_co_u32_e32 v32, vcc, s11, v24
	s_mov_b32 s11, 0x60000
	s_nop 0
	v_addc_co_u32_e32 v33, vcc, 0, v25, vcc
	global_load_dword v53, v[32:33], off nt
	v_add_co_u32_e32 v32, vcc, s11, v24
	s_mov_b32 s11, 0x64000
	s_nop 0
	v_addc_co_u32_e32 v33, vcc, 0, v25, vcc
	global_load_dword v54, v[32:33], off nt
	v_add_co_u32_e32 v32, vcc, s11, v24
	s_mov_b32 s11, 0x68000
	s_nop 0
	v_addc_co_u32_e32 v33, vcc, 0, v25, vcc
	global_load_dword v55, v[32:33], off nt
	v_add_co_u32_e32 v32, vcc, s11, v24
	s_mov_b32 s11, 0x6c000
	s_nop 0
	v_addc_co_u32_e32 v33, vcc, 0, v25, vcc
	global_load_dword v56, v[32:33], off nt
	v_add_co_u32_e32 v32, vcc, s11, v24
	s_mov_b32 s11, 0x70000
	s_nop 0
	v_addc_co_u32_e32 v33, vcc, 0, v25, vcc
	global_load_dword v57, v[32:33], off nt
	v_add_co_u32_e32 v32, vcc, s11, v24
	s_mov_b32 s11, 0x74000
	s_nop 0
	v_addc_co_u32_e32 v33, vcc, 0, v25, vcc
	global_load_dword v58, v[32:33], off nt
	v_add_co_u32_e32 v32, vcc, s11, v24
	s_mov_b32 s11, 0x78000
	s_nop 0
	v_addc_co_u32_e32 v33, vcc, 0, v25, vcc
	global_load_dword v59, v[32:33], off nt
	v_add_co_u32_e32 v32, vcc, s11, v24
	s_mov_b32 s11, 0x7c000
	s_nop 0
	v_addc_co_u32_e32 v33, vcc, 0, v25, vcc
	v_add_co_u32_e32 v24, vcc, s11, v24
	global_load_dword v32, v[32:33], off nt
	s_nop 0
	v_addc_co_u32_e32 v25, vcc, 0, v25, vcc
	global_load_dword v24, v[24:25], off nt
	s_waitcnt vmcnt(0)
	ds_write2_b32 v3, v5, v11 offset1:66
	ds_write2_b32 v3, v18, v31 offset0:132 offset1:198
	v_add_u32_e32 v5, 0x400, v3
	ds_write2_b32 v5, v34, v35 offset0:8 offset1:74
	ds_write2_b32 v5, v36, v37 offset0:140 offset1:206
	v_add_u32_e32 v5, 0x800, v3
	ds_write2_b32 v5, v38, v39 offset0:16 offset1:82
	ds_write2_b32 v5, v40, v41 offset0:148 offset1:214
	v_add_u32_e32 v5, 0xc00, v3
	ds_write2_b32 v5, v42, v43 offset0:24 offset1:90
	ds_write2_b32 v5, v44, v45 offset0:156 offset1:222
	v_add_u32_e32 v5, 0x1000, v3
	ds_write2_b32 v5, v46, v47 offset0:32 offset1:98
	ds_write2_b32 v5, v48, v49 offset0:164 offset1:230
	v_add_u32_e32 v5, 0x1400, v3
	ds_write2_b32 v5, v50, v51 offset0:40 offset1:106
	ds_write2_b32 v5, v52, v53 offset0:172 offset1:238
	v_add_u32_e32 v5, 0x1800, v3
	ds_write2_b32 v5, v54, v55 offset0:48 offset1:114
	ds_write2_b32 v5, v56, v57 offset0:180 offset1:246
	v_add_u32_e32 v5, 0x1c00, v3
	ds_write2_b32 v5, v58, v59 offset0:56 offset1:122
	ds_write2_b32 v5, v32, v24 offset0:188 offset1:254
	s_waitcnt lgkmcnt(0)
	ds_read2_b32 v[36:37], v27 offset0:33 offset1:41
	ds_read2_b32 v[38:39], v27 offset1:8
	ds_read2_b32 v[40:41], v27 offset0:66 offset1:74
	ds_read2_b32 v[42:43], v27 offset0:99 offset1:107
	ds_read2_b32 v[44:45], v27 offset0:132 offset1:140
	ds_read2_b32 v[46:47], v27 offset0:165 offset1:173
	ds_read2_b32 v[48:49], v27 offset0:198 offset1:206
	ds_read2_b32 v[50:51], v27 offset0:231 offset1:239
	s_waitcnt lgkmcnt(7)
	v_bfe_u32 v11, v36, 16, 1
	s_waitcnt lgkmcnt(6)
	v_bfe_u32 v5, v38, 16, 1
	v_add3_u32 v5, v38, v5, s79
	v_lshrrev_b32_e32 v5, 16, v5
	v_add3_u32 v11, v36, v11, s79
	v_and_or_b32 v32, v11, s80, v5
	s_waitcnt lgkmcnt(5)
	v_bfe_u32 v5, v40, 16, 1
	v_add3_u32 v5, v40, v5, s79
	s_waitcnt lgkmcnt(4)
	v_bfe_u32 v11, v42, 16, 1
	v_lshrrev_b32_e32 v5, 16, v5
	v_add3_u32 v11, v42, v11, s79
	v_and_or_b32 v33, v11, s80, v5
	s_waitcnt lgkmcnt(3)
	v_bfe_u32 v5, v44, 16, 1
	v_add3_u32 v5, v44, v5, s79
	s_waitcnt lgkmcnt(2)
	v_bfe_u32 v11, v46, 16, 1
	v_lshrrev_b32_e32 v5, 16, v5
	v_add3_u32 v11, v46, v11, s79
	v_and_or_b32 v34, v11, s80, v5
	s_waitcnt lgkmcnt(1)
	v_bfe_u32 v5, v48, 16, 1
	v_add3_u32 v5, v48, v5, s79
	s_waitcnt lgkmcnt(0)
	v_bfe_u32 v11, v50, 16, 1
	v_lshrrev_b32_e32 v5, 16, v5
	v_add3_u32 v11, v50, v11, s79
	v_add_u32_e32 v52, s14, v26
	s_mov_b32 s11, s91
	v_and_or_b32 v35, v11, s80, v5
	v_ashrrev_i32_e32 v53, 31, v52
	v_cvt_pk_bf16_f32 v5, v39, v37
	v_lshl_add_u64 v[24:25], s[10:11], 1, v[16:17]
	v_lshlrev_b64 v[52:53], 12, v[52:53]
	v_lshl_add_u64 v[52:53], v[24:25], 0, v[52:53]
	global_store_dwordx4 v[52:53], v[32:35], off nt
	v_add_u32_e32 v36, s14, v28
	v_ashrrev_i32_e32 v37, 31, v36
	v_mov_b32_e32 v32, v5
	v_cvt_pk_bf16_f32 v33, v41, v43
	s_nop 0
	s_nop 0
	v_cvt_pk_bf16_f32 v34, v45, v47
	v_cvt_pk_bf16_f32 v35, v49, v51
	v_lshlrev_b64 v[36:37], 12, v[36:37]
	v_lshl_add_u64 v[36:37], v[24:25], 0, v[36:37]
	global_store_dwordx4 v[36:37], v[32:35], off nt
	ds_read2_b32 v[36:37], v27 offset0:49 offset1:57
	ds_read2_b32 v[38:39], v27 offset0:16 offset1:24
	ds_read2_b32 v[40:41], v27 offset0:82 offset1:90
	ds_read2_b32 v[42:43], v27 offset0:115 offset1:123
	ds_read2_b32 v[44:45], v27 offset0:148 offset1:156
	ds_read2_b32 v[46:47], v27 offset0:181 offset1:189
	ds_read2_b32 v[48:49], v27 offset0:214 offset1:222
	ds_read2_b32 v[50:51], v27 offset0:247 offset1:255
	s_waitcnt lgkmcnt(7)
	v_bfe_u32 v11, v36, 16, 1
	s_waitcnt lgkmcnt(6)
	v_bfe_u32 v5, v38, 16, 1
	v_add3_u32 v5, v38, v5, s79
	v_lshrrev_b32_e32 v5, 16, v5
	v_add3_u32 v11, v36, v11, s79
	v_and_or_b32 v32, v11, s80, v5
	s_waitcnt lgkmcnt(5)
	v_bfe_u32 v5, v40, 16, 1
	v_add3_u32 v5, v40, v5, s79
	s_waitcnt lgkmcnt(4)
	v_bfe_u32 v11, v42, 16, 1
	v_lshrrev_b32_e32 v5, 16, v5
	v_add3_u32 v11, v42, v11, s79
	v_and_or_b32 v33, v11, s80, v5
	s_waitcnt lgkmcnt(3)
	v_bfe_u32 v5, v44, 16, 1
	v_add3_u32 v5, v44, v5, s79
	s_waitcnt lgkmcnt(2)
	v_bfe_u32 v11, v46, 16, 1
	v_lshrrev_b32_e32 v5, 16, v5
	v_add3_u32 v11, v46, v11, s79
	v_and_or_b32 v34, v11, s80, v5
	s_waitcnt lgkmcnt(1)
	v_bfe_u32 v5, v48, 16, 1
	v_add3_u32 v5, v48, v5, s79
	s_waitcnt lgkmcnt(0)
	v_bfe_u32 v11, v50, 16, 1
	v_lshrrev_b32_e32 v5, 16, v5
	v_add3_u32 v11, v50, v11, s79
	v_add_u32_e32 v52, s14, v29
	v_and_or_b32 v35, v11, s80, v5
	v_ashrrev_i32_e32 v53, 31, v52
	v_cvt_pk_bf16_f32 v5, v39, v37
	v_lshlrev_b64 v[52:53], 12, v[52:53]
	v_lshl_add_u64 v[52:53], v[24:25], 0, v[52:53]
	global_store_dwordx4 v[52:53], v[32:35], off nt
	v_add_u32_e32 v36, s14, v30
	v_ashrrev_i32_e32 v37, 31, v36
	v_mov_b32_e32 v32, v5
	v_cvt_pk_bf16_f32 v33, v41, v43
	s_nop 0
	s_nop 0
	v_cvt_pk_bf16_f32 v34, v45, v47
	v_cvt_pk_bf16_f32 v35, v49, v51
	v_lshlrev_b64 v[36:37], 12, v[36:37]
	v_lshl_add_u64 v[24:25], v[24:25], 0, v[36:37]
	global_store_dwordx4 v[24:25], v[32:35], off nt
	s_waitcnt lgkmcnt(0)

.LBB0_1787:
	s_andn2_b64 vcc, exec, s[10:11]
	s_cbranch_vccnz .LBB0_1775
	s_mul_hi_i32 s10, s13, 0x6bca1af3
	s_lshr_b32 s11, s10, 31
	s_ashr_i32 s10, s10, 6
	s_add_i32 s10, s10, s11
	s_mul_i32 s11, s10, 0x98
	s_sub_i32 s11, s13, s11
	s_lshl_b32 s13, s11, 5
	s_cmpk_gt_i32 s11, 0x7f
	s_cselect_b32 s11, 8, 0
	s_or_b32 s14, s11, s13
	s_lshl_b32 s10, s10, 6
	s_ashr_i32 s15, s14, 31
	v_add_u32_e32 v5, s10, v1
	v_lshl_add_u64 v[24:25], s[14:15], 2, v[20:21]
	v_mad_i64_i32 v[32:33], s[14:15], v5, s37, v[24:25]
	v_add_u32_e32 v18, 2, v5
	global_load_dword v11, v[32:33], off nt
	v_mad_i64_i32 v[32:33], s[14:15], v18, s37, v[24:25]
	v_add_u32_e32 v31, 4, v5
	global_load_dword v18, v[32:33], off nt
	v_mad_i64_i32 v[32:33], s[14:15], v31, s37, v[24:25]
	global_load_dword v31, v[32:33], off nt
	v_add_u32_e32 v32, 6, v5
	v_mad_i64_i32 v[32:33], s[14:15], v32, s37, v[24:25]
	global_load_dword v34, v[32:33], off nt
	v_add_u32_e32 v32, 8, v5
	v_mad_i64_i32 v[32:33], s[14:15], v32, s37, v[24:25]
	global_load_dword v35, v[32:33], off nt
	v_add_u32_e32 v32, 10, v5
	v_mad_i64_i32 v[32:33], s[14:15], v32, s37, v[24:25]
	global_load_dword v36, v[32:33], off nt
	v_add_u32_e32 v32, 12, v5
	v_mad_i64_i32 v[32:33], s[14:15], v32, s37, v[24:25]
	global_load_dword v37, v[32:33], off nt
	v_add_u32_e32 v32, 14, v5
	v_mad_i64_i32 v[32:33], s[14:15], v32, s37, v[24:25]
	global_load_dword v38, v[32:33], off nt
	v_add_u32_e32 v32, 16, v5
	v_mad_i64_i32 v[32:33], s[14:15], v32, s37, v[24:25]
	global_load_dword v39, v[32:33], off nt
	v_add_u32_e32 v32, 18, v5
	v_mad_i64_i32 v[32:33], s[14:15], v32, s37, v[24:25]
	global_load_dword v40, v[32:33], off nt
	v_add_u32_e32 v32, 20, v5
	v_mad_i64_i32 v[32:33], s[14:15], v32, s37, v[24:25]
	global_load_dword v41, v[32:33], off nt
	v_add_u32_e32 v32, 22, v5
	v_mad_i64_i32 v[32:33], s[14:15], v32, s37, v[24:25]
	global_load_dword v42, v[32:33], off nt
	v_add_u32_e32 v32, 24, v5
	v_mad_i64_i32 v[32:33], s[14:15], v32, s37, v[24:25]
	global_load_dword v43, v[32:33], off nt
	v_add_u32_e32 v32, 26, v5
	v_mad_i64_i32 v[32:33], s[14:15], v32, s37, v[24:25]
	global_load_dword v44, v[32:33], off nt
	v_add_u32_e32 v32, 28, v5
	v_mad_i64_i32 v[32:33], s[14:15], v32, s37, v[24:25]
	global_load_dword v45, v[32:33], off nt
	v_add_u32_e32 v32, 30, v5
	v_mad_i64_i32 v[32:33], s[14:15], v32, s37, v[24:25]
	global_load_dword v46, v[32:33], off nt
	v_add_u32_e32 v32, 32, v5
	v_mad_i64_i32 v[32:33], s[14:15], v32, s37, v[24:25]
	global_load_dword v47, v[32:33], off nt
	v_add_u32_e32 v32, 34, v5
	v_mad_i64_i32 v[32:33], s[14:15], v32, s37, v[24:25]
	global_load_dword v48, v[32:33], off nt
	v_add_u32_e32 v32, 36, v5
	v_mad_i64_i32 v[32:33], s[14:15], v32, s37, v[24:25]
	global_load_dword v49, v[32:33], off nt
	v_add_u32_e32 v32, 38, v5
	v_mad_i64_i32 v[32:33], s[14:15], v32, s37, v[24:25]
	global_load_dword v50, v[32:33], off nt
	v_add_u32_e32 v32, 40, v5
	v_mad_i64_i32 v[32:33], s[14:15], v32, s37, v[24:25]
	global_load_dword v51, v[32:33], off nt
	v_add_u32_e32 v32, 42, v5
	v_mad_i64_i32 v[32:33], s[14:15], v32, s37, v[24:25]
	global_load_dword v52, v[32:33], off nt
	v_add_u32_e32 v32, 44, v5
	v_mad_i64_i32 v[32:33], s[14:15], v32, s37, v[24:25]
	global_load_dword v53, v[32:33], off nt
	v_add_u32_e32 v32, 46, v5
	v_mad_i64_i32 v[32:33], s[14:15], v32, s37, v[24:25]
	global_load_dword v54, v[32:33], off nt
	v_add_u32_e32 v32, 48, v5
	v_mad_i64_i32 v[32:33], s[14:15], v32, s37, v[24:25]
	global_load_dword v55, v[32:33], off nt
	v_add_u32_e32 v32, 50, v5
	v_mad_i64_i32 v[32:33], s[14:15], v32, s37, v[24:25]
	global_load_dword v56, v[32:33], off nt
	v_add_u32_e32 v32, 52, v5
	v_mad_i64_i32 v[32:33], s[14:15], v32, s37, v[24:25]
	global_load_dword v57, v[32:33], off nt
	v_add_u32_e32 v32, 54, v5
	v_mad_i64_i32 v[32:33], s[14:15], v32, s37, v[24:25]
	global_load_dword v58, v[32:33], off nt
	v_add_u32_e32 v32, 56, v5
	v_mad_i64_i32 v[32:33], s[14:15], v32, s37, v[24:25]
	global_load_dword v59, v[32:33], off nt
	v_add_u32_e32 v32, 58, v5
	v_mad_i64_i32 v[32:33], s[14:15], v32, s37, v[24:25]
	global_load_dword v60, v[32:33], off nt
	v_add_u32_e32 v32, 60, v5
	v_add_u32_e32 v5, 62, v5
	v_mad_i64_i32 v[32:33], s[14:15], v32, s37, v[24:25]
	v_mad_i64_i32 v[24:25], s[14:15], v5, s37, v[24:25]
	global_load_dword v32, v[32:33], off nt
	s_ashr_i32 s11, s10, 31
	global_load_dword v5, v[24:25], off nt
	s_waitcnt vmcnt(0)
	ds_write2_b32 v3, v11, v18 offset1:66
	ds_write2_b32 v3, v31, v34 offset0:132 offset1:198
	v_add_u32_e32 v11, 0x400, v3
	ds_write2_b32 v11, v35, v36 offset0:8 offset1:74
	ds_write2_b32 v11, v37, v38 offset0:140 offset1:206
	v_add_u32_e32 v11, 0x800, v3
	ds_write2_b32 v11, v39, v40 offset0:16 offset1:82
	ds_write2_b32 v11, v41, v42 offset0:148 offset1:214
	v_add_u32_e32 v11, 0xc00, v3
	ds_write2_b32 v11, v43, v44 offset0:24 offset1:90
	ds_write2_b32 v11, v45, v46 offset0:156 offset1:222
	v_add_u32_e32 v11, 0x1000, v3
	ds_write2_b32 v11, v47, v48 offset0:32 offset1:98
	ds_write2_b32 v11, v49, v50 offset0:164 offset1:230
	v_add_u32_e32 v11, 0x1400, v3
	ds_write2_b32 v11, v51, v52 offset0:40 offset1:106
	ds_write2_b32 v11, v53, v54 offset0:172 offset1:238
	v_add_u32_e32 v11, 0x1800, v3
	ds_write2_b32 v11, v55, v56 offset0:48 offset1:114
	ds_write2_b32 v11, v57, v58 offset0:180 offset1:246
	v_add_u32_e32 v11, 0x1c00, v3
	ds_write2_b32 v11, v59, v60 offset0:56 offset1:122
	ds_write2_b32 v11, v32, v5 offset0:188 offset1:254
	s_waitcnt lgkmcnt(0)
	ds_read2_b32 v[36:37], v27 offset0:33 offset1:41
	ds_read2_b32 v[38:39], v27 offset1:8
	ds_read2_b32 v[40:41], v27 offset0:66 offset1:74
	ds_read2_b32 v[42:43], v27 offset0:99 offset1:107
	ds_read2_b32 v[44:45], v27 offset0:132 offset1:140
	ds_read2_b32 v[46:47], v27 offset0:165 offset1:173
	ds_read2_b32 v[48:49], v27 offset0:198 offset1:206
	ds_read2_b32 v[50:51], v27 offset0:231 offset1:239
	s_waitcnt lgkmcnt(7)
	v_bfe_u32 v11, v36, 16, 1
	s_waitcnt lgkmcnt(6)
	v_bfe_u32 v5, v38, 16, 1
	v_add3_u32 v5, v38, v5, s79
	v_lshrrev_b32_e32 v5, 16, v5
	v_add3_u32 v11, v36, v11, s79
	v_and_or_b32 v32, v11, s80, v5
	s_waitcnt lgkmcnt(5)
	v_bfe_u32 v5, v40, 16, 1
	v_add3_u32 v5, v40, v5, s79
	s_waitcnt lgkmcnt(4)
	v_bfe_u32 v11, v42, 16, 1
	v_lshrrev_b32_e32 v5, 16, v5
	v_add3_u32 v11, v42, v11, s79
	v_and_or_b32 v33, v11, s80, v5
	s_waitcnt lgkmcnt(3)
	v_bfe_u32 v5, v44, 16, 1
	v_add3_u32 v5, v44, v5, s79
	s_waitcnt lgkmcnt(2)
	v_bfe_u32 v11, v46, 16, 1
	v_lshrrev_b32_e32 v5, 16, v5
	v_add3_u32 v11, v46, v11, s79
	v_and_or_b32 v34, v11, s80, v5
	s_waitcnt lgkmcnt(1)
	v_bfe_u32 v5, v48, 16, 1
	v_add3_u32 v5, v48, v5, s79
	s_waitcnt lgkmcnt(0)
	v_bfe_u32 v11, v50, 16, 1
	v_lshrrev_b32_e32 v5, 16, v5
	v_add3_u32 v11, v50, v11, s79
	v_add_u32_e32 v52, s13, v26
	v_and_or_b32 v35, v11, s80, v5
	v_ashrrev_i32_e32 v53, 31, v52
	v_cvt_pk_bf16_f32 v5, v39, v37
	v_lshl_add_u64 v[24:25], s[10:11], 1, v[22:23]
	v_lshlrev_b64 v[52:53], 12, v[52:53]
	v_lshl_add_u64 v[52:53], v[24:25], 0, v[52:53]
	global_store_dwordx4 v[52:53], v[32:35], off nt
	v_add_u32_e32 v36, s13, v28
	v_ashrrev_i32_e32 v37, 31, v36
	v_mov_b32_e32 v32, v5
	v_cvt_pk_bf16_f32 v33, v41, v43
	s_nop 0
	s_nop 0
	v_cvt_pk_bf16_f32 v34, v45, v47
	v_cvt_pk_bf16_f32 v35, v49, v51
	v_lshlrev_b64 v[36:37], 12, v[36:37]
	v_lshl_add_u64 v[36:37], v[24:25], 0, v[36:37]
	global_store_dwordx4 v[36:37], v[32:35], off nt
	ds_read2_b32 v[36:37], v27 offset0:49 offset1:57
	ds_read2_b32 v[38:39], v27 offset0:16 offset1:24
	ds_read2_b32 v[40:41], v27 offset0:82 offset1:90
	ds_read2_b32 v[42:43], v27 offset0:115 offset1:123
	ds_read2_b32 v[44:45], v27 offset0:148 offset1:156
	ds_read2_b32 v[46:47], v27 offset0:181 offset1:189
	ds_read2_b32 v[48:49], v27 offset0:214 offset1:222
	ds_read2_b32 v[50:51], v27 offset0:247 offset1:255
	s_waitcnt lgkmcnt(7)
	v_bfe_u32 v11, v36, 16, 1
	s_waitcnt lgkmcnt(6)
	v_bfe_u32 v5, v38, 16, 1
	v_add3_u32 v5, v38, v5, s79
	v_lshrrev_b32_e32 v5, 16, v5
	v_add3_u32 v11, v36, v11, s79
	v_and_or_b32 v32, v11, s80, v5
	s_waitcnt lgkmcnt(5)
	v_bfe_u32 v5, v40, 16, 1
	v_add3_u32 v5, v40, v5, s79
	s_waitcnt lgkmcnt(4)
	v_bfe_u32 v11, v42, 16, 1
	v_lshrrev_b32_e32 v5, 16, v5
	v_add3_u32 v11, v42, v11, s79
	v_and_or_b32 v33, v11, s80, v5
	s_waitcnt lgkmcnt(3)
	v_bfe_u32 v5, v44, 16, 1
	v_add3_u32 v5, v44, v5, s79
	s_waitcnt lgkmcnt(2)
	v_bfe_u32 v11, v46, 16, 1
	v_lshrrev_b32_e32 v5, 16, v5
	v_add3_u32 v11, v46, v11, s79
	v_and_or_b32 v34, v11, s80, v5
	s_waitcnt lgkmcnt(1)
	v_bfe_u32 v5, v48, 16, 1
	v_add3_u32 v5, v48, v5, s79
	s_waitcnt lgkmcnt(0)
	v_bfe_u32 v11, v50, 16, 1
	v_lshrrev_b32_e32 v5, 16, v5
	v_add3_u32 v11, v50, v11, s79
	v_add_u32_e32 v52, s13, v29
	v_and_or_b32 v35, v11, s80, v5
	v_ashrrev_i32_e32 v53, 31, v52
	v_cvt_pk_bf16_f32 v5, v39, v37
	v_lshlrev_b64 v[52:53], 12, v[52:53]
	v_lshl_add_u64 v[52:53], v[24:25], 0, v[52:53]
	global_store_dwordx4 v[52:53], v[32:35], off nt
	v_add_u32_e32 v36, s13, v30
	v_ashrrev_i32_e32 v37, 31, v36
	v_mov_b32_e32 v32, v5
	v_cvt_pk_bf16_f32 v33, v41, v43
	s_nop 0
	s_nop 0
	v_cvt_pk_bf16_f32 v34, v45, v47
	v_cvt_pk_bf16_f32 v35, v49, v51
	v_lshlrev_b64 v[36:37], 12, v[36:37]
	v_lshl_add_u64 v[24:25], v[24:25], 0, v[36:37]
	global_store_dwordx4 v[24:25], v[32:35], off nt
	s_waitcnt lgkmcnt(0)
	s_branch .LBB0_1775
